# U-phase dot products on matrix cores: fp8->bf16 (exact) + v_mfma_f32_4x4x4_16b_bf16 diagonal, same 8x128B load pattern
# speedup vs baseline: 1.0298x; 1.0124x over previous
; DEV void sort_lists(int lane, int& myi0, int& myi1, float& myg0, float& myg1) {
; #pragma unroll
;     for (int k = 2; k <= 128; k <<= 1) {
; #pragma unroll
;       for (int j = k >> 1; j >= 1; j >>= 1) {
;         if (j == 64) {
;           const bool sw_ = myi1 < myi0;
;           const int ti = sw_ ? myi1 : myi0, tj = sw_ ? myi0 : myi1; const float tg = sw_ ? myg1 : myg0, th = sw_ ? myg0 : myg1;
;           myi0 = ti; myi1 = tj; myg0 = tg; myg1 = th;
;         } else {
;           const bool lower = (lane & j) == 0;
;           {
;             const bool up = (k == 128) ? true : ((k == 64) ? true : ((lane & k) == 0));
;             const int oi = __shfl_xor(myi0, j); const float og = __shfl_xor(myg0, j);
;             const bool take = (lower == up) ? (oi < myi0) : (oi > myi0);
;             myi0 = take ? oi : myi0; myg0 = take ? og : myg0;
;           }
;           {
;             const bool up = (k == 128) ? true : ((k == 64) ? false : ((lane & k) == 0));
;             const int oi = __shfl_xor(myi1, j); const float og = __shfl_xor(myg1, j);
;             const bool take = (lower == up) ? (oi < myi1) : (oi > myi1);
;             myi1 = take ? oi : myi1; myg1 = take ? og : myg1;
;           }
;         }
;       }
;     }
; }
; DEV void peer_gather(const Params& P, int l, int m0, const int* idxs, const float* gs) {
;     ...
;   int ni0 = idxs[(wid * 16) * 128 + lane], ni1 = idxs[(wid * 16) * 128 + 64 + lane];
;   float ng0 = gs[(wid * 16) * 128 + lane], ng1 = gs[(wid * 16) * 128 + 64 + lane];
;   sort_lists(lane, ni0, ni1, ng0, ng1);
.Lpg0_p0:
	v_readlane_b32 s82, v231, 26
	v_readlane_b32 s83, v231, 27
	s_nop 4
	s_lshl_b32 s98, s2, 2
	s_add_u32 s98, s98, s33
	s_add_u32 s98, s98, 0
	s_lshl_b32 s98, s98, 9
	v_add_u32_e32 v116, s98, v234
	global_load_dword v241, v116, s[82:83]
	global_load_dword v242, v116, s[82:83] offset:256
	s_lshl_b32 s98, s2, 2
	s_add_u32 s98, s98, s33
	s_add_u32 s98, s98, 1
	s_lshl_b32 s98, s98, 9
	v_add_u32_e32 v117, s98, v234
	global_load_dword v243, v117, s[82:83]
	global_load_dword v244, v117, s[82:83] offset:256
	s_lshl_b32 s98, s2, 2
	s_add_u32 s98, s98, s33
	s_add_u32 s98, s98, 2
	s_lshl_b32 s98, s98, 9
	v_add_u32_e32 v118, s98, v234
	global_load_dword v245, v118, s[82:83]
	global_load_dword v246, v118, s[82:83] offset:256
	s_lshl_b32 s98, s2, 2
	s_add_u32 s98, s98, s33
	s_add_u32 s98, s98, 3
	s_lshl_b32 s98, s98, 9
	v_add_u32_e32 v119, s98, v234
	global_load_dword v247, v119, s[82:83]
	global_load_dword v248, v119, s[82:83] offset:256
	s_waitcnt vmcnt(0)
	v_or_b32_e32 v116, 64, v233
	v_lshl_or_b32 v241, v241, 7, v233
	v_lshl_or_b32 v242, v242, 7, v116
	v_lshl_or_b32 v243, v243, 7, v233
	v_lshl_or_b32 v244, v244, 7, v116
	v_lshl_or_b32 v245, v245, 7, v233
	v_lshl_or_b32 v246, v246, 7, v116
	v_lshl_or_b32 v247, v247, 7, v233
	v_lshl_or_b32 v248, v248, 7, v116
	v_xor_b32_e32 v116, 4, v234
	ds_bpermute_b32 v0, v116, v241
	ds_bpermute_b32 v1, v116, v243
	ds_bpermute_b32 v2, v116, v245
	ds_bpermute_b32 v3, v116, v247
	ds_bpermute_b32 v4, v116, v242
	ds_bpermute_b32 v5, v116, v244
	ds_bpermute_b32 v6, v116, v246
	ds_bpermute_b32 v7, v116, v248
	s_waitcnt lgkmcnt(0)
	s_mov_b32 s88, 0x99999999
	s_mov_b32 s89, 0x99999999
	v_min_u32_e32 v104, v241, v0
	v_max_u32_e32 v105, v241, v0
	v_cndmask_b32_e64 v241, v105, v104, s[88:89]
	v_min_u32_e32 v106, v243, v1
	v_max_u32_e32 v107, v243, v1
	v_cndmask_b32_e64 v243, v107, v106, s[88:89]
	v_min_u32_e32 v104, v245, v2
	v_max_u32_e32 v105, v245, v2
	v_cndmask_b32_e64 v245, v105, v104, s[88:89]
	v_min_u32_e32 v106, v247, v3
	v_max_u32_e32 v107, v247, v3
	v_cndmask_b32_e64 v247, v107, v106, s[88:89]
	v_min_u32_e32 v104, v242, v4
	v_max_u32_e32 v105, v242, v4
	v_cndmask_b32_e64 v242, v105, v104, s[88:89]
	v_min_u32_e32 v106, v244, v5
	v_max_u32_e32 v107, v244, v5
	v_cndmask_b32_e64 v244, v107, v106, s[88:89]
	v_min_u32_e32 v104, v246, v6
	v_max_u32_e32 v105, v246, v6
	v_cndmask_b32_e64 v246, v105, v104, s[88:89]
	v_min_u32_e32 v106, v248, v7
	v_max_u32_e32 v107, v248, v7
	v_cndmask_b32_e64 v248, v107, v106, s[88:89]
	v_xor_b32_e32 v116, 8, v234
	ds_bpermute_b32 v0, v116, v241
	ds_bpermute_b32 v1, v116, v243
	ds_bpermute_b32 v2, v116, v245
	ds_bpermute_b32 v3, v116, v247
	ds_bpermute_b32 v4, v116, v242
	ds_bpermute_b32 v5, v116, v244
	ds_bpermute_b32 v6, v116, v246
	ds_bpermute_b32 v7, v116, v248
	s_waitcnt lgkmcnt(0)
	s_mov_b32 s88, 0xc3c3c3c3
	s_mov_b32 s89, 0xc3c3c3c3
	v_min_u32_e32 v104, v241, v0
	v_max_u32_e32 v105, v241, v0
	v_cndmask_b32_e64 v241, v105, v104, s[88:89]
	v_min_u32_e32 v106, v243, v1
	v_max_u32_e32 v107, v243, v1
	v_cndmask_b32_e64 v243, v107, v106, s[88:89]
	v_min_u32_e32 v104, v245, v2
	v_max_u32_e32 v105, v245, v2
	v_cndmask_b32_e64 v245, v105, v104, s[88:89]
	v_min_u32_e32 v106, v247, v3
	v_max_u32_e32 v107, v247, v3
	v_cndmask_b32_e64 v247, v107, v106, s[88:89]
	v_min_u32_e32 v104, v242, v4
	v_max_u32_e32 v105, v242, v4
	v_cndmask_b32_e64 v242, v105, v104, s[88:89]
	v_min_u32_e32 v106, v244, v5
	v_max_u32_e32 v107, v244, v5
	v_cndmask_b32_e64 v244, v107, v106, s[88:89]
	v_min_u32_e32 v104, v246, v6
	v_max_u32_e32 v105, v246, v6
	v_cndmask_b32_e64 v246, v105, v104, s[88:89]
	v_min_u32_e32 v106, v248, v7
	v_max_u32_e32 v107, v248, v7
	v_cndmask_b32_e64 v248, v107, v106, s[88:89]
	v_xor_b32_e32 v116, 4, v234
	ds_bpermute_b32 v0, v116, v241
	ds_bpermute_b32 v1, v116, v243
	ds_bpermute_b32 v2, v116, v245
	ds_bpermute_b32 v3, v116, v247
	ds_bpermute_b32 v4, v116, v242
	ds_bpermute_b32 v5, v116, v244
	ds_bpermute_b32 v6, v116, v246
	ds_bpermute_b32 v7, v116, v248
	s_waitcnt lgkmcnt(0)
	s_mov_b32 s88, 0xa5a5a5a5
	s_mov_b32 s89, 0xa5a5a5a5
	v_min_u32_e32 v104, v241, v0
	v_max_u32_e32 v105, v241, v0
	v_cndmask_b32_e64 v241, v105, v104, s[88:89]
	v_min_u32_e32 v106, v243, v1
	v_max_u32_e32 v107, v243, v1
	v_cndmask_b32_e64 v243, v107, v106, s[88:89]
	v_min_u32_e32 v104, v245, v2
	v_max_u32_e32 v105, v245, v2
	v_cndmask_b32_e64 v245, v105, v104, s[88:89]
	v_min_u32_e32 v106, v247, v3
	v_max_u32_e32 v107, v247, v3
	v_cndmask_b32_e64 v247, v107, v106, s[88:89]
	v_min_u32_e32 v104, v242, v4
	v_max_u32_e32 v105, v242, v4
	v_cndmask_b32_e64 v242, v105, v104, s[88:89]
	v_min_u32_e32 v106, v244, v5
	v_max_u32_e32 v107, v244, v5
	v_cndmask_b32_e64 v244, v107, v106, s[88:89]
	v_min_u32_e32 v104, v246, v6
	v_max_u32_e32 v105, v246, v6
	v_cndmask_b32_e64 v246, v105, v104, s[88:89]
	v_min_u32_e32 v106, v248, v7
	v_max_u32_e32 v107, v248, v7
	v_cndmask_b32_e64 v248, v107, v106, s[88:89]
	v_xor_b32_e32 v116, 16, v234
	ds_bpermute_b32 v0, v116, v241
	ds_bpermute_b32 v1, v116, v243
	ds_bpermute_b32 v2, v116, v245
	ds_bpermute_b32 v3, v116, v247
	ds_bpermute_b32 v4, v116, v242
	ds_bpermute_b32 v5, v116, v244
	ds_bpermute_b32 v6, v116, v246
	ds_bpermute_b32 v7, v116, v248
	s_waitcnt lgkmcnt(0)
; DEV void sort_lists(int lane, int& myi0, int& myi1, float& myg0, float& myg1) {
; #pragma unroll
;     for (int k = 2; k <= 128; k <<= 1) {
; #pragma unroll
;       for (int j = k >> 1; j >= 1; j >>= 1) {
;         if (j == 64) {
;           const bool sw_ = myi1 < myi0;
;           const int ti = sw_ ? myi1 : myi0, tj = sw_ ? myi0 : myi1; const float tg = sw_ ? myg1 : myg0, th = sw_ ? myg0 : myg1;
;           myi0 = ti; myi1 = tj; myg0 = tg; myg1 = th;
;         } else {
;           const bool lower = (lane & j) == 0;
;           {
;             const bool up = (k == 128) ? true : ((k == 64) ? true : ((lane & k) == 0));
;             const int oi = __shfl_xor(myi0, j); const float og = __shfl_xor(myg0, j);
;             const bool take = (lower == up) ? (oi < myi0) : (oi > myi0);
;             myi0 = take ? oi : myi0; myg0 = take ? og : myg0;
;           }
;           {
;             const bool up = (k == 128) ? true : ((k == 64) ? false : ((lane & k) == 0));
;             const int oi = __shfl_xor(myi1, j); const float og = __shfl_xor(myg1, j);
;             const bool take = (lower == up) ? (oi < myi1) : (oi > myi1);
;             myi1 = take ? oi : myi1; myg1 = take ? og : myg1;
;           }
;         }
;       }
;     }
; }
	s_mov_b32 s88, 0xf00ff00f
	s_mov_b32 s89, 0xf00ff00f
	v_min_u32_e32 v104, v241, v0
	v_max_u32_e32 v105, v241, v0
	v_cndmask_b32_e64 v241, v105, v104, s[88:89]
	v_min_u32_e32 v106, v243, v1
	v_max_u32_e32 v107, v243, v1
	v_cndmask_b32_e64 v243, v107, v106, s[88:89]
	v_min_u32_e32 v104, v245, v2
	v_max_u32_e32 v105, v245, v2
	v_cndmask_b32_e64 v245, v105, v104, s[88:89]
	v_min_u32_e32 v106, v247, v3
	v_max_u32_e32 v107, v247, v3
	v_cndmask_b32_e64 v247, v107, v106, s[88:89]
	v_min_u32_e32 v104, v242, v4
	v_max_u32_e32 v105, v242, v4
	v_cndmask_b32_e64 v242, v105, v104, s[88:89]
	v_min_u32_e32 v106, v244, v5
	v_max_u32_e32 v107, v244, v5
	v_cndmask_b32_e64 v244, v107, v106, s[88:89]
	v_min_u32_e32 v104, v246, v6
	v_max_u32_e32 v105, v246, v6
	v_cndmask_b32_e64 v246, v105, v104, s[88:89]
	v_min_u32_e32 v106, v248, v7
	v_max_u32_e32 v107, v248, v7
	v_cndmask_b32_e64 v248, v107, v106, s[88:89]
	v_xor_b32_e32 v116, 8, v234
	ds_bpermute_b32 v0, v116, v241
	ds_bpermute_b32 v1, v116, v243
	ds_bpermute_b32 v2, v116, v245
	ds_bpermute_b32 v3, v116, v247
	ds_bpermute_b32 v4, v116, v242
	ds_bpermute_b32 v5, v116, v244
	ds_bpermute_b32 v6, v116, v246
	ds_bpermute_b32 v7, v116, v248
	s_waitcnt lgkmcnt(0)
	s_mov_b32 s88, 0xcc33cc33
	s_mov_b32 s89, 0xcc33cc33
	v_min_u32_e32 v104, v241, v0
	v_max_u32_e32 v105, v241, v0
	v_cndmask_b32_e64 v241, v105, v104, s[88:89]
	v_min_u32_e32 v106, v243, v1
	v_max_u32_e32 v107, v243, v1
	v_cndmask_b32_e64 v243, v107, v106, s[88:89]
	v_min_u32_e32 v104, v245, v2
	v_max_u32_e32 v105, v245, v2
	v_cndmask_b32_e64 v245, v105, v104, s[88:89]
	v_min_u32_e32 v106, v247, v3
	v_max_u32_e32 v107, v247, v3
	v_cndmask_b32_e64 v247, v107, v106, s[88:89]
	v_min_u32_e32 v104, v242, v4
	v_max_u32_e32 v105, v242, v4
	v_cndmask_b32_e64 v242, v105, v104, s[88:89]
	v_min_u32_e32 v106, v244, v5
	v_max_u32_e32 v107, v244, v5
	v_cndmask_b32_e64 v244, v107, v106, s[88:89]
	v_min_u32_e32 v104, v246, v6
	v_max_u32_e32 v105, v246, v6
	v_cndmask_b32_e64 v246, v105, v104, s[88:89]
	v_min_u32_e32 v106, v248, v7
	v_max_u32_e32 v107, v248, v7
	v_cndmask_b32_e64 v248, v107, v106, s[88:89]
	v_xor_b32_e32 v116, 4, v234
	ds_bpermute_b32 v0, v116, v241
	ds_bpermute_b32 v1, v116, v243
	ds_bpermute_b32 v2, v116, v245
	ds_bpermute_b32 v3, v116, v247
	ds_bpermute_b32 v4, v116, v242
	ds_bpermute_b32 v5, v116, v244
	ds_bpermute_b32 v6, v116, v246
	ds_bpermute_b32 v7, v116, v248
	s_waitcnt lgkmcnt(0)
	s_mov_b32 s88, 0xaa55aa55
	s_mov_b32 s89, 0xaa55aa55
	v_min_u32_e32 v104, v241, v0
	v_max_u32_e32 v105, v241, v0
	v_cndmask_b32_e64 v241, v105, v104, s[88:89]
	v_min_u32_e32 v106, v243, v1
	v_max_u32_e32 v107, v243, v1
	v_cndmask_b32_e64 v243, v107, v106, s[88:89]
	v_min_u32_e32 v104, v245, v2
	v_max_u32_e32 v105, v245, v2
	v_cndmask_b32_e64 v245, v105, v104, s[88:89]
	v_min_u32_e32 v106, v247, v3
	v_max_u32_e32 v107, v247, v3
	v_cndmask_b32_e64 v247, v107, v106, s[88:89]
	v_min_u32_e32 v104, v242, v4
	v_max_u32_e32 v105, v242, v4
	v_cndmask_b32_e64 v242, v105, v104, s[88:89]
	v_min_u32_e32 v106, v244, v5
	v_max_u32_e32 v107, v244, v5
	v_cndmask_b32_e64 v244, v107, v106, s[88:89]
	v_min_u32_e32 v104, v246, v6
	v_max_u32_e32 v105, v246, v6
	v_cndmask_b32_e64 v246, v105, v104, s[88:89]
	v_min_u32_e32 v106, v248, v7
	v_max_u32_e32 v107, v248, v7
	v_cndmask_b32_e64 v248, v107, v106, s[88:89]
	v_xor_b32_e32 v116, 32, v234
	ds_bpermute_b32 v0, v116, v241
	ds_bpermute_b32 v1, v116, v243
	ds_bpermute_b32 v2, v116, v245
	ds_bpermute_b32 v3, v116, v247
	ds_bpermute_b32 v4, v116, v242
	ds_bpermute_b32 v5, v116, v244
	ds_bpermute_b32 v6, v116, v246
	ds_bpermute_b32 v7, v116, v248
	s_waitcnt lgkmcnt(0)
	s_mov_b32 s88, 0xff0000ff
	s_mov_b32 s89, 0xff0000ff
	v_min_u32_e32 v104, v241, v0
	v_max_u32_e32 v105, v241, v0
	v_cndmask_b32_e64 v241, v105, v104, s[88:89]
	v_min_u32_e32 v106, v243, v1
	v_max_u32_e32 v107, v243, v1
	v_cndmask_b32_e64 v243, v107, v106, s[88:89]
	v_min_u32_e32 v104, v245, v2
	v_max_u32_e32 v105, v245, v2
	v_cndmask_b32_e64 v245, v105, v104, s[88:89]
	v_min_u32_e32 v106, v247, v3
	v_max_u32_e32 v107, v247, v3
	v_cndmask_b32_e64 v247, v107, v106, s[88:89]
	v_min_u32_e32 v104, v242, v4
	v_max_u32_e32 v105, v242, v4
	v_cndmask_b32_e64 v242, v105, v104, s[88:89]
	v_min_u32_e32 v106, v244, v5
	v_max_u32_e32 v107, v244, v5
	v_cndmask_b32_e64 v244, v107, v106, s[88:89]
	v_min_u32_e32 v104, v246, v6
	v_max_u32_e32 v105, v246, v6
	v_cndmask_b32_e64 v246, v105, v104, s[88:89]
	v_min_u32_e32 v106, v248, v7
	v_max_u32_e32 v107, v248, v7
	v_cndmask_b32_e64 v248, v107, v106, s[88:89]
	v_xor_b32_e32 v116, 16, v234
	ds_bpermute_b32 v0, v116, v241
	ds_bpermute_b32 v1, v116, v243
	ds_bpermute_b32 v2, v116, v245
	ds_bpermute_b32 v3, v116, v247
	ds_bpermute_b32 v4, v116, v242
	ds_bpermute_b32 v5, v116, v244
	ds_bpermute_b32 v6, v116, v246
	ds_bpermute_b32 v7, v116, v248
	s_waitcnt lgkmcnt(0)
	s_mov_b32 s88, 0xf0f00f0f
	s_mov_b32 s89, 0xf0f00f0f
	v_min_u32_e32 v104, v241, v0
	v_max_u32_e32 v105, v241, v0
	v_cndmask_b32_e64 v241, v105, v104, s[88:89]
	v_min_u32_e32 v106, v243, v1
	v_max_u32_e32 v107, v243, v1
	v_cndmask_b32_e64 v243, v107, v106, s[88:89]
	v_min_u32_e32 v104, v245, v2
	v_max_u32_e32 v105, v245, v2
	v_cndmask_b32_e64 v245, v105, v104, s[88:89]
	v_min_u32_e32 v106, v247, v3
	v_max_u32_e32 v107, v247, v3
	v_cndmask_b32_e64 v247, v107, v106, s[88:89]
	v_min_u32_e32 v104, v242, v4
	v_max_u32_e32 v105, v242, v4
	v_cndmask_b32_e64 v242, v105, v104, s[88:89]
	v_min_u32_e32 v106, v244, v5
	v_max_u32_e32 v107, v244, v5
	v_cndmask_b32_e64 v244, v107, v106, s[88:89]
	v_min_u32_e32 v104, v246, v6
	v_max_u32_e32 v105, v246, v6
	v_cndmask_b32_e64 v246, v105, v104, s[88:89]
	v_min_u32_e32 v106, v248, v7
	v_max_u32_e32 v107, v248, v7
	v_cndmask_b32_e64 v248, v107, v106, s[88:89]
	v_xor_b32_e32 v116, 8, v234
	ds_bpermute_b32 v0, v116, v241
	ds_bpermute_b32 v1, v116, v243
	ds_bpermute_b32 v2, v116, v245
	ds_bpermute_b32 v3, v116, v247
	ds_bpermute_b32 v4, v116, v242
	ds_bpermute_b32 v5, v116, v244
	ds_bpermute_b32 v6, v116, v246
	ds_bpermute_b32 v7, v116, v248
	s_waitcnt lgkmcnt(0)
; DEV void sort_lists(int lane, int& myi0, int& myi1, float& myg0, float& myg1) {
; #pragma unroll
;     for (int k = 2; k <= 128; k <<= 1) {
; #pragma unroll
;       for (int j = k >> 1; j >= 1; j >>= 1) {
;         if (j == 64) {
;           const bool sw_ = myi1 < myi0;
;           const int ti = sw_ ? myi1 : myi0, tj = sw_ ? myi0 : myi1; const float tg = sw_ ? myg1 : myg0, th = sw_ ? myg0 : myg1;
;           myi0 = ti; myi1 = tj; myg0 = tg; myg1 = th;
;         } else {
;           const bool lower = (lane & j) == 0;
;           {
;             const bool up = (k == 128) ? true : ((k == 64) ? true : ((lane & k) == 0));
;             const int oi = __shfl_xor(myi0, j); const float og = __shfl_xor(myg0, j);
;             const bool take = (lower == up) ? (oi < myi0) : (oi > myi0);
;             myi0 = take ? oi : myi0; myg0 = take ? og : myg0;
;           }
;           {
;             const bool up = (k == 128) ? true : ((k == 64) ? false : ((lane & k) == 0));
;             const int oi = __shfl_xor(myi1, j); const float og = __shfl_xor(myg1, j);
;             const bool take = (lower == up) ? (oi < myi1) : (oi > myi1);
;             myi1 = take ? oi : myi1; myg1 = take ? og : myg1;
;           }
;         }
;       }
;     }
; }
	s_mov_b32 s88, 0xcccc3333
	s_mov_b32 s89, 0xcccc3333
	v_min_u32_e32 v104, v241, v0
	v_max_u32_e32 v105, v241, v0
	v_cndmask_b32_e64 v241, v105, v104, s[88:89]
	v_min_u32_e32 v106, v243, v1
	v_max_u32_e32 v107, v243, v1
	v_cndmask_b32_e64 v243, v107, v106, s[88:89]
	v_min_u32_e32 v104, v245, v2
	v_max_u32_e32 v105, v245, v2
	v_cndmask_b32_e64 v245, v105, v104, s[88:89]
	v_min_u32_e32 v106, v247, v3
	v_max_u32_e32 v107, v247, v3
	v_cndmask_b32_e64 v247, v107, v106, s[88:89]
	v_min_u32_e32 v104, v242, v4
	v_max_u32_e32 v105, v242, v4
	v_cndmask_b32_e64 v242, v105, v104, s[88:89]
	v_min_u32_e32 v106, v244, v5
	v_max_u32_e32 v107, v244, v5
	v_cndmask_b32_e64 v244, v107, v106, s[88:89]
	v_min_u32_e32 v104, v246, v6
	v_max_u32_e32 v105, v246, v6
	v_cndmask_b32_e64 v246, v105, v104, s[88:89]
	v_min_u32_e32 v106, v248, v7
	v_max_u32_e32 v107, v248, v7
	v_cndmask_b32_e64 v248, v107, v106, s[88:89]
	v_xor_b32_e32 v116, 4, v234
	ds_bpermute_b32 v0, v116, v241
	ds_bpermute_b32 v1, v116, v243
	ds_bpermute_b32 v2, v116, v245
	ds_bpermute_b32 v3, v116, v247
	ds_bpermute_b32 v4, v116, v242
	ds_bpermute_b32 v5, v116, v244
	ds_bpermute_b32 v6, v116, v246
	ds_bpermute_b32 v7, v116, v248
	s_waitcnt lgkmcnt(0)
	s_mov_b32 s88, 0xaaaa5555
	s_mov_b32 s89, 0xaaaa5555
	v_min_u32_e32 v104, v241, v0
	v_max_u32_e32 v105, v241, v0
	v_cndmask_b32_e64 v241, v105, v104, s[88:89]
	v_min_u32_e32 v106, v243, v1
	v_max_u32_e32 v107, v243, v1
	v_cndmask_b32_e64 v243, v107, v106, s[88:89]
	v_min_u32_e32 v104, v245, v2
	v_max_u32_e32 v105, v245, v2
	v_cndmask_b32_e64 v245, v105, v104, s[88:89]
	v_min_u32_e32 v106, v247, v3
	v_max_u32_e32 v107, v247, v3
	v_cndmask_b32_e64 v247, v107, v106, s[88:89]
	v_min_u32_e32 v104, v242, v4
	v_max_u32_e32 v105, v242, v4
	v_cndmask_b32_e64 v242, v105, v104, s[88:89]
	v_min_u32_e32 v106, v244, v5
	v_max_u32_e32 v107, v244, v5
	v_cndmask_b32_e64 v244, v107, v106, s[88:89]
	v_min_u32_e32 v104, v246, v6
	v_max_u32_e32 v105, v246, v6
	v_cndmask_b32_e64 v246, v105, v104, s[88:89]
	v_min_u32_e32 v106, v248, v7
	v_max_u32_e32 v107, v248, v7
	v_cndmask_b32_e64 v248, v107, v106, s[88:89]
	v_xor_b32_e32 v116, 64, v234
	ds_bpermute_b32 v0, v116, v241
	ds_bpermute_b32 v1, v116, v243
	ds_bpermute_b32 v2, v116, v245
	ds_bpermute_b32 v3, v116, v247
	ds_bpermute_b32 v4, v116, v242
	ds_bpermute_b32 v5, v116, v244
	ds_bpermute_b32 v6, v116, v246
	ds_bpermute_b32 v7, v116, v248
	s_waitcnt lgkmcnt(0)
	s_mov_b32 s88, 0xffff
	s_mov_b32 s89, 0xffff0000
	v_min_u32_e32 v104, v241, v0
	v_max_u32_e32 v105, v241, v0
	v_cndmask_b32_e64 v241, v105, v104, s[88:89]
	v_min_u32_e32 v106, v243, v1
	v_max_u32_e32 v107, v243, v1
	v_cndmask_b32_e64 v243, v107, v106, s[88:89]
	v_min_u32_e32 v104, v245, v2
	v_max_u32_e32 v105, v245, v2
	v_cndmask_b32_e64 v245, v105, v104, s[88:89]
	v_min_u32_e32 v106, v247, v3
	v_max_u32_e32 v107, v247, v3
	v_cndmask_b32_e64 v247, v107, v106, s[88:89]
	v_min_u32_e32 v104, v242, v4
	v_max_u32_e32 v105, v242, v4
	v_cndmask_b32_e64 v242, v105, v104, s[88:89]
	v_min_u32_e32 v106, v244, v5
	v_max_u32_e32 v107, v244, v5
	v_cndmask_b32_e64 v244, v107, v106, s[88:89]
	v_min_u32_e32 v104, v246, v6
	v_max_u32_e32 v105, v246, v6
	v_cndmask_b32_e64 v246, v105, v104, s[88:89]
	v_min_u32_e32 v106, v248, v7
	v_max_u32_e32 v107, v248, v7
	v_cndmask_b32_e64 v248, v107, v106, s[88:89]
	v_xor_b32_e32 v116, 32, v234
	ds_bpermute_b32 v0, v116, v241
	ds_bpermute_b32 v1, v116, v243
	ds_bpermute_b32 v2, v116, v245
	ds_bpermute_b32 v3, v116, v247
	ds_bpermute_b32 v4, v116, v242
	ds_bpermute_b32 v5, v116, v244
	ds_bpermute_b32 v6, v116, v246
	ds_bpermute_b32 v7, v116, v248
	s_waitcnt lgkmcnt(0)
	s_mov_b32 s88, 0xff00ff
	s_mov_b32 s89, 0xff00ff00
	v_min_u32_e32 v104, v241, v0
	v_max_u32_e32 v105, v241, v0
	v_cndmask_b32_e64 v241, v105, v104, s[88:89]
	v_min_u32_e32 v106, v243, v1
	v_max_u32_e32 v107, v243, v1
	v_cndmask_b32_e64 v243, v107, v106, s[88:89]
	v_min_u32_e32 v104, v245, v2
	v_max_u32_e32 v105, v245, v2
	v_cndmask_b32_e64 v245, v105, v104, s[88:89]
	v_min_u32_e32 v106, v247, v3
	v_max_u32_e32 v107, v247, v3
	v_cndmask_b32_e64 v247, v107, v106, s[88:89]
	v_min_u32_e32 v104, v242, v4
	v_max_u32_e32 v105, v242, v4
	v_cndmask_b32_e64 v242, v105, v104, s[88:89]
	v_min_u32_e32 v106, v244, v5
	v_max_u32_e32 v107, v244, v5
	v_cndmask_b32_e64 v244, v107, v106, s[88:89]
	v_min_u32_e32 v104, v246, v6
	v_max_u32_e32 v105, v246, v6
	v_cndmask_b32_e64 v246, v105, v104, s[88:89]
	v_min_u32_e32 v106, v248, v7
	v_max_u32_e32 v107, v248, v7
	v_cndmask_b32_e64 v248, v107, v106, s[88:89]
	v_xor_b32_e32 v116, 16, v234
	ds_bpermute_b32 v0, v116, v241
	ds_bpermute_b32 v1, v116, v243
	ds_bpermute_b32 v2, v116, v245
	ds_bpermute_b32 v3, v116, v247
	ds_bpermute_b32 v4, v116, v242
	ds_bpermute_b32 v5, v116, v244
	ds_bpermute_b32 v6, v116, v246
	ds_bpermute_b32 v7, v116, v248
	s_waitcnt lgkmcnt(0)
	s_mov_b32 s88, 0xf0f0f0f
	s_mov_b32 s89, 0xf0f0f0f0
	v_min_u32_e32 v104, v241, v0
	v_max_u32_e32 v105, v241, v0
	v_cndmask_b32_e64 v241, v105, v104, s[88:89]
	v_min_u32_e32 v106, v243, v1
	v_max_u32_e32 v107, v243, v1
	v_cndmask_b32_e64 v243, v107, v106, s[88:89]
	v_min_u32_e32 v104, v245, v2
	v_max_u32_e32 v105, v245, v2
	v_cndmask_b32_e64 v245, v105, v104, s[88:89]
	v_min_u32_e32 v106, v247, v3
	v_max_u32_e32 v107, v247, v3
	v_cndmask_b32_e64 v247, v107, v106, s[88:89]
	v_min_u32_e32 v104, v242, v4
	v_max_u32_e32 v105, v242, v4
	v_cndmask_b32_e64 v242, v105, v104, s[88:89]
	v_min_u32_e32 v106, v244, v5
	v_max_u32_e32 v107, v244, v5
	v_cndmask_b32_e64 v244, v107, v106, s[88:89]
	v_min_u32_e32 v104, v246, v6
	v_max_u32_e32 v105, v246, v6
	v_cndmask_b32_e64 v246, v105, v104, s[88:89]
	v_min_u32_e32 v106, v248, v7
	v_max_u32_e32 v107, v248, v7
	v_cndmask_b32_e64 v248, v107, v106, s[88:89]
	v_xor_b32_e32 v116, 8, v234
	ds_bpermute_b32 v0, v116, v241
	ds_bpermute_b32 v1, v116, v243
	ds_bpermute_b32 v2, v116, v245
	ds_bpermute_b32 v3, v116, v247
	ds_bpermute_b32 v4, v116, v242
	ds_bpermute_b32 v5, v116, v244
	ds_bpermute_b32 v6, v116, v246
	ds_bpermute_b32 v7, v116, v248
	s_waitcnt lgkmcnt(0)
; DEV void sort_lists(int lane, int& myi0, int& myi1, float& myg0, float& myg1) {
; #pragma unroll
;     for (int k = 2; k <= 128; k <<= 1) {
; #pragma unroll
;       for (int j = k >> 1; j >= 1; j >>= 1) {
;         if (j == 64) {
;           const bool sw_ = myi1 < myi0;
;           const int ti = sw_ ? myi1 : myi0, tj = sw_ ? myi0 : myi1; const float tg = sw_ ? myg1 : myg0, th = sw_ ? myg0 : myg1;
;           myi0 = ti; myi1 = tj; myg0 = tg; myg1 = th;
;         } else {
;           const bool lower = (lane & j) == 0;
;           {
;             const bool up = (k == 128) ? true : ((k == 64) ? true : ((lane & k) == 0));
;             const int oi = __shfl_xor(myi0, j); const float og = __shfl_xor(myg0, j);
;             const bool take = (lower == up) ? (oi < myi0) : (oi > myi0);
;             myi0 = take ? oi : myi0; myg0 = take ? og : myg0;
;           }
;           {
;             const bool up = (k == 128) ? true : ((k == 64) ? false : ((lane & k) == 0));
;             const int oi = __shfl_xor(myi1, j); const float og = __shfl_xor(myg1, j);
;             const bool take = (lower == up) ? (oi < myi1) : (oi > myi1);
;             myi1 = take ? oi : myi1; myg1 = take ? og : myg1;
;           }
;         }
;       }
;     }
; }
	s_mov_b32 s88, 0x33333333
	s_mov_b32 s89, 0xcccccccc
	v_min_u32_e32 v104, v241, v0
	v_max_u32_e32 v105, v241, v0
	v_cndmask_b32_e64 v241, v105, v104, s[88:89]
	v_min_u32_e32 v106, v243, v1
	v_max_u32_e32 v107, v243, v1
	v_cndmask_b32_e64 v243, v107, v106, s[88:89]
	v_min_u32_e32 v104, v245, v2
	v_max_u32_e32 v105, v245, v2
	v_cndmask_b32_e64 v245, v105, v104, s[88:89]
	v_min_u32_e32 v106, v247, v3
	v_max_u32_e32 v107, v247, v3
	v_cndmask_b32_e64 v247, v107, v106, s[88:89]
	v_min_u32_e32 v104, v242, v4
	v_max_u32_e32 v105, v242, v4
	v_cndmask_b32_e64 v242, v105, v104, s[88:89]
	v_min_u32_e32 v106, v244, v5
	v_max_u32_e32 v107, v244, v5
	v_cndmask_b32_e64 v244, v107, v106, s[88:89]
	v_min_u32_e32 v104, v246, v6
	v_max_u32_e32 v105, v246, v6
	v_cndmask_b32_e64 v246, v105, v104, s[88:89]
	v_min_u32_e32 v106, v248, v7
	v_max_u32_e32 v107, v248, v7
	v_cndmask_b32_e64 v248, v107, v106, s[88:89]
	v_xor_b32_e32 v116, 4, v234
	ds_bpermute_b32 v0, v116, v241
	ds_bpermute_b32 v1, v116, v243
	ds_bpermute_b32 v2, v116, v245
	ds_bpermute_b32 v3, v116, v247
	ds_bpermute_b32 v4, v116, v242
	ds_bpermute_b32 v5, v116, v244
	ds_bpermute_b32 v6, v116, v246
	ds_bpermute_b32 v7, v116, v248
	s_waitcnt lgkmcnt(0)
	s_mov_b32 s88, 0x55555555
	s_mov_b32 s89, 0xaaaaaaaa
	v_min_u32_e32 v104, v241, v0
	v_max_u32_e32 v105, v241, v0
	v_cndmask_b32_e64 v241, v105, v104, s[88:89]
	v_min_u32_e32 v106, v243, v1
	v_max_u32_e32 v107, v243, v1
	v_cndmask_b32_e64 v243, v107, v106, s[88:89]
	v_min_u32_e32 v104, v245, v2
	v_max_u32_e32 v105, v245, v2
	v_cndmask_b32_e64 v245, v105, v104, s[88:89]
	v_min_u32_e32 v106, v247, v3
	v_max_u32_e32 v107, v247, v3
	v_cndmask_b32_e64 v247, v107, v106, s[88:89]
	v_min_u32_e32 v104, v242, v4
	v_max_u32_e32 v105, v242, v4
	v_cndmask_b32_e64 v242, v105, v104, s[88:89]
	v_min_u32_e32 v106, v244, v5
	v_max_u32_e32 v107, v244, v5
	v_cndmask_b32_e64 v244, v107, v106, s[88:89]
	v_min_u32_e32 v104, v246, v6
	v_max_u32_e32 v105, v246, v6
	v_cndmask_b32_e64 v246, v105, v104, s[88:89]
	v_min_u32_e32 v106, v248, v7
	v_max_u32_e32 v107, v248, v7
	v_cndmask_b32_e64 v248, v107, v106, s[88:89]
	v_xor_b32_e32 v116, 128, v234
	ds_bpermute_b32 v0, v116, v241
	ds_bpermute_b32 v1, v116, v243
	ds_bpermute_b32 v2, v116, v245
	ds_bpermute_b32 v3, v116, v247
	ds_bpermute_b32 v4, v116, v242
	ds_bpermute_b32 v5, v116, v244
	ds_bpermute_b32 v6, v116, v246
	ds_bpermute_b32 v7, v116, v248
	s_waitcnt lgkmcnt(0)
	s_mov_b32 s88, 0xffffffff
	s_mov_b32 s89, 0x0
	v_min_u32_e32 v104, v241, v0
	v_max_u32_e32 v105, v241, v0
	v_cndmask_b32_e64 v241, v105, v104, s[88:89]
	v_min_u32_e32 v106, v243, v1
	v_max_u32_e32 v107, v243, v1
	v_cndmask_b32_e64 v243, v107, v106, s[88:89]
	v_min_u32_e32 v104, v245, v2
	v_max_u32_e32 v105, v245, v2
	v_cndmask_b32_e64 v245, v105, v104, s[88:89]
	v_min_u32_e32 v106, v247, v3
	v_max_u32_e32 v107, v247, v3
	v_cndmask_b32_e64 v247, v107, v106, s[88:89]
	s_mov_b32 s88, 0x0
	s_mov_b32 s89, 0xffffffff
	v_min_u32_e32 v104, v242, v4
	v_max_u32_e32 v105, v242, v4
	v_cndmask_b32_e64 v242, v105, v104, s[88:89]
	v_min_u32_e32 v106, v244, v5
	v_max_u32_e32 v107, v244, v5
	v_cndmask_b32_e64 v244, v107, v106, s[88:89]
	v_min_u32_e32 v104, v246, v6
	v_max_u32_e32 v105, v246, v6
	v_cndmask_b32_e64 v246, v105, v104, s[88:89]
	v_min_u32_e32 v106, v248, v7
	v_max_u32_e32 v107, v248, v7
	v_cndmask_b32_e64 v248, v107, v106, s[88:89]
	v_xor_b32_e32 v116, 64, v234
	ds_bpermute_b32 v0, v116, v241
	ds_bpermute_b32 v1, v116, v243
	ds_bpermute_b32 v2, v116, v245
	ds_bpermute_b32 v3, v116, v247
	ds_bpermute_b32 v4, v116, v242
	ds_bpermute_b32 v5, v116, v244
	ds_bpermute_b32 v6, v116, v246
	ds_bpermute_b32 v7, v116, v248
	s_waitcnt lgkmcnt(0)
	s_mov_b32 s88, 0xffff
	s_mov_b32 s89, 0xffff
	v_min_u32_e32 v104, v241, v0
	v_max_u32_e32 v105, v241, v0
	v_cndmask_b32_e64 v241, v105, v104, s[88:89]
	v_min_u32_e32 v106, v243, v1
	v_max_u32_e32 v107, v243, v1
	v_cndmask_b32_e64 v243, v107, v106, s[88:89]
	v_min_u32_e32 v104, v245, v2
	v_max_u32_e32 v105, v245, v2
	v_cndmask_b32_e64 v245, v105, v104, s[88:89]
	v_min_u32_e32 v106, v247, v3
	v_max_u32_e32 v107, v247, v3
	v_cndmask_b32_e64 v247, v107, v106, s[88:89]
	s_mov_b32 s88, 0xffff0000
	s_mov_b32 s89, 0xffff0000
	v_min_u32_e32 v104, v242, v4
	v_max_u32_e32 v105, v242, v4
	v_cndmask_b32_e64 v242, v105, v104, s[88:89]
	v_min_u32_e32 v106, v244, v5
	v_max_u32_e32 v107, v244, v5
	v_cndmask_b32_e64 v244, v107, v106, s[88:89]
	v_min_u32_e32 v104, v246, v6
	v_max_u32_e32 v105, v246, v6
	v_cndmask_b32_e64 v246, v105, v104, s[88:89]
	v_min_u32_e32 v106, v248, v7
	v_max_u32_e32 v107, v248, v7
	v_cndmask_b32_e64 v248, v107, v106, s[88:89]
	v_xor_b32_e32 v116, 32, v234
	ds_bpermute_b32 v0, v116, v241
	ds_bpermute_b32 v1, v116, v243
	ds_bpermute_b32 v2, v116, v245
	ds_bpermute_b32 v3, v116, v247
	ds_bpermute_b32 v4, v116, v242
	ds_bpermute_b32 v5, v116, v244
	ds_bpermute_b32 v6, v116, v246
	ds_bpermute_b32 v7, v116, v248
	s_waitcnt lgkmcnt(0)
	s_mov_b32 s88, 0xff00ff
	s_mov_b32 s89, 0xff00ff
	v_min_u32_e32 v104, v241, v0
	v_max_u32_e32 v105, v241, v0
	v_cndmask_b32_e64 v241, v105, v104, s[88:89]
	v_min_u32_e32 v106, v243, v1
	v_max_u32_e32 v107, v243, v1
	v_cndmask_b32_e64 v243, v107, v106, s[88:89]
	v_min_u32_e32 v104, v245, v2
	v_max_u32_e32 v105, v245, v2
	v_cndmask_b32_e64 v245, v105, v104, s[88:89]
	v_min_u32_e32 v106, v247, v3
	v_max_u32_e32 v107, v247, v3
	v_cndmask_b32_e64 v247, v107, v106, s[88:89]
	s_mov_b32 s88, 0xff00ff00
	s_mov_b32 s89, 0xff00ff00
	v_min_u32_e32 v104, v242, v4
	v_max_u32_e32 v105, v242, v4
	v_cndmask_b32_e64 v242, v105, v104, s[88:89]
	v_min_u32_e32 v106, v244, v5
	v_max_u32_e32 v107, v244, v5
	v_cndmask_b32_e64 v244, v107, v106, s[88:89]
	v_min_u32_e32 v104, v246, v6
	v_max_u32_e32 v105, v246, v6
	v_cndmask_b32_e64 v246, v105, v104, s[88:89]
	v_min_u32_e32 v106, v248, v7
	v_max_u32_e32 v107, v248, v7
	v_cndmask_b32_e64 v248, v107, v106, s[88:89]
	v_xor_b32_e32 v116, 16, v234
	ds_bpermute_b32 v0, v116, v241
	ds_bpermute_b32 v1, v116, v243
	ds_bpermute_b32 v2, v116, v245
	ds_bpermute_b32 v3, v116, v247
	ds_bpermute_b32 v4, v116, v242
	ds_bpermute_b32 v5, v116, v244
	ds_bpermute_b32 v6, v116, v246
	ds_bpermute_b32 v7, v116, v248
	s_waitcnt lgkmcnt(0)
; DEV void sort_lists(int lane, int& myi0, int& myi1, float& myg0, float& myg1) {
; #pragma unroll
;     for (int k = 2; k <= 128; k <<= 1) {
; #pragma unroll
;       for (int j = k >> 1; j >= 1; j >>= 1) {
;         if (j == 64) {
;           const bool sw_ = myi1 < myi0;
;           const int ti = sw_ ? myi1 : myi0, tj = sw_ ? myi0 : myi1; const float tg = sw_ ? myg1 : myg0, th = sw_ ? myg0 : myg1;
;           myi0 = ti; myi1 = tj; myg0 = tg; myg1 = th;
;         } else {
;           const bool lower = (lane & j) == 0;
;           {
;             const bool up = (k == 128) ? true : ((k == 64) ? true : ((lane & k) == 0));
;             const int oi = __shfl_xor(myi0, j); const float og = __shfl_xor(myg0, j);
;             const bool take = (lower == up) ? (oi < myi0) : (oi > myi0);
;             myi0 = take ? oi : myi0; myg0 = take ? og : myg0;
;           }
;           {
;             const bool up = (k == 128) ? true : ((k == 64) ? false : ((lane & k) == 0));
;             const int oi = __shfl_xor(myi1, j); const float og = __shfl_xor(myg1, j);
;             const bool take = (lower == up) ? (oi < myi1) : (oi > myi1);
;             myi1 = take ? oi : myi1; myg1 = take ? og : myg1;
;           }
;         }
;       }
;     }
; }
	s_mov_b32 s88, 0xf0f0f0f
	s_mov_b32 s89, 0xf0f0f0f
	v_min_u32_e32 v104, v241, v0
	v_max_u32_e32 v105, v241, v0
	v_cndmask_b32_e64 v241, v105, v104, s[88:89]
	v_min_u32_e32 v106, v243, v1
	v_max_u32_e32 v107, v243, v1
	v_cndmask_b32_e64 v243, v107, v106, s[88:89]
	v_min_u32_e32 v104, v245, v2
	v_max_u32_e32 v105, v245, v2
	v_cndmask_b32_e64 v245, v105, v104, s[88:89]
	v_min_u32_e32 v106, v247, v3
	v_max_u32_e32 v107, v247, v3
	v_cndmask_b32_e64 v247, v107, v106, s[88:89]
	s_mov_b32 s88, 0xf0f0f0f0
	s_mov_b32 s89, 0xf0f0f0f0
	v_min_u32_e32 v104, v242, v4
	v_max_u32_e32 v105, v242, v4
	v_cndmask_b32_e64 v242, v105, v104, s[88:89]
	v_min_u32_e32 v106, v244, v5
	v_max_u32_e32 v107, v244, v5
	v_cndmask_b32_e64 v244, v107, v106, s[88:89]
	v_min_u32_e32 v104, v246, v6
	v_max_u32_e32 v105, v246, v6
	v_cndmask_b32_e64 v246, v105, v104, s[88:89]
	v_min_u32_e32 v106, v248, v7
	v_max_u32_e32 v107, v248, v7
	v_cndmask_b32_e64 v248, v107, v106, s[88:89]
	v_xor_b32_e32 v116, 8, v234
	ds_bpermute_b32 v0, v116, v241
	ds_bpermute_b32 v1, v116, v243
	ds_bpermute_b32 v2, v116, v245
	ds_bpermute_b32 v3, v116, v247
	ds_bpermute_b32 v4, v116, v242
	ds_bpermute_b32 v5, v116, v244
	ds_bpermute_b32 v6, v116, v246
	ds_bpermute_b32 v7, v116, v248
	s_waitcnt lgkmcnt(0)
	s_mov_b32 s88, 0x33333333
	s_mov_b32 s89, 0x33333333
	v_min_u32_e32 v104, v241, v0
	v_max_u32_e32 v105, v241, v0
	v_cndmask_b32_e64 v241, v105, v104, s[88:89]
	v_min_u32_e32 v106, v243, v1
	v_max_u32_e32 v107, v243, v1
	v_cndmask_b32_e64 v243, v107, v106, s[88:89]
	v_min_u32_e32 v104, v245, v2
	v_max_u32_e32 v105, v245, v2
	v_cndmask_b32_e64 v245, v105, v104, s[88:89]
	v_min_u32_e32 v106, v247, v3
	v_max_u32_e32 v107, v247, v3
	v_cndmask_b32_e64 v247, v107, v106, s[88:89]
	s_mov_b32 s88, 0xcccccccc
	s_mov_b32 s89, 0xcccccccc
	v_min_u32_e32 v104, v242, v4
	v_max_u32_e32 v105, v242, v4
	v_cndmask_b32_e64 v242, v105, v104, s[88:89]
	v_min_u32_e32 v106, v244, v5
	v_max_u32_e32 v107, v244, v5
	v_cndmask_b32_e64 v244, v107, v106, s[88:89]
	v_min_u32_e32 v104, v246, v6
	v_max_u32_e32 v105, v246, v6
	v_cndmask_b32_e64 v246, v105, v104, s[88:89]
	v_min_u32_e32 v106, v248, v7
	v_max_u32_e32 v107, v248, v7
	v_cndmask_b32_e64 v248, v107, v106, s[88:89]
	v_xor_b32_e32 v116, 4, v234
	ds_bpermute_b32 v0, v116, v241
	ds_bpermute_b32 v1, v116, v243
	ds_bpermute_b32 v2, v116, v245
	ds_bpermute_b32 v3, v116, v247
	ds_bpermute_b32 v4, v116, v242
	ds_bpermute_b32 v5, v116, v244
	ds_bpermute_b32 v6, v116, v246
	ds_bpermute_b32 v7, v116, v248
	s_waitcnt lgkmcnt(0)
	s_mov_b32 s88, 0x55555555
	s_mov_b32 s89, 0x55555555
	v_min_u32_e32 v104, v241, v0
	v_max_u32_e32 v105, v241, v0
	v_cndmask_b32_e64 v241, v105, v104, s[88:89]
	v_min_u32_e32 v106, v243, v1
	v_max_u32_e32 v107, v243, v1
	v_cndmask_b32_e64 v243, v107, v106, s[88:89]
	v_min_u32_e32 v104, v245, v2
	v_max_u32_e32 v105, v245, v2
	v_cndmask_b32_e64 v245, v105, v104, s[88:89]
	v_min_u32_e32 v106, v247, v3
	v_max_u32_e32 v107, v247, v3
	v_cndmask_b32_e64 v247, v107, v106, s[88:89]
	s_mov_b32 s88, 0xaaaaaaaa
	s_mov_b32 s89, 0xaaaaaaaa
	v_min_u32_e32 v104, v242, v4
	v_max_u32_e32 v105, v242, v4
	v_cndmask_b32_e64 v242, v105, v104, s[88:89]
	v_min_u32_e32 v106, v244, v5
	v_max_u32_e32 v107, v244, v5
	v_cndmask_b32_e64 v244, v107, v106, s[88:89]
	v_min_u32_e32 v104, v246, v6
	v_max_u32_e32 v105, v246, v6
	v_cndmask_b32_e64 v246, v105, v104, s[88:89]
	v_min_u32_e32 v106, v248, v7
	v_max_u32_e32 v107, v248, v7
	v_cndmask_b32_e64 v248, v107, v106, s[88:89]
	v_min_u32_e32 v104, v241, v242
	v_max_u32_e32 v242, v241, v242
	v_mov_b32_e32 v241, v104
	v_min_u32_e32 v106, v243, v244
	v_max_u32_e32 v244, v243, v244
	v_mov_b32_e32 v243, v106
	v_min_u32_e32 v104, v245, v246
	v_max_u32_e32 v246, v245, v246
	v_mov_b32_e32 v245, v104
	v_min_u32_e32 v106, v247, v248
	v_max_u32_e32 v248, v247, v248
	v_mov_b32_e32 v247, v106
	v_xor_b32_e32 v116, 128, v234
	ds_bpermute_b32 v0, v116, v241
	ds_bpermute_b32 v1, v116, v243
	ds_bpermute_b32 v2, v116, v245
	ds_bpermute_b32 v3, v116, v247
	ds_bpermute_b32 v4, v116, v242
	ds_bpermute_b32 v5, v116, v244
	ds_bpermute_b32 v6, v116, v246
	ds_bpermute_b32 v7, v116, v248
	s_waitcnt lgkmcnt(0)
	s_mov_b32 s88, 0xffffffff
	s_mov_b32 s89, 0x0
	v_min_u32_e32 v104, v241, v0
	v_max_u32_e32 v105, v241, v0
	v_cndmask_b32_e64 v241, v105, v104, s[88:89]
	v_min_u32_e32 v106, v243, v1
	v_max_u32_e32 v107, v243, v1
	v_cndmask_b32_e64 v243, v107, v106, s[88:89]
	v_min_u32_e32 v104, v245, v2
	v_max_u32_e32 v105, v245, v2
	v_cndmask_b32_e64 v245, v105, v104, s[88:89]
	v_min_u32_e32 v106, v247, v3
	v_max_u32_e32 v107, v247, v3
	v_cndmask_b32_e64 v247, v107, v106, s[88:89]
	v_min_u32_e32 v104, v242, v4
	v_max_u32_e32 v105, v242, v4
	v_cndmask_b32_e64 v242, v105, v104, s[88:89]
	v_min_u32_e32 v106, v244, v5
	v_max_u32_e32 v107, v244, v5
	v_cndmask_b32_e64 v244, v107, v106, s[88:89]
	v_min_u32_e32 v104, v246, v6
	v_max_u32_e32 v105, v246, v6
	v_cndmask_b32_e64 v246, v105, v104, s[88:89]
	v_min_u32_e32 v106, v248, v7
	v_max_u32_e32 v107, v248, v7
	v_cndmask_b32_e64 v248, v107, v106, s[88:89]
	v_xor_b32_e32 v116, 64, v234
	ds_bpermute_b32 v0, v116, v241
	ds_bpermute_b32 v1, v116, v243
	ds_bpermute_b32 v2, v116, v245
	ds_bpermute_b32 v3, v116, v247
	ds_bpermute_b32 v4, v116, v242
	ds_bpermute_b32 v5, v116, v244
	ds_bpermute_b32 v6, v116, v246
	ds_bpermute_b32 v7, v116, v248
	s_waitcnt lgkmcnt(0)
; DEV void sort_lists(int lane, int& myi0, int& myi1, float& myg0, float& myg1) {
; #pragma unroll
;     for (int k = 2; k <= 128; k <<= 1) {
; #pragma unroll
;       for (int j = k >> 1; j >= 1; j >>= 1) {
;         if (j == 64) {
;           const bool sw_ = myi1 < myi0;
;           const int ti = sw_ ? myi1 : myi0, tj = sw_ ? myi0 : myi1; const float tg = sw_ ? myg1 : myg0, th = sw_ ? myg0 : myg1;
;           myi0 = ti; myi1 = tj; myg0 = tg; myg1 = th;
;         } else {
;           const bool lower = (lane & j) == 0;
;           {
;             const bool up = (k == 128) ? true : ((k == 64) ? true : ((lane & k) == 0));
;             const int oi = __shfl_xor(myi0, j); const float og = __shfl_xor(myg0, j);
;             const bool take = (lower == up) ? (oi < myi0) : (oi > myi0);
;             myi0 = take ? oi : myi0; myg0 = take ? og : myg0;
;           }
;           {
;             const bool up = (k == 128) ? true : ((k == 64) ? false : ((lane & k) == 0));
;             const int oi = __shfl_xor(myi1, j); const float og = __shfl_xor(myg1, j);
;             const bool take = (lower == up) ? (oi < myi1) : (oi > myi1);
;             myi1 = take ? oi : myi1; myg1 = take ? og : myg1;
;           }
;         }
;       }
;     }
; }
; DEV void peer_gather(const Params& P, int l, int m0, const int* idxs, const float* gs) {
;     ...
;   int ni0 = idxs[(wid * 16) * 128 + lane], ni1 = idxs[(wid * 16) * 128 + 64 + lane];
;   float ng0 = gs[(wid * 16) * 128 + lane], ng1 = gs[(wid * 16) * 128 + 64 + lane];
;   sort_lists(lane, ni0, ni1, ng0, ng1);
	s_mov_b32 s88, 0xffff
	s_mov_b32 s89, 0xffff
	v_min_u32_e32 v104, v241, v0
	v_max_u32_e32 v105, v241, v0
	v_cndmask_b32_e64 v241, v105, v104, s[88:89]
	v_min_u32_e32 v106, v243, v1
	v_max_u32_e32 v107, v243, v1
	v_cndmask_b32_e64 v243, v107, v106, s[88:89]
	v_min_u32_e32 v104, v245, v2
	v_max_u32_e32 v105, v245, v2
	v_cndmask_b32_e64 v245, v105, v104, s[88:89]
	v_min_u32_e32 v106, v247, v3
	v_max_u32_e32 v107, v247, v3
	v_cndmask_b32_e64 v247, v107, v106, s[88:89]
	v_min_u32_e32 v104, v242, v4
	v_max_u32_e32 v105, v242, v4
	v_cndmask_b32_e64 v242, v105, v104, s[88:89]
	v_min_u32_e32 v106, v244, v5
	v_max_u32_e32 v107, v244, v5
	v_cndmask_b32_e64 v244, v107, v106, s[88:89]
	v_min_u32_e32 v104, v246, v6
	v_max_u32_e32 v105, v246, v6
	v_cndmask_b32_e64 v246, v105, v104, s[88:89]
	v_min_u32_e32 v106, v248, v7
	v_max_u32_e32 v107, v248, v7
	v_cndmask_b32_e64 v248, v107, v106, s[88:89]
	v_xor_b32_e32 v116, 32, v234
	ds_bpermute_b32 v0, v116, v241
	ds_bpermute_b32 v1, v116, v243
	ds_bpermute_b32 v2, v116, v245
	ds_bpermute_b32 v3, v116, v247
	ds_bpermute_b32 v4, v116, v242
	ds_bpermute_b32 v5, v116, v244
	ds_bpermute_b32 v6, v116, v246
	ds_bpermute_b32 v7, v116, v248
	s_waitcnt lgkmcnt(0)
	s_mov_b32 s88, 0xff00ff
	s_mov_b32 s89, 0xff00ff
	v_min_u32_e32 v104, v241, v0
	v_max_u32_e32 v105, v241, v0
	v_cndmask_b32_e64 v241, v105, v104, s[88:89]
	v_min_u32_e32 v106, v243, v1
	v_max_u32_e32 v107, v243, v1
	v_cndmask_b32_e64 v243, v107, v106, s[88:89]
	v_min_u32_e32 v104, v245, v2
	v_max_u32_e32 v105, v245, v2
	v_cndmask_b32_e64 v245, v105, v104, s[88:89]
	v_min_u32_e32 v106, v247, v3
	v_max_u32_e32 v107, v247, v3
	v_cndmask_b32_e64 v247, v107, v106, s[88:89]
	v_min_u32_e32 v104, v242, v4
	v_max_u32_e32 v105, v242, v4
	v_cndmask_b32_e64 v242, v105, v104, s[88:89]
	v_min_u32_e32 v106, v244, v5
	v_max_u32_e32 v107, v244, v5
	v_cndmask_b32_e64 v244, v107, v106, s[88:89]
	v_min_u32_e32 v104, v246, v6
	v_max_u32_e32 v105, v246, v6
	v_cndmask_b32_e64 v246, v105, v104, s[88:89]
	v_min_u32_e32 v106, v248, v7
	v_max_u32_e32 v107, v248, v7
	v_cndmask_b32_e64 v248, v107, v106, s[88:89]
	v_xor_b32_e32 v116, 16, v234
	ds_bpermute_b32 v0, v116, v241
	ds_bpermute_b32 v1, v116, v243
	ds_bpermute_b32 v2, v116, v245
	ds_bpermute_b32 v3, v116, v247
	ds_bpermute_b32 v4, v116, v242
	ds_bpermute_b32 v5, v116, v244
	ds_bpermute_b32 v6, v116, v246
	ds_bpermute_b32 v7, v116, v248
	s_waitcnt lgkmcnt(0)
	s_mov_b32 s88, 0xf0f0f0f
	s_mov_b32 s89, 0xf0f0f0f
	v_min_u32_e32 v104, v241, v0
	v_max_u32_e32 v105, v241, v0
	v_cndmask_b32_e64 v241, v105, v104, s[88:89]
	v_min_u32_e32 v106, v243, v1
	v_max_u32_e32 v107, v243, v1
	v_cndmask_b32_e64 v243, v107, v106, s[88:89]
	v_min_u32_e32 v104, v245, v2
	v_max_u32_e32 v105, v245, v2
	v_cndmask_b32_e64 v245, v105, v104, s[88:89]
	v_min_u32_e32 v106, v247, v3
	v_max_u32_e32 v107, v247, v3
	v_cndmask_b32_e64 v247, v107, v106, s[88:89]
	v_min_u32_e32 v104, v242, v4
	v_max_u32_e32 v105, v242, v4
	v_cndmask_b32_e64 v242, v105, v104, s[88:89]
	v_min_u32_e32 v106, v244, v5
	v_max_u32_e32 v107, v244, v5
	v_cndmask_b32_e64 v244, v107, v106, s[88:89]
	v_min_u32_e32 v104, v246, v6
	v_max_u32_e32 v105, v246, v6
	v_cndmask_b32_e64 v246, v105, v104, s[88:89]
	v_min_u32_e32 v106, v248, v7
	v_max_u32_e32 v107, v248, v7
	v_cndmask_b32_e64 v248, v107, v106, s[88:89]
	v_xor_b32_e32 v116, 8, v234
	ds_bpermute_b32 v0, v116, v241
	ds_bpermute_b32 v1, v116, v243
	ds_bpermute_b32 v2, v116, v245
	ds_bpermute_b32 v3, v116, v247
	ds_bpermute_b32 v4, v116, v242
	ds_bpermute_b32 v5, v116, v244
	ds_bpermute_b32 v6, v116, v246
	ds_bpermute_b32 v7, v116, v248
	s_waitcnt lgkmcnt(0)
	s_mov_b32 s88, 0x33333333
	s_mov_b32 s89, 0x33333333
	v_min_u32_e32 v104, v241, v0
	v_max_u32_e32 v105, v241, v0
	v_cndmask_b32_e64 v241, v105, v104, s[88:89]
	v_min_u32_e32 v106, v243, v1
	v_max_u32_e32 v107, v243, v1
	v_cndmask_b32_e64 v243, v107, v106, s[88:89]
	v_min_u32_e32 v104, v245, v2
	v_max_u32_e32 v105, v245, v2
	v_cndmask_b32_e64 v245, v105, v104, s[88:89]
	v_min_u32_e32 v106, v247, v3
	v_max_u32_e32 v107, v247, v3
	v_cndmask_b32_e64 v247, v107, v106, s[88:89]
	v_min_u32_e32 v104, v242, v4
	v_max_u32_e32 v105, v242, v4
	v_cndmask_b32_e64 v242, v105, v104, s[88:89]
	v_min_u32_e32 v106, v244, v5
	v_max_u32_e32 v107, v244, v5
	v_cndmask_b32_e64 v244, v107, v106, s[88:89]
	v_min_u32_e32 v104, v246, v6
	v_max_u32_e32 v105, v246, v6
	v_cndmask_b32_e64 v246, v105, v104, s[88:89]
	v_min_u32_e32 v106, v248, v7
	v_max_u32_e32 v107, v248, v7
	v_cndmask_b32_e64 v248, v107, v106, s[88:89]
	v_xor_b32_e32 v116, 4, v234
	ds_bpermute_b32 v0, v116, v241
	ds_bpermute_b32 v1, v116, v243
	ds_bpermute_b32 v2, v116, v245
	ds_bpermute_b32 v3, v116, v247
	ds_bpermute_b32 v4, v116, v242
	ds_bpermute_b32 v5, v116, v244
	ds_bpermute_b32 v6, v116, v246
	ds_bpermute_b32 v7, v116, v248
	s_waitcnt lgkmcnt(0)
	s_mov_b32 s88, 0x55555555
	s_mov_b32 s89, 0x55555555
	v_min_u32_e32 v104, v241, v0
	v_max_u32_e32 v105, v241, v0
	v_cndmask_b32_e64 v241, v105, v104, s[88:89]
	v_min_u32_e32 v106, v243, v1
	v_max_u32_e32 v107, v243, v1
	v_cndmask_b32_e64 v243, v107, v106, s[88:89]
	v_min_u32_e32 v104, v245, v2
	v_max_u32_e32 v105, v245, v2
	v_cndmask_b32_e64 v245, v105, v104, s[88:89]
	v_min_u32_e32 v106, v247, v3
	v_max_u32_e32 v107, v247, v3
	v_cndmask_b32_e64 v247, v107, v106, s[88:89]
	v_min_u32_e32 v104, v242, v4
	v_max_u32_e32 v105, v242, v4
	v_cndmask_b32_e64 v242, v105, v104, s[88:89]
	v_min_u32_e32 v106, v244, v5
	v_max_u32_e32 v107, v244, v5
	v_cndmask_b32_e64 v244, v107, v106, s[88:89]
	v_min_u32_e32 v104, v246, v6
	v_max_u32_e32 v105, v246, v6
	v_cndmask_b32_e64 v246, v105, v104, s[88:89]
	v_min_u32_e32 v106, v248, v7
	v_max_u32_e32 v107, v248, v7
	v_cndmask_b32_e64 v248, v107, v106, s[88:89]
	v_mov_b32_e32 v117, 0
	s_lshl_b32 s98, s2, 11
	s_add_u32 s98, s98, s101
	v_add_u32_e32 v116, s98, v234
	ds_write_b32 v116, v241 offset:0
	ds_write_b32 v116, v242 offset:256
	ds_write_b32 v116, v243 offset:512
	ds_write_b32 v116, v244 offset:768
	ds_write_b32 v116, v245 offset:1024
	ds_write_b32 v116, v246 offset:1280
	ds_write_b32 v116, v247 offset:1536
	ds_write_b32 v116, v248 offset:1792
	v_add_u32_e32 v118, 0x10000, v116
	ds_write_b32 v118, v117 offset:0
	ds_write_b32 v118, v117 offset:256
	ds_write_b32 v118, v117 offset:512
	ds_write_b32 v118, v117 offset:768
	ds_write_b32 v118, v117 offset:1024
	ds_write_b32 v118, v117 offset:1280
	ds_write_b32 v118, v117 offset:1536
	ds_write_b32 v118, v117 offset:1792
	s_add_u32 s2, s2, 1
	s_cmp_lt_u32 s2, 4
	s_cbranch_scc1 .Lpg0_p0
; #define PG_ISSUE(BUF, TAB, e0_) do { const int isrc_ = ((e0_) < 64) ? myi0 : myi1; \
;       _Pragma("unroll") for (int e = 0; e < 8; ++e) { const int idx_ = __builtin_amdgcn_readlane(isrc_, ((e0_) + e) & 63); \
;         BUF[e] = *(const u32x4*)((TAB) + (size_t)idx_ * 1024 + lane * 16); } } while (0)
; DEV void peer_gather(const Params& P, int l, int m0, const int* idxs, const float* gs) {
;     ...
;     for (int e0 = 0; e0 < 128; e0 += 16) {
;       PG_ISSUE(b1, U, e0 + 8);
;       PG_U8(b0, 0, e0);
;       if (e0 + 16 < 128) PG_ISSUE(b0, U, e0 + 16); else PG_ISSUE(b0, V, 0);
;       PG_U8(b1, 0, e0 + 8);
;     }
	s_waitcnt lgkmcnt(0)
	v_lshrrev_b32_e32 v248, 3, v233
	v_readfirstlane_b32 s82, v128
	v_readfirstlane_b32 s83, v129
	s_nop 4
	v_readfirstlane_b32 s80, v124
	v_readfirstlane_b32 s81, v125
	s_nop 4
	s_mov_b32 s90, 0xffffff80
	s_mov_b32 s86, 0xcccccccc
	s_mov_b32 s87, 0xcccccccc
	s_mov_b32 s88, 0xaaaaaaaa
	s_mov_b32 s89, 0xaaaaaaaa
	s_mov_b32 s100, 0
	s_mov_b32 s98, 0
	s_mov_b32 s99, 0
	s_add_u32 vcc_lo, s3, s98
	s_lshl_b32 vcc_lo, vcc_lo, 11
	s_lshl_b32 vcc_hi, s99, 8
	s_add_u32 vcc_lo, vcc_lo, vcc_hi
	v_add_u32_e32 v119, vcc_lo, v236
	global_load_dwordx4 v[80:83], v119, s[82:83]
	global_load_dwordx4 v[84:87], v119, s[82:83] offset:16
	s_lshl_b32 vcc_lo, s98, 9
	s_add_u32 vcc_lo, vcc_lo, s101
	v_add_u32_e32 v116, vcc_lo, v234
	ds_read_b32 v134, v116
	ds_read_b32 v135, v116 offset:256
	s_lshl_b32 vcc_lo, s99, 21
	s_add_u32 s84, s80, vcc_lo
	s_addc_u32 s85, s81, 0
	v_mov_b32_e32 v240, v235
	s_waitcnt lgkmcnt(0)
	ds_bpermute_b32 v142, v249, v134
	ds_bpermute_b32 v143, v250, v134
	s_waitcnt lgkmcnt(0)
	v_and_or_b32 v142, v142, s90, v240
	v_and_or_b32 v143, v143, s90, v240
	global_load_dwordx4 v[0:3], v142, s[84:85]
	global_load_dwordx4 v[4:7], v143, s[84:85]
	ds_bpermute_b32 v142, v251, v134
	ds_bpermute_b32 v143, v252, v134
	s_waitcnt lgkmcnt(0)
	v_and_or_b32 v142, v142, s90, v240
	v_and_or_b32 v143, v143, s90, v240
	global_load_dwordx4 v[8:11], v142, s[84:85]
	global_load_dwordx4 v[12:15], v143, s[84:85]
	ds_bpermute_b32 v142, v253, v134
	ds_bpermute_b32 v143, v254, v134
	s_waitcnt lgkmcnt(0)
	v_and_or_b32 v142, v142, s90, v240
	v_and_or_b32 v143, v143, s90, v240
	global_load_dwordx4 v[16:19], v142, s[84:85]
	global_load_dwordx4 v[20:23], v143, s[84:85]
	ds_bpermute_b32 v142, v255, v134
	ds_bpermute_b32 v143, v153, v134
	s_waitcnt lgkmcnt(0)
	v_and_or_b32 v142, v142, s90, v240
	v_and_or_b32 v143, v143, s90, v240
	global_load_dwordx4 v[24:27], v142, s[84:85]
	global_load_dwordx4 v[28:31], v143, s[84:85]
	ds_bpermute_b32 v142, v249, v135
	ds_bpermute_b32 v143, v250, v135
	s_waitcnt lgkmcnt(0)
	v_and_or_b32 v142, v142, s90, v240
	v_and_or_b32 v143, v143, s90, v240
	global_load_dwordx4 v[32:35], v142, s[84:85]
	global_load_dwordx4 v[36:39], v143, s[84:85]
	ds_bpermute_b32 v142, v251, v135
	ds_bpermute_b32 v143, v252, v135
	s_waitcnt lgkmcnt(0)
	v_and_or_b32 v142, v142, s90, v240
	v_and_or_b32 v143, v143, s90, v240
	global_load_dwordx4 v[40:43], v142, s[84:85]
	global_load_dwordx4 v[44:47], v143, s[84:85]
	ds_bpermute_b32 v142, v253, v135
	ds_bpermute_b32 v143, v254, v135
	s_waitcnt lgkmcnt(0)
	v_and_or_b32 v142, v142, s90, v240
	v_and_or_b32 v143, v143, s90, v240
	global_load_dwordx4 v[48:51], v142, s[84:85]
	global_load_dwordx4 v[52:55], v143, s[84:85]
	ds_bpermute_b32 v142, v255, v135
	ds_bpermute_b32 v143, v153, v135
	s_waitcnt lgkmcnt(0)
	v_and_or_b32 v142, v142, s90, v240
	v_and_or_b32 v143, v143, s90, v240
	global_load_dwordx4 v[56:59], v142, s[84:85]
	global_load_dwordx4 v[60:63], v143, s[84:85]
	s_mov_b32 s92, 1
	s_lshl_b32 vcc_lo, s92, 9
	s_add_u32 vcc_lo, vcc_lo, s101
	v_add_u32_e32 v116, vcc_lo, v234
	ds_read_b32 v134, v116
	ds_read_b32 v135, v116 offset:256
.Lpg0_uloop:
	s_and_b32 s98, s100, 15
	s_lshr_b32 s99, s100, 4
	s_add_u32 s92, s100, 1
	s_min_u32 s92, s92, 127
	s_lshr_b32 s93, s92, 4
	s_and_b32 s92, s92, 15
	s_waitcnt vmcnt(16)
	v_mov_b32_e32 v64, v80
	v_mov_b32_e32 v65, v81
	v_mov_b32_e32 v66, v82
	v_mov_b32_e32 v67, v83
	v_mov_b32_e32 v68, v84
	v_mov_b32_e32 v69, v85
	v_mov_b32_e32 v70, v86
	v_mov_b32_e32 v71, v87
	s_add_u32 vcc_lo, s3, s92
	s_lshl_b32 vcc_lo, vcc_lo, 11
	s_lshl_b32 vcc_hi, s93, 8
	s_add_u32 vcc_lo, vcc_lo, vcc_hi
	v_add_u32_e32 v119, vcc_lo, v236
	global_load_dwordx4 v[80:83], v119, s[82:83]
	global_load_dwordx4 v[84:87], v119, s[82:83] offset:16
	s_lshl_b32 vcc_lo, s93, 21
	s_add_u32 s84, s80, vcc_lo
	s_addc_u32 s85, s81, 0
	v_mov_b32_e32 v240, v235
	s_waitcnt lgkmcnt(0)
	ds_bpermute_b32 v142, v249, v134
	ds_bpermute_b32 v143, v250, v134
	s_waitcnt vmcnt(16)
	v_cvt_scalef32_pk_bf16_fp8 v104, v0, 1.0
	v_cvt_scalef32_pk_bf16_fp8 v106, v4, 1.0
	v_cvt_scalef32_pk_bf16_fp8 v105, v0, 1.0 op_sel:[1,0,0]
	v_cvt_scalef32_pk_bf16_fp8 v107, v4, 1.0 op_sel:[1,0,0]
	v_cvt_scalef32_pk_bf16_fp8 v108, v1, 1.0
	v_cvt_scalef32_pk_bf16_fp8 v110, v5, 1.0
	v_cvt_scalef32_pk_bf16_fp8 v109, v1, 1.0 op_sel:[1,0,0]
	v_cvt_scalef32_pk_bf16_fp8 v111, v5, 1.0 op_sel:[1,0,0]
	v_mfma_f32_4x4x4_16b_bf16 v[72:75], v[104:105], v[64:65], 0
	v_mfma_f32_4x4x4_16b_bf16 v[76:79], v[106:107], v[64:65], 0
	v_cvt_scalef32_pk_bf16_fp8 v104, v2, 1.0
	v_cvt_scalef32_pk_bf16_fp8 v106, v6, 1.0
	v_cvt_scalef32_pk_bf16_fp8 v105, v2, 1.0 op_sel:[1,0,0]
	v_cvt_scalef32_pk_bf16_fp8 v107, v6, 1.0 op_sel:[1,0,0]
	v_mfma_f32_4x4x4_16b_bf16 v[72:75], v[108:109], v[66:67], v[72:75]
	v_mfma_f32_4x4x4_16b_bf16 v[76:79], v[110:111], v[66:67], v[76:79]
	v_cvt_scalef32_pk_bf16_fp8 v108, v3, 1.0
	v_cvt_scalef32_pk_bf16_fp8 v110, v7, 1.0
	v_cvt_scalef32_pk_bf16_fp8 v109, v3, 1.0 op_sel:[1,0,0]
	v_cvt_scalef32_pk_bf16_fp8 v111, v7, 1.0 op_sel:[1,0,0]
	v_mfma_f32_4x4x4_16b_bf16 v[72:75], v[104:105], v[68:69], v[72:75]
	v_mfma_f32_4x4x4_16b_bf16 v[76:79], v[106:107], v[68:69], v[76:79]
	s_waitcnt lgkmcnt(0)
	v_and_or_b32 v142, v142, s90, v240
	v_and_or_b32 v143, v143, s90, v240
	global_load_dwordx4 v[0:3], v142, s[84:85]
	global_load_dwordx4 v[4:7], v143, s[84:85]
	ds_bpermute_b32 v142, v251, v134
	ds_bpermute_b32 v143, v252, v134
	s_waitcnt vmcnt(16)
; #define PG_ISSUE(BUF, TAB, e0_) do { const int isrc_ = ((e0_) < 64) ? myi0 : myi1; \
;       _Pragma("unroll") for (int e = 0; e < 8; ++e) { const int idx_ = __builtin_amdgcn_readlane(isrc_, ((e0_) + e) & 63); \
;         BUF[e] = *(const u32x4*)((TAB) + (size_t)idx_ * 1024 + lane * 16); } } while (0)
; DEV void peer_gather(const Params& P, int l, int m0, const int* idxs, const float* gs) {
;     ...
;     for (int e0 = 0; e0 < 128; e0 += 16) {
;       PG_ISSUE(b1, U, e0 + 8);
;       PG_U8(b0, 0, e0);
;       if (e0 + 16 < 128) PG_ISSUE(b0, U, e0 + 16); else PG_ISSUE(b0, V, 0);
;       PG_U8(b1, 0, e0 + 8);
;     }
	v_cvt_scalef32_pk_bf16_fp8 v104, v8, 1.0
	v_cvt_scalef32_pk_bf16_fp8 v106, v12, 1.0
	v_cvt_scalef32_pk_bf16_fp8 v105, v8, 1.0 op_sel:[1,0,0]
	v_cvt_scalef32_pk_bf16_fp8 v107, v12, 1.0 op_sel:[1,0,0]
	v_mfma_f32_4x4x4_16b_bf16 v[72:75], v[108:109], v[70:71], v[72:75]
	v_mfma_f32_4x4x4_16b_bf16 v[76:79], v[110:111], v[70:71], v[76:79]
	v_cvt_scalef32_pk_bf16_fp8 v108, v9, 1.0
	v_cvt_scalef32_pk_bf16_fp8 v110, v13, 1.0
	v_cvt_scalef32_pk_bf16_fp8 v109, v9, 1.0 op_sel:[1,0,0]
	v_cvt_scalef32_pk_bf16_fp8 v111, v13, 1.0 op_sel:[1,0,0]
	v_cndmask_b32_e64 v148, v72, v73, s[88:89]
	v_cndmask_b32_e64 v149, v74, v75, s[88:89]
	v_cndmask_b32_e64 v88, v148, v149, s[86:87]
	v_cndmask_b32_e64 v150, v76, v77, s[88:89]
	v_cndmask_b32_e64 v151, v78, v79, s[88:89]
	v_cndmask_b32_e64 v89, v150, v151, s[86:87]
	v_mfma_f32_4x4x4_16b_bf16 v[72:75], v[104:105], v[64:65], 0
	v_mfma_f32_4x4x4_16b_bf16 v[76:79], v[106:107], v[64:65], 0
	v_cvt_scalef32_pk_bf16_fp8 v104, v10, 1.0
	v_cvt_scalef32_pk_bf16_fp8 v106, v14, 1.0
	v_cvt_scalef32_pk_bf16_fp8 v105, v10, 1.0 op_sel:[1,0,0]
	v_cvt_scalef32_pk_bf16_fp8 v107, v14, 1.0 op_sel:[1,0,0]
	v_mfma_f32_4x4x4_16b_bf16 v[72:75], v[108:109], v[66:67], v[72:75]
	v_mfma_f32_4x4x4_16b_bf16 v[76:79], v[110:111], v[66:67], v[76:79]
	v_cvt_scalef32_pk_bf16_fp8 v108, v11, 1.0
	v_cvt_scalef32_pk_bf16_fp8 v110, v15, 1.0
	v_cvt_scalef32_pk_bf16_fp8 v109, v11, 1.0 op_sel:[1,0,0]
	v_cvt_scalef32_pk_bf16_fp8 v111, v15, 1.0 op_sel:[1,0,0]
	v_mfma_f32_4x4x4_16b_bf16 v[72:75], v[104:105], v[68:69], v[72:75]
	v_mfma_f32_4x4x4_16b_bf16 v[76:79], v[106:107], v[68:69], v[76:79]
	s_waitcnt lgkmcnt(0)
	v_and_or_b32 v142, v142, s90, v240
	v_and_or_b32 v143, v143, s90, v240
	global_load_dwordx4 v[8:11], v142, s[84:85]
	global_load_dwordx4 v[12:15], v143, s[84:85]
	ds_bpermute_b32 v142, v253, v134
	ds_bpermute_b32 v143, v254, v134
	s_waitcnt vmcnt(16)
	v_cvt_scalef32_pk_bf16_fp8 v104, v16, 1.0
	v_cvt_scalef32_pk_bf16_fp8 v106, v20, 1.0
	v_cvt_scalef32_pk_bf16_fp8 v105, v16, 1.0 op_sel:[1,0,0]
	v_cvt_scalef32_pk_bf16_fp8 v107, v20, 1.0 op_sel:[1,0,0]
	v_mfma_f32_4x4x4_16b_bf16 v[72:75], v[108:109], v[70:71], v[72:75]
	v_mfma_f32_4x4x4_16b_bf16 v[76:79], v[110:111], v[70:71], v[76:79]
	v_cvt_scalef32_pk_bf16_fp8 v108, v17, 1.0
	v_cvt_scalef32_pk_bf16_fp8 v110, v21, 1.0
	v_cvt_scalef32_pk_bf16_fp8 v109, v17, 1.0 op_sel:[1,0,0]
	v_cvt_scalef32_pk_bf16_fp8 v111, v21, 1.0 op_sel:[1,0,0]
	v_cndmask_b32_e64 v148, v72, v73, s[88:89]
	v_cndmask_b32_e64 v149, v74, v75, s[88:89]
	v_cndmask_b32_e64 v90, v148, v149, s[86:87]
	v_cndmask_b32_e64 v150, v76, v77, s[88:89]
	v_cndmask_b32_e64 v151, v78, v79, s[88:89]
	v_cndmask_b32_e64 v91, v150, v151, s[86:87]
	v_mfma_f32_4x4x4_16b_bf16 v[72:75], v[104:105], v[64:65], 0
	v_mfma_f32_4x4x4_16b_bf16 v[76:79], v[106:107], v[64:65], 0
	v_cvt_scalef32_pk_bf16_fp8 v104, v18, 1.0
	v_cvt_scalef32_pk_bf16_fp8 v106, v22, 1.0
	v_cvt_scalef32_pk_bf16_fp8 v105, v18, 1.0 op_sel:[1,0,0]
	v_cvt_scalef32_pk_bf16_fp8 v107, v22, 1.0 op_sel:[1,0,0]
	v_mfma_f32_4x4x4_16b_bf16 v[72:75], v[108:109], v[66:67], v[72:75]
	v_mfma_f32_4x4x4_16b_bf16 v[76:79], v[110:111], v[66:67], v[76:79]
	v_cvt_scalef32_pk_bf16_fp8 v108, v19, 1.0
	v_cvt_scalef32_pk_bf16_fp8 v110, v23, 1.0
	v_cvt_scalef32_pk_bf16_fp8 v109, v19, 1.0 op_sel:[1,0,0]
	v_cvt_scalef32_pk_bf16_fp8 v111, v23, 1.0 op_sel:[1,0,0]
	v_mfma_f32_4x4x4_16b_bf16 v[72:75], v[104:105], v[68:69], v[72:75]
	v_mfma_f32_4x4x4_16b_bf16 v[76:79], v[106:107], v[68:69], v[76:79]
	s_waitcnt lgkmcnt(0)
	v_and_or_b32 v142, v142, s90, v240
	v_and_or_b32 v143, v143, s90, v240
	global_load_dwordx4 v[16:19], v142, s[84:85]
	global_load_dwordx4 v[20:23], v143, s[84:85]
	ds_bpermute_b32 v142, v255, v134
	ds_bpermute_b32 v143, v153, v134
	s_waitcnt vmcnt(16)
	v_cvt_scalef32_pk_bf16_fp8 v104, v24, 1.0
	v_cvt_scalef32_pk_bf16_fp8 v106, v28, 1.0
	v_cvt_scalef32_pk_bf16_fp8 v105, v24, 1.0 op_sel:[1,0,0]
	v_cvt_scalef32_pk_bf16_fp8 v107, v28, 1.0 op_sel:[1,0,0]
	v_mfma_f32_4x4x4_16b_bf16 v[72:75], v[108:109], v[70:71], v[72:75]
	v_mfma_f32_4x4x4_16b_bf16 v[76:79], v[110:111], v[70:71], v[76:79]
	v_cvt_scalef32_pk_bf16_fp8 v108, v25, 1.0
	v_cvt_scalef32_pk_bf16_fp8 v110, v29, 1.0
	v_cvt_scalef32_pk_bf16_fp8 v109, v25, 1.0 op_sel:[1,0,0]
	v_cvt_scalef32_pk_bf16_fp8 v111, v29, 1.0 op_sel:[1,0,0]
	v_cndmask_b32_e64 v148, v72, v73, s[88:89]
	v_cndmask_b32_e64 v149, v74, v75, s[88:89]
	v_cndmask_b32_e64 v92, v148, v149, s[86:87]
	v_cndmask_b32_e64 v150, v76, v77, s[88:89]
	v_cndmask_b32_e64 v151, v78, v79, s[88:89]
	v_cndmask_b32_e64 v93, v150, v151, s[86:87]
	v_mfma_f32_4x4x4_16b_bf16 v[72:75], v[104:105], v[64:65], 0
	v_mfma_f32_4x4x4_16b_bf16 v[76:79], v[106:107], v[64:65], 0
	v_cvt_scalef32_pk_bf16_fp8 v104, v26, 1.0
	v_cvt_scalef32_pk_bf16_fp8 v106, v30, 1.0
	v_cvt_scalef32_pk_bf16_fp8 v105, v26, 1.0 op_sel:[1,0,0]
	v_cvt_scalef32_pk_bf16_fp8 v107, v30, 1.0 op_sel:[1,0,0]
	v_mfma_f32_4x4x4_16b_bf16 v[72:75], v[108:109], v[66:67], v[72:75]
	v_mfma_f32_4x4x4_16b_bf16 v[76:79], v[110:111], v[66:67], v[76:79]
	v_cvt_scalef32_pk_bf16_fp8 v108, v27, 1.0
	v_cvt_scalef32_pk_bf16_fp8 v110, v31, 1.0
	v_cvt_scalef32_pk_bf16_fp8 v109, v27, 1.0 op_sel:[1,0,0]
	v_cvt_scalef32_pk_bf16_fp8 v111, v31, 1.0 op_sel:[1,0,0]
	v_mfma_f32_4x4x4_16b_bf16 v[72:75], v[104:105], v[68:69], v[72:75]
	v_mfma_f32_4x4x4_16b_bf16 v[76:79], v[106:107], v[68:69], v[76:79]
	s_waitcnt lgkmcnt(0)
	v_and_or_b32 v142, v142, s90, v240
	v_and_or_b32 v143, v143, s90, v240
	global_load_dwordx4 v[24:27], v142, s[84:85]
	global_load_dwordx4 v[28:31], v143, s[84:85]
	ds_bpermute_b32 v142, v249, v135
	ds_bpermute_b32 v143, v250, v135
	s_waitcnt vmcnt(16)
; #define PG_ISSUE(BUF, TAB, e0_) do { const int isrc_ = ((e0_) < 64) ? myi0 : myi1; \
;       _Pragma("unroll") for (int e = 0; e < 8; ++e) { const int idx_ = __builtin_amdgcn_readlane(isrc_, ((e0_) + e) & 63); \
;         BUF[e] = *(const u32x4*)((TAB) + (size_t)idx_ * 1024 + lane * 16); } } while (0)
; DEV void peer_gather(const Params& P, int l, int m0, const int* idxs, const float* gs) {
;     ...
;     for (int e0 = 0; e0 < 128; e0 += 16) {
;       PG_ISSUE(b1, U, e0 + 8);
;       PG_U8(b0, 0, e0);
;       if (e0 + 16 < 128) PG_ISSUE(b0, U, e0 + 16); else PG_ISSUE(b0, V, 0);
;       PG_U8(b1, 0, e0 + 8);
;     }
	v_cvt_scalef32_pk_bf16_fp8 v104, v32, 1.0
	v_cvt_scalef32_pk_bf16_fp8 v106, v36, 1.0
	v_cvt_scalef32_pk_bf16_fp8 v105, v32, 1.0 op_sel:[1,0,0]
	v_cvt_scalef32_pk_bf16_fp8 v107, v36, 1.0 op_sel:[1,0,0]
	v_mfma_f32_4x4x4_16b_bf16 v[72:75], v[108:109], v[70:71], v[72:75]
	v_mfma_f32_4x4x4_16b_bf16 v[76:79], v[110:111], v[70:71], v[76:79]
	v_cvt_scalef32_pk_bf16_fp8 v108, v33, 1.0
	v_cvt_scalef32_pk_bf16_fp8 v110, v37, 1.0
	v_cvt_scalef32_pk_bf16_fp8 v109, v33, 1.0 op_sel:[1,0,0]
	v_cvt_scalef32_pk_bf16_fp8 v111, v37, 1.0 op_sel:[1,0,0]
	v_cndmask_b32_e64 v148, v72, v73, s[88:89]
	v_cndmask_b32_e64 v149, v74, v75, s[88:89]
	v_cndmask_b32_e64 v94, v148, v149, s[86:87]
	v_cndmask_b32_e64 v150, v76, v77, s[88:89]
	v_cndmask_b32_e64 v151, v78, v79, s[88:89]
	v_cndmask_b32_e64 v95, v150, v151, s[86:87]
	v_mfma_f32_4x4x4_16b_bf16 v[72:75], v[104:105], v[64:65], 0
	v_mfma_f32_4x4x4_16b_bf16 v[76:79], v[106:107], v[64:65], 0
	v_cvt_scalef32_pk_bf16_fp8 v104, v34, 1.0
	v_cvt_scalef32_pk_bf16_fp8 v106, v38, 1.0
	v_cvt_scalef32_pk_bf16_fp8 v105, v34, 1.0 op_sel:[1,0,0]
	v_cvt_scalef32_pk_bf16_fp8 v107, v38, 1.0 op_sel:[1,0,0]
	v_mfma_f32_4x4x4_16b_bf16 v[72:75], v[108:109], v[66:67], v[72:75]
	v_mfma_f32_4x4x4_16b_bf16 v[76:79], v[110:111], v[66:67], v[76:79]
	v_cvt_scalef32_pk_bf16_fp8 v108, v35, 1.0
	v_cvt_scalef32_pk_bf16_fp8 v110, v39, 1.0
	v_cvt_scalef32_pk_bf16_fp8 v109, v35, 1.0 op_sel:[1,0,0]
	v_cvt_scalef32_pk_bf16_fp8 v111, v39, 1.0 op_sel:[1,0,0]
	v_mfma_f32_4x4x4_16b_bf16 v[72:75], v[104:105], v[68:69], v[72:75]
	v_mfma_f32_4x4x4_16b_bf16 v[76:79], v[106:107], v[68:69], v[76:79]
	s_waitcnt lgkmcnt(0)
	v_and_or_b32 v142, v142, s90, v240
	v_and_or_b32 v143, v143, s90, v240
	global_load_dwordx4 v[32:35], v142, s[84:85]
	global_load_dwordx4 v[36:39], v143, s[84:85]
	ds_bpermute_b32 v142, v251, v135
	ds_bpermute_b32 v143, v252, v135
	s_waitcnt vmcnt(16)
	v_cvt_scalef32_pk_bf16_fp8 v104, v40, 1.0
	v_cvt_scalef32_pk_bf16_fp8 v106, v44, 1.0
	v_cvt_scalef32_pk_bf16_fp8 v105, v40, 1.0 op_sel:[1,0,0]
	v_cvt_scalef32_pk_bf16_fp8 v107, v44, 1.0 op_sel:[1,0,0]
	v_mfma_f32_4x4x4_16b_bf16 v[72:75], v[108:109], v[70:71], v[72:75]
	v_mfma_f32_4x4x4_16b_bf16 v[76:79], v[110:111], v[70:71], v[76:79]
	v_cvt_scalef32_pk_bf16_fp8 v108, v41, 1.0
	v_cvt_scalef32_pk_bf16_fp8 v110, v45, 1.0
	v_cvt_scalef32_pk_bf16_fp8 v109, v41, 1.0 op_sel:[1,0,0]
	v_cvt_scalef32_pk_bf16_fp8 v111, v45, 1.0 op_sel:[1,0,0]
	v_cndmask_b32_e64 v148, v72, v73, s[88:89]
	v_cndmask_b32_e64 v149, v74, v75, s[88:89]
	v_cndmask_b32_e64 v96, v148, v149, s[86:87]
	v_cndmask_b32_e64 v150, v76, v77, s[88:89]
	v_cndmask_b32_e64 v151, v78, v79, s[88:89]
	v_cndmask_b32_e64 v97, v150, v151, s[86:87]
	v_mfma_f32_4x4x4_16b_bf16 v[72:75], v[104:105], v[64:65], 0
	v_mfma_f32_4x4x4_16b_bf16 v[76:79], v[106:107], v[64:65], 0
	v_cvt_scalef32_pk_bf16_fp8 v104, v42, 1.0
	v_cvt_scalef32_pk_bf16_fp8 v106, v46, 1.0
	v_cvt_scalef32_pk_bf16_fp8 v105, v42, 1.0 op_sel:[1,0,0]
	v_cvt_scalef32_pk_bf16_fp8 v107, v46, 1.0 op_sel:[1,0,0]
	v_mfma_f32_4x4x4_16b_bf16 v[72:75], v[108:109], v[66:67], v[72:75]
	v_mfma_f32_4x4x4_16b_bf16 v[76:79], v[110:111], v[66:67], v[76:79]
	v_cvt_scalef32_pk_bf16_fp8 v108, v43, 1.0
	v_cvt_scalef32_pk_bf16_fp8 v110, v47, 1.0
	v_cvt_scalef32_pk_bf16_fp8 v109, v43, 1.0 op_sel:[1,0,0]
	v_cvt_scalef32_pk_bf16_fp8 v111, v47, 1.0 op_sel:[1,0,0]
	v_mfma_f32_4x4x4_16b_bf16 v[72:75], v[104:105], v[68:69], v[72:75]
	v_mfma_f32_4x4x4_16b_bf16 v[76:79], v[106:107], v[68:69], v[76:79]
	s_waitcnt lgkmcnt(0)
	v_and_or_b32 v142, v142, s90, v240
	v_and_or_b32 v143, v143, s90, v240
	global_load_dwordx4 v[40:43], v142, s[84:85]
	global_load_dwordx4 v[44:47], v143, s[84:85]
	ds_bpermute_b32 v142, v253, v135
	ds_bpermute_b32 v143, v254, v135
	s_waitcnt vmcnt(16)
	v_cvt_scalef32_pk_bf16_fp8 v104, v48, 1.0
	v_cvt_scalef32_pk_bf16_fp8 v106, v52, 1.0
	v_cvt_scalef32_pk_bf16_fp8 v105, v48, 1.0 op_sel:[1,0,0]
	v_cvt_scalef32_pk_bf16_fp8 v107, v52, 1.0 op_sel:[1,0,0]
	v_mfma_f32_4x4x4_16b_bf16 v[72:75], v[108:109], v[70:71], v[72:75]
	v_mfma_f32_4x4x4_16b_bf16 v[76:79], v[110:111], v[70:71], v[76:79]
	v_cvt_scalef32_pk_bf16_fp8 v108, v49, 1.0
	v_cvt_scalef32_pk_bf16_fp8 v110, v53, 1.0
	v_cvt_scalef32_pk_bf16_fp8 v109, v49, 1.0 op_sel:[1,0,0]
	v_cvt_scalef32_pk_bf16_fp8 v111, v53, 1.0 op_sel:[1,0,0]
	v_cndmask_b32_e64 v148, v72, v73, s[88:89]
	v_cndmask_b32_e64 v149, v74, v75, s[88:89]
	v_cndmask_b32_e64 v98, v148, v149, s[86:87]
	v_cndmask_b32_e64 v150, v76, v77, s[88:89]
	v_cndmask_b32_e64 v151, v78, v79, s[88:89]
	v_cndmask_b32_e64 v99, v150, v151, s[86:87]
	v_mfma_f32_4x4x4_16b_bf16 v[72:75], v[104:105], v[64:65], 0
	v_mfma_f32_4x4x4_16b_bf16 v[76:79], v[106:107], v[64:65], 0
	v_cvt_scalef32_pk_bf16_fp8 v104, v50, 1.0
	v_cvt_scalef32_pk_bf16_fp8 v106, v54, 1.0
	v_cvt_scalef32_pk_bf16_fp8 v105, v50, 1.0 op_sel:[1,0,0]
	v_cvt_scalef32_pk_bf16_fp8 v107, v54, 1.0 op_sel:[1,0,0]
	v_mfma_f32_4x4x4_16b_bf16 v[72:75], v[108:109], v[66:67], v[72:75]
	v_mfma_f32_4x4x4_16b_bf16 v[76:79], v[110:111], v[66:67], v[76:79]
	v_cvt_scalef32_pk_bf16_fp8 v108, v51, 1.0
	v_cvt_scalef32_pk_bf16_fp8 v110, v55, 1.0
	v_cvt_scalef32_pk_bf16_fp8 v109, v51, 1.0 op_sel:[1,0,0]
	v_cvt_scalef32_pk_bf16_fp8 v111, v55, 1.0 op_sel:[1,0,0]
	v_mfma_f32_4x4x4_16b_bf16 v[72:75], v[104:105], v[68:69], v[72:75]
	v_mfma_f32_4x4x4_16b_bf16 v[76:79], v[106:107], v[68:69], v[76:79]
	s_waitcnt lgkmcnt(0)
	v_and_or_b32 v142, v142, s90, v240
	v_and_or_b32 v143, v143, s90, v240
	global_load_dwordx4 v[48:51], v142, s[84:85]
	global_load_dwordx4 v[52:55], v143, s[84:85]
	ds_bpermute_b32 v142, v255, v135
	ds_bpermute_b32 v143, v153, v135
	s_waitcnt vmcnt(16)
; #define PG_ISSUE(BUF, TAB, e0_) do { const int isrc_ = ((e0_) < 64) ? myi0 : myi1; \
;       _Pragma("unroll") for (int e = 0; e < 8; ++e) { const int idx_ = __builtin_amdgcn_readlane(isrc_, ((e0_) + e) & 63); \
;         BUF[e] = *(const u32x4*)((TAB) + (size_t)idx_ * 1024 + lane * 16); } } while (0)
; DEV void peer_gather(const Params& P, int l, int m0, const int* idxs, const float* gs) {
;     ...
;     for (int e0 = 0; e0 < 128; e0 += 16) {
;       PG_ISSUE(b1, U, e0 + 8);
;       PG_U8(b0, 0, e0);
;       if (e0 + 16 < 128) PG_ISSUE(b0, U, e0 + 16); else PG_ISSUE(b0, V, 0);
;       PG_U8(b1, 0, e0 + 8);
;     }
	v_cvt_scalef32_pk_bf16_fp8 v104, v56, 1.0
	v_cvt_scalef32_pk_bf16_fp8 v106, v60, 1.0
	v_cvt_scalef32_pk_bf16_fp8 v105, v56, 1.0 op_sel:[1,0,0]
	v_cvt_scalef32_pk_bf16_fp8 v107, v60, 1.0 op_sel:[1,0,0]
	v_mfma_f32_4x4x4_16b_bf16 v[72:75], v[108:109], v[70:71], v[72:75]
	v_mfma_f32_4x4x4_16b_bf16 v[76:79], v[110:111], v[70:71], v[76:79]
	v_cvt_scalef32_pk_bf16_fp8 v108, v57, 1.0
	v_cvt_scalef32_pk_bf16_fp8 v110, v61, 1.0
	v_cvt_scalef32_pk_bf16_fp8 v109, v57, 1.0 op_sel:[1,0,0]
	v_cvt_scalef32_pk_bf16_fp8 v111, v61, 1.0 op_sel:[1,0,0]
	v_cndmask_b32_e64 v148, v72, v73, s[88:89]
	v_cndmask_b32_e64 v149, v74, v75, s[88:89]
	v_cndmask_b32_e64 v100, v148, v149, s[86:87]
	v_cndmask_b32_e64 v150, v76, v77, s[88:89]
	v_cndmask_b32_e64 v151, v78, v79, s[88:89]
	v_cndmask_b32_e64 v101, v150, v151, s[86:87]
	v_mfma_f32_4x4x4_16b_bf16 v[72:75], v[104:105], v[64:65], 0
	v_mfma_f32_4x4x4_16b_bf16 v[76:79], v[106:107], v[64:65], 0
	v_cvt_scalef32_pk_bf16_fp8 v104, v58, 1.0
	v_cvt_scalef32_pk_bf16_fp8 v106, v62, 1.0
	v_cvt_scalef32_pk_bf16_fp8 v105, v58, 1.0 op_sel:[1,0,0]
	v_cvt_scalef32_pk_bf16_fp8 v107, v62, 1.0 op_sel:[1,0,0]
	v_mfma_f32_4x4x4_16b_bf16 v[72:75], v[108:109], v[66:67], v[72:75]
	v_mfma_f32_4x4x4_16b_bf16 v[76:79], v[110:111], v[66:67], v[76:79]
	v_cvt_scalef32_pk_bf16_fp8 v108, v59, 1.0
	v_cvt_scalef32_pk_bf16_fp8 v110, v63, 1.0
	v_cvt_scalef32_pk_bf16_fp8 v109, v59, 1.0 op_sel:[1,0,0]
	v_cvt_scalef32_pk_bf16_fp8 v111, v63, 1.0 op_sel:[1,0,0]
	v_mfma_f32_4x4x4_16b_bf16 v[72:75], v[104:105], v[68:69], v[72:75]
	v_mfma_f32_4x4x4_16b_bf16 v[76:79], v[106:107], v[68:69], v[76:79]
	s_waitcnt lgkmcnt(0)
	v_and_or_b32 v142, v142, s90, v240
	v_and_or_b32 v143, v143, s90, v240
	global_load_dwordx4 v[56:59], v142, s[84:85]
	global_load_dwordx4 v[60:63], v143, s[84:85]
	v_mfma_f32_4x4x4_16b_bf16 v[72:75], v[108:109], v[70:71], v[72:75]
	v_mfma_f32_4x4x4_16b_bf16 v[76:79], v[110:111], v[70:71], v[76:79]
	s_add_u32 s92, s100, 2
	s_min_u32 s92, s92, 127
	s_and_b32 s92, s92, 15
	s_lshl_b32 vcc_lo, s92, 9
	s_add_u32 vcc_lo, vcc_lo, s101
	v_add_u32_e32 v116, vcc_lo, v234
	ds_read_b32 v134, v116
	ds_read_b32 v135, v116 offset:256
	s_lshl_b32 vcc_lo, s98, 9
	s_add_u32 vcc_lo, vcc_lo, s101
	s_add_u32 vcc_lo, vcc_lo, 0x10000
	v_add_u32_e32 v117, vcc_lo, v234
	ds_read_b32 v136, v117
	ds_read_b32 v137, v117 offset:256
	v_cndmask_b32_e64 v148, v72, v73, s[88:89]
	v_cndmask_b32_e64 v149, v74, v75, s[88:89]
	v_cndmask_b32_e64 v102, v148, v149, s[86:87]
	v_cndmask_b32_e64 v150, v76, v77, s[88:89]
	v_cndmask_b32_e64 v151, v78, v79, s[88:89]
	v_cndmask_b32_e64 v103, v150, v151, s[86:87]
	s_mov_b32 s88, 0xf0f0f0f0
	s_mov_b32 s89, 0xf0f0f0f0
	v_cndmask_b32_e64 v144, v88, v92, s[88:89]
	v_cndmask_b32_e64 v92, v92, v88, s[88:89]
	v_cndmask_b32_e64 v145, v89, v93, s[88:89]
	v_cndmask_b32_e64 v93, v93, v89, s[88:89]
	v_cndmask_b32_e64 v146, v90, v94, s[88:89]
	v_cndmask_b32_e64 v94, v94, v90, s[88:89]
	v_cndmask_b32_e64 v147, v91, v95, s[88:89]
	v_cndmask_b32_e64 v95, v95, v91, s[88:89]
	v_add_f32_dpp v88, v92, v144 row_half_mirror row_mask:0xf bank_mask:0xf
	v_add_f32_dpp v89, v93, v145 row_half_mirror row_mask:0xf bank_mask:0xf
	v_add_f32_dpp v90, v94, v146 row_half_mirror row_mask:0xf bank_mask:0xf
	v_add_f32_dpp v91, v95, v147 row_half_mirror row_mask:0xf bank_mask:0xf
	v_cndmask_b32_e64 v144, v96, v100, s[88:89]
	v_cndmask_b32_e64 v100, v100, v96, s[88:89]
	v_cndmask_b32_e64 v145, v97, v101, s[88:89]
	v_cndmask_b32_e64 v101, v101, v97, s[88:89]
	v_cndmask_b32_e64 v146, v98, v102, s[88:89]
	v_cndmask_b32_e64 v102, v102, v98, s[88:89]
	v_cndmask_b32_e64 v147, v99, v103, s[88:89]
	v_cndmask_b32_e64 v103, v103, v99, s[88:89]
	v_add_f32_dpp v96, v100, v144 row_half_mirror row_mask:0xf bank_mask:0xf
	v_add_f32_dpp v97, v101, v145 row_half_mirror row_mask:0xf bank_mask:0xf
	v_add_f32_dpp v98, v102, v146 row_half_mirror row_mask:0xf bank_mask:0xf
	v_add_f32_dpp v99, v103, v147 row_half_mirror row_mask:0xf bank_mask:0xf
	s_mov_b32 s88, 0xcccccccc
	s_mov_b32 s89, 0xcccccccc
	v_cndmask_b32_e64 v144, v88, v90, s[88:89]
	v_cndmask_b32_e64 v90, v90, v88, s[88:89]
	v_cndmask_b32_e64 v145, v89, v91, s[88:89]
	v_cndmask_b32_e64 v91, v91, v89, s[88:89]
	v_cndmask_b32_e64 v146, v96, v98, s[88:89]
	v_cndmask_b32_e64 v98, v98, v96, s[88:89]
	v_cndmask_b32_e64 v147, v97, v99, s[88:89]
	v_cndmask_b32_e64 v99, v99, v97, s[88:89]
	v_add_f32_dpp v88, v90, v144 quad_perm:[2,3,0,1] row_mask:0xf bank_mask:0xf
	v_add_f32_dpp v89, v91, v145 quad_perm:[2,3,0,1] row_mask:0xf bank_mask:0xf
	v_add_f32_dpp v96, v98, v146 quad_perm:[2,3,0,1] row_mask:0xf bank_mask:0xf
	v_add_f32_dpp v97, v99, v147 quad_perm:[2,3,0,1] row_mask:0xf bank_mask:0xf
	s_mov_b32 s88, 0xaaaaaaaa
	s_mov_b32 s89, 0xaaaaaaaa
	v_cndmask_b32_e64 v144, v88, v89, s[88:89]
	v_cndmask_b32_e64 v89, v89, v88, s[88:89]
	v_cndmask_b32_e64 v145, v96, v97, s[88:89]
	v_cndmask_b32_e64 v97, v97, v96, s[88:89]
	s_nop 1
	v_add_f32_dpp v88, v89, v144 quad_perm:[1,0,3,2] row_mask:0xf bank_mask:0xf
	v_add_f32_dpp v96, v97, v145 quad_perm:[1,0,3,2] row_mask:0xf bank_mask:0xf
	s_nop 0
	ds_bpermute_b32 v144, v239, v88
	ds_bpermute_b32 v145, v239, v96
	s_waitcnt lgkmcnt(0)
	v_add_f32_e32 v136, v136, v144
	v_add_f32_e32 v137, v137, v145
	ds_write_b32 v117, v136
	ds_write_b32 v117, v137 offset:256
	s_add_u32 s100, s100, 1
	s_cmp_lt_u32 s100, 128
	s_cbranch_scc1 .Lpg0_uloop
	s_waitcnt vmcnt(0) lgkmcnt(0)
	s_mov_b32 s2, 0
.Lpg0_act:
	v_readlane_b32 s82, v231, 28
	v_readlane_b32 s83, v231, 29
	s_nop 4
	s_lshl_b32 s98, s2, 11
	s_add_u32 s98, s98, s101
	v_add_u32_e32 v116, s98, v234
	v_add_u32_e32 v117, 0x10000, v116
	ds_read_b32 v0, v116 offset:0
	ds_read_b32 v8, v117 offset:0
	ds_read_b32 v1, v116 offset:256
	ds_read_b32 v9, v117 offset:256
	ds_read_b32 v2, v116 offset:512
	ds_read_b32 v10, v117 offset:512
	ds_read_b32 v3, v116 offset:768
	ds_read_b32 v11, v117 offset:768
	ds_read_b32 v4, v116 offset:1024
	ds_read_b32 v12, v117 offset:1024
	ds_read_b32 v5, v116 offset:1280
	ds_read_b32 v13, v117 offset:1280
	ds_read_b32 v6, v116 offset:1536
	ds_read_b32 v14, v117 offset:1536
	ds_read_b32 v7, v116 offset:1792
	ds_read_b32 v15, v117 offset:1792
	s_waitcnt lgkmcnt(0)
	s_lshl_b32 s99, s2, 2
	s_add_u32 s99, s99, s33
	s_add_u32 s99, s99, 0
	s_lshl_b32 s99, s99, 9
	v_and_b32_e32 v0, 0x7f, v0
	v_lshl_add_u32 v0, v0, 2, s99
	global_load_dword v16, v0, s[82:83]
	v_and_b32_e32 v1, 0x7f, v1
	v_lshl_add_u32 v1, v1, 2, s99
	global_load_dword v17, v1, s[82:83]
	s_lshl_b32 s99, s2, 2
	s_add_u32 s99, s99, s33
	s_add_u32 s99, s99, 1
	s_lshl_b32 s99, s99, 9
	v_and_b32_e32 v2, 0x7f, v2
	v_lshl_add_u32 v2, v2, 2, s99
	global_load_dword v18, v2, s[82:83]
	v_and_b32_e32 v3, 0x7f, v3
	v_lshl_add_u32 v3, v3, 2, s99
	global_load_dword v19, v3, s[82:83]
	s_lshl_b32 s99, s2, 2
	s_add_u32 s99, s99, s33
	s_add_u32 s99, s99, 2
	s_lshl_b32 s99, s99, 9
	v_and_b32_e32 v4, 0x7f, v4
	v_lshl_add_u32 v4, v4, 2, s99
	global_load_dword v20, v4, s[82:83]
	v_and_b32_e32 v5, 0x7f, v5
	v_lshl_add_u32 v5, v5, 2, s99
	global_load_dword v21, v5, s[82:83]
	s_lshl_b32 s99, s2, 2
	s_add_u32 s99, s99, s33
	s_add_u32 s99, s99, 3
	s_lshl_b32 s99, s99, 9
	v_and_b32_e32 v6, 0x7f, v6
	v_lshl_add_u32 v6, v6, 2, s99
	global_load_dword v22, v6, s[82:83]
	v_and_b32_e32 v7, 0x7f, v7
	v_lshl_add_u32 v7, v7, 2, s99
	global_load_dword v23, v7, s[82:83]
	v_mul_f32_e32 v8, 0x3c800000, v8
	v_mul_f32_e32 v9, 0x3c800000, v9
	v_mul_f32_e32 v10, 0x3c800000, v10
	v_mul_f32_e32 v11, 0x3c800000, v11
	v_mul_f32_e32 v12, 0x3c800000, v12
	v_mul_f32_e32 v13, 0x3c800000, v13
	v_mul_f32_e32 v14, 0x3c800000, v14
	v_mul_f32_e32 v15, 0x3c800000, v15
	v_mul_f32_e32 v24, 0x3d372713, v8
	v_mul_f32_e32 v25, 0x3d372713, v9
	v_mul_f32_e32 v26, 0x3d372713, v10
	v_mul_f32_e32 v27, 0x3d372713, v11
	v_mul_f32_e32 v28, 0x3d372713, v12
	v_mul_f32_e32 v29, 0x3d372713, v13
	v_mul_f32_e32 v30, 0x3d372713, v14
	v_mul_f32_e32 v31, 0x3d372713, v15
	v_mul_f32_e32 v24, v8, v24
	v_mul_f32_e32 v25, v9, v25
	v_mul_f32_e32 v26, v10, v26
	v_mul_f32_e32 v27, v11, v27
	v_mul_f32_e32 v28, v12, v28
	v_mul_f32_e32 v29, v13, v29
	v_mul_f32_e32 v30, v14, v30
	v_mul_f32_e32 v31, v15, v31
	v_fma_f32 v24, v8, v24, v8
	v_fma_f32 v25, v9, v25, v9
	v_fma_f32 v26, v10, v26, v10
	v_fma_f32 v27, v11, v27, v11
	v_fma_f32 v28, v12, v28, v12
	v_fma_f32 v29, v13, v29, v13
	v_fma_f32 v30, v14, v30, v14
	v_fma_f32 v31, v15, v31, v15
	v_mul_f32_e32 v24, 0xbfcc422a, v24
	v_mul_f32_e32 v25, 0xbfcc422a, v25
	v_mul_f32_e32 v26, 0xbfcc422a, v26
	v_mul_f32_e32 v27, 0xbfcc422a, v27
	v_mul_f32_e32 v28, 0xbfcc422a, v28
	v_mul_f32_e32 v29, 0xbfcc422a, v29
	v_mul_f32_e32 v30, 0xbfcc422a, v30
	v_mul_f32_e32 v31, 0xbfcc422a, v31
	v_mul_f32_e32 v24, 0x3fb8aa3b, v24
	v_mul_f32_e32 v25, 0x3fb8aa3b, v25
	v_mul_f32_e32 v26, 0x3fb8aa3b, v26
	v_mul_f32_e32 v27, 0x3fb8aa3b, v27
	v_mul_f32_e32 v28, 0x3fb8aa3b, v28
	v_mul_f32_e32 v29, 0x3fb8aa3b, v29
	v_mul_f32_e32 v30, 0x3fb8aa3b, v30
	v_mul_f32_e32 v31, 0x3fb8aa3b, v31
	v_exp_f32_e32 v24, v24
	v_exp_f32_e32 v25, v25
	v_exp_f32_e32 v26, v26
	v_exp_f32_e32 v27, v27
	v_exp_f32_e32 v28, v28
	v_exp_f32_e32 v29, v29
	v_exp_f32_e32 v30, v30
	v_exp_f32_e32 v31, v31
	s_nop 0
	v_add_f32_e32 v24, 1.0, v24
	v_add_f32_e32 v25, 1.0, v25
	v_add_f32_e32 v26, 1.0, v26
	v_add_f32_e32 v27, 1.0, v27
	v_add_f32_e32 v28, 1.0, v28
	v_add_f32_e32 v29, 1.0, v29
	v_add_f32_e32 v30, 1.0, v30
	v_add_f32_e32 v31, 1.0, v31
	v_rcp_f32_e32 v24, v24
	v_rcp_f32_e32 v25, v25
	v_rcp_f32_e32 v26, v26
	v_rcp_f32_e32 v27, v27
	v_rcp_f32_e32 v28, v28
	v_rcp_f32_e32 v29, v29
	v_rcp_f32_e32 v30, v30
	v_rcp_f32_e32 v31, v31
	s_nop 0
	v_mul_f32_e32 v24, v8, v24
	v_mul_f32_e32 v25, v9, v25
	v_mul_f32_e32 v26, v10, v26
	v_mul_f32_e32 v27, v11, v27
	v_mul_f32_e32 v28, v12, v28
	v_mul_f32_e32 v29, v13, v29
	v_mul_f32_e32 v30, v14, v30
	v_mul_f32_e32 v31, v15, v31
	s_waitcnt vmcnt(0)
	v_mul_f32_e32 v24, v24, v16
	ds_write_b32 v117, v24 offset:0
	v_mul_f32_e32 v25, v25, v17
	ds_write_b32 v117, v25 offset:256
	v_mul_f32_e32 v26, v26, v18
	ds_write_b32 v117, v26 offset:512
	v_mul_f32_e32 v27, v27, v19
	ds_write_b32 v117, v27 offset:768
	v_mul_f32_e32 v28, v28, v20
	ds_write_b32 v117, v28 offset:1024
	v_mul_f32_e32 v29, v29, v21
	ds_write_b32 v117, v29 offset:1280
	v_mul_f32_e32 v30, v30, v22
	ds_write_b32 v117, v30 offset:1536
	v_mul_f32_e32 v31, v31, v23
	ds_write_b32 v117, v31 offset:1792
	s_add_u32 s2, s2, 1
	s_cmp_lt_u32 s2, 4
	s_cbranch_scc1 .Lpg0_act
; #define PG_ISSUE(BUF, TAB, e0_) do { const int isrc_ = ((e0_) < 64) ? myi0 : myi1; \
;       _Pragma("unroll") for (int e = 0; e < 8; ++e) { const int idx_ = __builtin_amdgcn_readlane(isrc_, ((e0_) + e) & 63); \
;         BUF[e] = *(const u32x4*)((TAB) + (size_t)idx_ * 1024 + lane * 16); } } while (0)
; DEV void peer_gather(const Params& P, int l, int m0, const int* idxs, const float* gs) {
;     ...
;     float* hrow = P.out + tok * DM + lane * 16;
;     f32x4 hv[4];
; #pragma unroll
;     for (int q = 0; q < 4; ++q) hv[q] = *(const f32x4*)(hrow + 4 * q);
;     ...
; #pragma nounroll
;     for (int e0 = 0; e0 < 128; e0 += 16) {
;       PG_ISSUE(b1, V, e0 + 8);
;       if (e0 == 64 && i + 1 < 16) sort_lists(lane, ni0, ni1, ng0, ng1);
;       PG_V16(b0, e0);
;       if (e0 + 16 < 128) PG_ISSUE(b0, V, e0 + 16);
;       PG_V16(b1, e0 + 8);
;     }
	s_waitcnt lgkmcnt(0)
	v_add_u32_e32 v249, 0, v237
	v_add_u32_e32 v250, 32, v237
	v_add_u32_e32 v251, 64, v237
	v_add_u32_e32 v252, 96, v237
	v_add_u32_e32 v253, 128, v237
	v_add_u32_e32 v254, 160, v237
	v_add_u32_e32 v255, 192, v237
	v_add_u32_e32 v153, 224, v237
	v_readfirstlane_b32 s80, v126
	v_readfirstlane_b32 s81, v127
	s_nop 4
	v_readfirstlane_b32 s82, v132
	v_readfirstlane_b32 s83, v133
	s_nop 4
	s_mov_b32 s90, 0xffffff80
	s_mov_b32 s100, 0
	s_mov_b32 s98, 0
	s_mov_b32 s99, 0
	s_lshl_b32 vcc_lo, s98, 9
	s_add_u32 vcc_lo, vcc_lo, s101
	v_add_u32_e32 v116, vcc_lo, v234
	ds_read_b32 v134, v116
	ds_read_b32 v135, v116 offset:256
	s_lshl_b32 vcc_lo, s99, 21
	s_add_u32 s84, s80, vcc_lo
	s_addc_u32 s85, s81, 0
	v_mov_b32_e32 v240, v235
	s_waitcnt lgkmcnt(0)
	ds_bpermute_b32 v142, v249, v134
	ds_bpermute_b32 v143, v250, v134
	s_waitcnt lgkmcnt(0)
	v_and_or_b32 v142, v142, s90, v240
	v_and_or_b32 v143, v143, s90, v240
	global_load_dwordx4 v[0:3], v142, s[84:85]
	global_load_dwordx4 v[4:7], v143, s[84:85]
	ds_bpermute_b32 v142, v251, v134
	ds_bpermute_b32 v143, v252, v134
	s_waitcnt lgkmcnt(0)
	v_and_or_b32 v142, v142, s90, v240
	v_and_or_b32 v143, v143, s90, v240
	global_load_dwordx4 v[8:11], v142, s[84:85]
	global_load_dwordx4 v[12:15], v143, s[84:85]
	ds_bpermute_b32 v142, v253, v134
	ds_bpermute_b32 v143, v254, v134
	s_waitcnt lgkmcnt(0)
	v_and_or_b32 v142, v142, s90, v240
	v_and_or_b32 v143, v143, s90, v240
	global_load_dwordx4 v[16:19], v142, s[84:85]
	global_load_dwordx4 v[20:23], v143, s[84:85]
	ds_bpermute_b32 v142, v255, v134
	ds_bpermute_b32 v143, v153, v134
	s_waitcnt lgkmcnt(0)
	v_and_or_b32 v142, v142, s90, v240
	v_and_or_b32 v143, v143, s90, v240
	global_load_dwordx4 v[24:27], v142, s[84:85]
	global_load_dwordx4 v[28:31], v143, s[84:85]
	ds_bpermute_b32 v142, v249, v135
	ds_bpermute_b32 v143, v250, v135
	s_waitcnt lgkmcnt(0)
	v_and_or_b32 v142, v142, s90, v240
	v_and_or_b32 v143, v143, s90, v240
	global_load_dwordx4 v[32:35], v142, s[84:85]
	global_load_dwordx4 v[36:39], v143, s[84:85]
	ds_bpermute_b32 v142, v251, v135
	ds_bpermute_b32 v143, v252, v135
	s_waitcnt lgkmcnt(0)
	v_and_or_b32 v142, v142, s90, v240
	v_and_or_b32 v143, v143, s90, v240
	global_load_dwordx4 v[40:43], v142, s[84:85]
	global_load_dwordx4 v[44:47], v143, s[84:85]
	ds_bpermute_b32 v142, v253, v135
	ds_bpermute_b32 v143, v254, v135
	s_waitcnt lgkmcnt(0)
	v_and_or_b32 v142, v142, s90, v240
	v_and_or_b32 v143, v143, s90, v240
	global_load_dwordx4 v[48:51], v142, s[84:85]
	global_load_dwordx4 v[52:55], v143, s[84:85]
	ds_bpermute_b32 v142, v255, v135
	ds_bpermute_b32 v143, v153, v135
	s_waitcnt lgkmcnt(0)
	v_and_or_b32 v142, v142, s90, v240
	v_and_or_b32 v143, v143, s90, v240
	global_load_dwordx4 v[56:59], v142, s[84:85]
	global_load_dwordx4 v[60:63], v143, s[84:85]
	s_mov_b32 s92, 1
	s_lshl_b32 vcc_lo, s92, 9
	s_add_u32 vcc_lo, vcc_lo, s101
	v_add_u32_e32 v116, vcc_lo, v234
	ds_read_b32 v134, v116
	ds_read_b32 v135, v116 offset:256
	s_lshl_b32 vcc_lo, s98, 9
	s_add_u32 vcc_lo, vcc_lo, s101
	s_add_u32 vcc_lo, vcc_lo, 0x10000
	v_add_u32_e32 v117, vcc_lo, v234
	ds_read_b32 v136, v117
	ds_read_b32 v137, v117 offset:256
	s_waitcnt vmcnt(0)
.Lpg0_vloop:
	s_and_b32 s98, s100, 15
	s_lshr_b32 s99, s100, 4
	s_add_u32 s92, s100, 1
	s_min_u32 s92, s92, 127
	s_lshr_b32 s93, s92, 4
	s_and_b32 s92, s92, 15
	s_add_u32 vcc_lo, s3, s98
	s_lshl_b32 vcc_lo, vcc_lo, 12
	s_lshl_b32 vcc_hi, s99, 9
	s_add_u32 vcc_lo, vcc_lo, vcc_hi
	v_add_u32_e32 v119, vcc_lo, v238
	global_load_dword v80, v119, s[82:83]
	global_load_dword v81, v119, s[82:83] offset:32
	s_lshl_b32 vcc_lo, s93, 21
	s_add_u32 s84, s80, vcc_lo
	s_addc_u32 s85, s81, 0
	v_mov_b32_e32 v240, v235
	s_waitcnt lgkmcnt(0)
	ds_bpermute_b32 v138, v249, v136
	ds_bpermute_b32 v140, v250, v136
	ds_bpermute_b32 v142, v249, v134
	ds_bpermute_b32 v143, v250, v134
	ds_bpermute_b32 v144, v251, v136
	ds_bpermute_b32 v146, v252, v136
	s_waitcnt vmcnt(18) lgkmcnt(4)
	v_cvt_pk_f32_fp8_e32 v[104:105], v0
	v_cvt_pk_f32_fp8_e32 v[108:109], v4
	v_cvt_pk_f32_fp8_sdwa v[106:107], v0 src0_sel:WORD_1
	v_cvt_pk_f32_fp8_sdwa v[110:111], v4 src0_sel:WORD_1
	v_pk_mul_f32 v[64:65], v[104:105], v[138:139] op_sel_hi:[1,0]
	v_pk_mul_f32 v[66:67], v[106:107], v[138:139] op_sel_hi:[1,0]
	v_pk_fma_f32 v[64:65], v[108:109], v[140:141], v[64:65] op_sel_hi:[1,0,1]
	v_pk_fma_f32 v[66:67], v[110:111], v[140:141], v[66:67] op_sel_hi:[1,0,1]
	v_cvt_pk_f32_fp8_e32 v[104:105], v1
	v_cvt_pk_f32_fp8_e32 v[108:109], v5
	v_cvt_pk_f32_fp8_sdwa v[106:107], v1 src0_sel:WORD_1
	v_cvt_pk_f32_fp8_sdwa v[110:111], v5 src0_sel:WORD_1
	v_pk_mul_f32 v[68:69], v[104:105], v[138:139] op_sel_hi:[1,0]
	v_pk_mul_f32 v[70:71], v[106:107], v[138:139] op_sel_hi:[1,0]
	v_pk_fma_f32 v[68:69], v[108:109], v[140:141], v[68:69] op_sel_hi:[1,0,1]
	v_pk_fma_f32 v[70:71], v[110:111], v[140:141], v[70:71] op_sel_hi:[1,0,1]
	v_cvt_pk_f32_fp8_e32 v[104:105], v2
	v_cvt_pk_f32_fp8_e32 v[108:109], v6
	v_cvt_pk_f32_fp8_sdwa v[106:107], v2 src0_sel:WORD_1
	v_cvt_pk_f32_fp8_sdwa v[110:111], v6 src0_sel:WORD_1
	v_pk_mul_f32 v[72:73], v[104:105], v[138:139] op_sel_hi:[1,0]
	v_pk_mul_f32 v[74:75], v[106:107], v[138:139] op_sel_hi:[1,0]
	v_pk_fma_f32 v[72:73], v[108:109], v[140:141], v[72:73] op_sel_hi:[1,0,1]
	v_pk_fma_f32 v[74:75], v[110:111], v[140:141], v[74:75] op_sel_hi:[1,0,1]
	v_cvt_pk_f32_fp8_e32 v[104:105], v3
	v_cvt_pk_f32_fp8_e32 v[108:109], v7
	v_cvt_pk_f32_fp8_sdwa v[106:107], v3 src0_sel:WORD_1
	v_cvt_pk_f32_fp8_sdwa v[110:111], v7 src0_sel:WORD_1
	v_pk_mul_f32 v[76:77], v[104:105], v[138:139] op_sel_hi:[1,0]
	v_pk_mul_f32 v[78:79], v[106:107], v[138:139] op_sel_hi:[1,0]
	s_waitcnt lgkmcnt(0)
; #define PG_ISSUE(BUF, TAB, e0_) do { const int isrc_ = ((e0_) < 64) ? myi0 : myi1; \
;       _Pragma("unroll") for (int e = 0; e < 8; ++e) { const int idx_ = __builtin_amdgcn_readlane(isrc_, ((e0_) + e) & 63); \
;         BUF[e] = *(const u32x4*)((TAB) + (size_t)idx_ * 1024 + lane * 16); } } while (0)
; DEV void peer_gather(const Params& P, int l, int m0, const int* idxs, const float* gs) {
;     ...
; #pragma nounroll
;     for (int e0 = 0; e0 < 128; e0 += 16) {
;       PG_ISSUE(b1, V, e0 + 8);
;       if (e0 == 64 && i + 1 < 16) sort_lists(lane, ni0, ni1, ng0, ng1);
;       PG_V16(b0, e0);
;       if (e0 + 16 < 128) PG_ISSUE(b0, V, e0 + 16);
;       PG_V16(b1, e0 + 8);
;     }
	v_and_or_b32 v142, v142, s90, v240
	v_and_or_b32 v143, v143, s90, v240
	global_load_dwordx4 v[0:3], v142, s[84:85]
	global_load_dwordx4 v[4:7], v143, s[84:85]
	v_pk_fma_f32 v[76:77], v[108:109], v[140:141], v[76:77] op_sel_hi:[1,0,1]
	v_pk_fma_f32 v[78:79], v[110:111], v[140:141], v[78:79] op_sel_hi:[1,0,1]
	ds_bpermute_b32 v142, v251, v134
	ds_bpermute_b32 v143, v252, v134
	ds_bpermute_b32 v138, v253, v136
	ds_bpermute_b32 v140, v254, v136
	s_waitcnt vmcnt(18) lgkmcnt(4)
	v_cvt_pk_f32_fp8_e32 v[104:105], v8
	v_cvt_pk_f32_fp8_e32 v[108:109], v12
	v_cvt_pk_f32_fp8_sdwa v[106:107], v8 src0_sel:WORD_1
	v_cvt_pk_f32_fp8_sdwa v[110:111], v12 src0_sel:WORD_1
	v_pk_fma_f32 v[64:65], v[104:105], v[144:145], v[64:65] op_sel_hi:[1,0,1]
	v_pk_fma_f32 v[66:67], v[106:107], v[144:145], v[66:67] op_sel_hi:[1,0,1]
	v_pk_fma_f32 v[64:65], v[108:109], v[146:147], v[64:65] op_sel_hi:[1,0,1]
	v_pk_fma_f32 v[66:67], v[110:111], v[146:147], v[66:67] op_sel_hi:[1,0,1]
	v_cvt_pk_f32_fp8_e32 v[104:105], v9
	v_cvt_pk_f32_fp8_e32 v[108:109], v13
	v_cvt_pk_f32_fp8_sdwa v[106:107], v9 src0_sel:WORD_1
	v_cvt_pk_f32_fp8_sdwa v[110:111], v13 src0_sel:WORD_1
	v_pk_fma_f32 v[68:69], v[104:105], v[144:145], v[68:69] op_sel_hi:[1,0,1]
	v_pk_fma_f32 v[70:71], v[106:107], v[144:145], v[70:71] op_sel_hi:[1,0,1]
	v_pk_fma_f32 v[68:69], v[108:109], v[146:147], v[68:69] op_sel_hi:[1,0,1]
	v_pk_fma_f32 v[70:71], v[110:111], v[146:147], v[70:71] op_sel_hi:[1,0,1]
	v_cvt_pk_f32_fp8_e32 v[104:105], v10
	v_cvt_pk_f32_fp8_e32 v[108:109], v14
	v_cvt_pk_f32_fp8_sdwa v[106:107], v10 src0_sel:WORD_1
	v_cvt_pk_f32_fp8_sdwa v[110:111], v14 src0_sel:WORD_1
	v_pk_fma_f32 v[72:73], v[104:105], v[144:145], v[72:73] op_sel_hi:[1,0,1]
	v_pk_fma_f32 v[74:75], v[106:107], v[144:145], v[74:75] op_sel_hi:[1,0,1]
	v_pk_fma_f32 v[72:73], v[108:109], v[146:147], v[72:73] op_sel_hi:[1,0,1]
	v_pk_fma_f32 v[74:75], v[110:111], v[146:147], v[74:75] op_sel_hi:[1,0,1]
	v_cvt_pk_f32_fp8_e32 v[104:105], v11
	v_cvt_pk_f32_fp8_e32 v[108:109], v15
	v_cvt_pk_f32_fp8_sdwa v[106:107], v11 src0_sel:WORD_1
	v_cvt_pk_f32_fp8_sdwa v[110:111], v15 src0_sel:WORD_1
	v_pk_fma_f32 v[76:77], v[104:105], v[144:145], v[76:77] op_sel_hi:[1,0,1]
	v_pk_fma_f32 v[78:79], v[106:107], v[144:145], v[78:79] op_sel_hi:[1,0,1]
	s_waitcnt lgkmcnt(0)
	v_and_or_b32 v142, v142, s90, v240
	v_and_or_b32 v143, v143, s90, v240
	global_load_dwordx4 v[8:11], v142, s[84:85]
	global_load_dwordx4 v[12:15], v143, s[84:85]
	v_pk_fma_f32 v[76:77], v[108:109], v[146:147], v[76:77] op_sel_hi:[1,0,1]
	v_pk_fma_f32 v[78:79], v[110:111], v[146:147], v[78:79] op_sel_hi:[1,0,1]
	ds_bpermute_b32 v142, v253, v134
	ds_bpermute_b32 v143, v254, v134
	ds_bpermute_b32 v144, v255, v136
	ds_bpermute_b32 v146, v153, v136
	s_waitcnt vmcnt(18) lgkmcnt(4)
	v_cvt_pk_f32_fp8_e32 v[104:105], v16
	v_cvt_pk_f32_fp8_e32 v[108:109], v20
	v_cvt_pk_f32_fp8_sdwa v[106:107], v16 src0_sel:WORD_1
	v_cvt_pk_f32_fp8_sdwa v[110:111], v20 src0_sel:WORD_1
	v_pk_fma_f32 v[64:65], v[104:105], v[138:139], v[64:65] op_sel_hi:[1,0,1]
	v_pk_fma_f32 v[66:67], v[106:107], v[138:139], v[66:67] op_sel_hi:[1,0,1]
	v_pk_fma_f32 v[64:65], v[108:109], v[140:141], v[64:65] op_sel_hi:[1,0,1]
	v_pk_fma_f32 v[66:67], v[110:111], v[140:141], v[66:67] op_sel_hi:[1,0,1]
	v_cvt_pk_f32_fp8_e32 v[104:105], v17
	v_cvt_pk_f32_fp8_e32 v[108:109], v21
	v_cvt_pk_f32_fp8_sdwa v[106:107], v17 src0_sel:WORD_1
	v_cvt_pk_f32_fp8_sdwa v[110:111], v21 src0_sel:WORD_1
	v_pk_fma_f32 v[68:69], v[104:105], v[138:139], v[68:69] op_sel_hi:[1,0,1]
	v_pk_fma_f32 v[70:71], v[106:107], v[138:139], v[70:71] op_sel_hi:[1,0,1]
	v_pk_fma_f32 v[68:69], v[108:109], v[140:141], v[68:69] op_sel_hi:[1,0,1]
	v_pk_fma_f32 v[70:71], v[110:111], v[140:141], v[70:71] op_sel_hi:[1,0,1]
	v_cvt_pk_f32_fp8_e32 v[104:105], v18
	v_cvt_pk_f32_fp8_e32 v[108:109], v22
	v_cvt_pk_f32_fp8_sdwa v[106:107], v18 src0_sel:WORD_1
	v_cvt_pk_f32_fp8_sdwa v[110:111], v22 src0_sel:WORD_1
	v_pk_fma_f32 v[72:73], v[104:105], v[138:139], v[72:73] op_sel_hi:[1,0,1]
	v_pk_fma_f32 v[74:75], v[106:107], v[138:139], v[74:75] op_sel_hi:[1,0,1]
	v_pk_fma_f32 v[72:73], v[108:109], v[140:141], v[72:73] op_sel_hi:[1,0,1]
	v_pk_fma_f32 v[74:75], v[110:111], v[140:141], v[74:75] op_sel_hi:[1,0,1]
	v_cvt_pk_f32_fp8_e32 v[104:105], v19
	v_cvt_pk_f32_fp8_e32 v[108:109], v23
	v_cvt_pk_f32_fp8_sdwa v[106:107], v19 src0_sel:WORD_1
	v_cvt_pk_f32_fp8_sdwa v[110:111], v23 src0_sel:WORD_1
	v_pk_fma_f32 v[76:77], v[104:105], v[138:139], v[76:77] op_sel_hi:[1,0,1]
	v_pk_fma_f32 v[78:79], v[106:107], v[138:139], v[78:79] op_sel_hi:[1,0,1]
	s_waitcnt lgkmcnt(0)
	v_and_or_b32 v142, v142, s90, v240
	v_and_or_b32 v143, v143, s90, v240
	global_load_dwordx4 v[16:19], v142, s[84:85]
	global_load_dwordx4 v[20:23], v143, s[84:85]
	v_pk_fma_f32 v[76:77], v[108:109], v[140:141], v[76:77] op_sel_hi:[1,0,1]
	v_pk_fma_f32 v[78:79], v[110:111], v[140:141], v[78:79] op_sel_hi:[1,0,1]
	ds_bpermute_b32 v142, v255, v134
	ds_bpermute_b32 v143, v153, v134
	ds_bpermute_b32 v138, v249, v137
	ds_bpermute_b32 v140, v250, v137
	s_waitcnt vmcnt(18) lgkmcnt(4)
; #define PG_ISSUE(BUF, TAB, e0_) do { const int isrc_ = ((e0_) < 64) ? myi0 : myi1; \
;       _Pragma("unroll") for (int e = 0; e < 8; ++e) { const int idx_ = __builtin_amdgcn_readlane(isrc_, ((e0_) + e) & 63); \
;         BUF[e] = *(const u32x4*)((TAB) + (size_t)idx_ * 1024 + lane * 16); } } while (0)
; DEV void peer_gather(const Params& P, int l, int m0, const int* idxs, const float* gs) {
;     ...
; #pragma nounroll
;     for (int e0 = 0; e0 < 128; e0 += 16) {
;       PG_ISSUE(b1, V, e0 + 8);
;       if (e0 == 64 && i + 1 < 16) sort_lists(lane, ni0, ni1, ng0, ng1);
;       PG_V16(b0, e0);
;       if (e0 + 16 < 128) PG_ISSUE(b0, V, e0 + 16);
;       PG_V16(b1, e0 + 8);
;     }
	v_cvt_pk_f32_fp8_e32 v[104:105], v24
	v_cvt_pk_f32_fp8_e32 v[108:109], v28
	v_cvt_pk_f32_fp8_sdwa v[106:107], v24 src0_sel:WORD_1
	v_cvt_pk_f32_fp8_sdwa v[110:111], v28 src0_sel:WORD_1
	v_pk_fma_f32 v[64:65], v[104:105], v[144:145], v[64:65] op_sel_hi:[1,0,1]
	v_pk_fma_f32 v[66:67], v[106:107], v[144:145], v[66:67] op_sel_hi:[1,0,1]
	v_pk_fma_f32 v[64:65], v[108:109], v[146:147], v[64:65] op_sel_hi:[1,0,1]
	v_pk_fma_f32 v[66:67], v[110:111], v[146:147], v[66:67] op_sel_hi:[1,0,1]
	v_cvt_pk_f32_fp8_e32 v[104:105], v25
	v_cvt_pk_f32_fp8_e32 v[108:109], v29
	v_cvt_pk_f32_fp8_sdwa v[106:107], v25 src0_sel:WORD_1
	v_cvt_pk_f32_fp8_sdwa v[110:111], v29 src0_sel:WORD_1
	v_pk_fma_f32 v[68:69], v[104:105], v[144:145], v[68:69] op_sel_hi:[1,0,1]
	v_pk_fma_f32 v[70:71], v[106:107], v[144:145], v[70:71] op_sel_hi:[1,0,1]
	v_pk_fma_f32 v[68:69], v[108:109], v[146:147], v[68:69] op_sel_hi:[1,0,1]
	v_pk_fma_f32 v[70:71], v[110:111], v[146:147], v[70:71] op_sel_hi:[1,0,1]
	v_cvt_pk_f32_fp8_e32 v[104:105], v26
	v_cvt_pk_f32_fp8_e32 v[108:109], v30
	v_cvt_pk_f32_fp8_sdwa v[106:107], v26 src0_sel:WORD_1
	v_cvt_pk_f32_fp8_sdwa v[110:111], v30 src0_sel:WORD_1
	v_pk_fma_f32 v[72:73], v[104:105], v[144:145], v[72:73] op_sel_hi:[1,0,1]
	v_pk_fma_f32 v[74:75], v[106:107], v[144:145], v[74:75] op_sel_hi:[1,0,1]
	v_pk_fma_f32 v[72:73], v[108:109], v[146:147], v[72:73] op_sel_hi:[1,0,1]
	v_pk_fma_f32 v[74:75], v[110:111], v[146:147], v[74:75] op_sel_hi:[1,0,1]
	v_cvt_pk_f32_fp8_e32 v[104:105], v27
	v_cvt_pk_f32_fp8_e32 v[108:109], v31
	v_cvt_pk_f32_fp8_sdwa v[106:107], v27 src0_sel:WORD_1
	v_cvt_pk_f32_fp8_sdwa v[110:111], v31 src0_sel:WORD_1
	v_pk_fma_f32 v[76:77], v[104:105], v[144:145], v[76:77] op_sel_hi:[1,0,1]
	v_pk_fma_f32 v[78:79], v[106:107], v[144:145], v[78:79] op_sel_hi:[1,0,1]
	s_waitcnt lgkmcnt(0)
	v_and_or_b32 v142, v142, s90, v240
	v_and_or_b32 v143, v143, s90, v240
	global_load_dwordx4 v[24:27], v142, s[84:85]
	global_load_dwordx4 v[28:31], v143, s[84:85]
	v_pk_fma_f32 v[76:77], v[108:109], v[146:147], v[76:77] op_sel_hi:[1,0,1]
	v_pk_fma_f32 v[78:79], v[110:111], v[146:147], v[78:79] op_sel_hi:[1,0,1]
	ds_bpermute_b32 v142, v249, v135
	ds_bpermute_b32 v143, v250, v135
	ds_bpermute_b32 v144, v251, v137
	ds_bpermute_b32 v146, v252, v137
	s_waitcnt vmcnt(18) lgkmcnt(4)
	v_cvt_pk_f32_fp8_e32 v[104:105], v32
	v_cvt_pk_f32_fp8_e32 v[108:109], v36
	v_cvt_pk_f32_fp8_sdwa v[106:107], v32 src0_sel:WORD_1
	v_cvt_pk_f32_fp8_sdwa v[110:111], v36 src0_sel:WORD_1
	v_pk_fma_f32 v[64:65], v[104:105], v[138:139], v[64:65] op_sel_hi:[1,0,1]
	v_pk_fma_f32 v[66:67], v[106:107], v[138:139], v[66:67] op_sel_hi:[1,0,1]
	v_pk_fma_f32 v[64:65], v[108:109], v[140:141], v[64:65] op_sel_hi:[1,0,1]
	v_pk_fma_f32 v[66:67], v[110:111], v[140:141], v[66:67] op_sel_hi:[1,0,1]
	v_cvt_pk_f32_fp8_e32 v[104:105], v33
	v_cvt_pk_f32_fp8_e32 v[108:109], v37
	v_cvt_pk_f32_fp8_sdwa v[106:107], v33 src0_sel:WORD_1
	v_cvt_pk_f32_fp8_sdwa v[110:111], v37 src0_sel:WORD_1
	v_pk_fma_f32 v[68:69], v[104:105], v[138:139], v[68:69] op_sel_hi:[1,0,1]
	v_pk_fma_f32 v[70:71], v[106:107], v[138:139], v[70:71] op_sel_hi:[1,0,1]
	v_pk_fma_f32 v[68:69], v[108:109], v[140:141], v[68:69] op_sel_hi:[1,0,1]
	v_pk_fma_f32 v[70:71], v[110:111], v[140:141], v[70:71] op_sel_hi:[1,0,1]
	v_cvt_pk_f32_fp8_e32 v[104:105], v34
	v_cvt_pk_f32_fp8_e32 v[108:109], v38
	v_cvt_pk_f32_fp8_sdwa v[106:107], v34 src0_sel:WORD_1
	v_cvt_pk_f32_fp8_sdwa v[110:111], v38 src0_sel:WORD_1
	v_pk_fma_f32 v[72:73], v[104:105], v[138:139], v[72:73] op_sel_hi:[1,0,1]
	v_pk_fma_f32 v[74:75], v[106:107], v[138:139], v[74:75] op_sel_hi:[1,0,1]
	v_pk_fma_f32 v[72:73], v[108:109], v[140:141], v[72:73] op_sel_hi:[1,0,1]
	v_pk_fma_f32 v[74:75], v[110:111], v[140:141], v[74:75] op_sel_hi:[1,0,1]
	v_cvt_pk_f32_fp8_e32 v[104:105], v35
	v_cvt_pk_f32_fp8_e32 v[108:109], v39
	v_cvt_pk_f32_fp8_sdwa v[106:107], v35 src0_sel:WORD_1
	v_cvt_pk_f32_fp8_sdwa v[110:111], v39 src0_sel:WORD_1
	v_pk_fma_f32 v[76:77], v[104:105], v[138:139], v[76:77] op_sel_hi:[1,0,1]
	v_pk_fma_f32 v[78:79], v[106:107], v[138:139], v[78:79] op_sel_hi:[1,0,1]
	s_waitcnt lgkmcnt(0)
	v_and_or_b32 v142, v142, s90, v240
	v_and_or_b32 v143, v143, s90, v240
	global_load_dwordx4 v[32:35], v142, s[84:85]
	global_load_dwordx4 v[36:39], v143, s[84:85]
	v_pk_fma_f32 v[76:77], v[108:109], v[140:141], v[76:77] op_sel_hi:[1,0,1]
	v_pk_fma_f32 v[78:79], v[110:111], v[140:141], v[78:79] op_sel_hi:[1,0,1]
	ds_bpermute_b32 v142, v251, v135
	ds_bpermute_b32 v143, v252, v135
	ds_bpermute_b32 v138, v253, v137
	ds_bpermute_b32 v140, v254, v137
	s_waitcnt vmcnt(18) lgkmcnt(4)
	v_cvt_pk_f32_fp8_e32 v[104:105], v40
	v_cvt_pk_f32_fp8_e32 v[108:109], v44
	v_cvt_pk_f32_fp8_sdwa v[106:107], v40 src0_sel:WORD_1
	v_cvt_pk_f32_fp8_sdwa v[110:111], v44 src0_sel:WORD_1
	v_pk_fma_f32 v[64:65], v[104:105], v[144:145], v[64:65] op_sel_hi:[1,0,1]
	v_pk_fma_f32 v[66:67], v[106:107], v[144:145], v[66:67] op_sel_hi:[1,0,1]
	v_pk_fma_f32 v[64:65], v[108:109], v[146:147], v[64:65] op_sel_hi:[1,0,1]
	v_pk_fma_f32 v[66:67], v[110:111], v[146:147], v[66:67] op_sel_hi:[1,0,1]
	v_cvt_pk_f32_fp8_e32 v[104:105], v41
	v_cvt_pk_f32_fp8_e32 v[108:109], v45
	v_cvt_pk_f32_fp8_sdwa v[106:107], v41 src0_sel:WORD_1
	v_cvt_pk_f32_fp8_sdwa v[110:111], v45 src0_sel:WORD_1
	v_pk_fma_f32 v[68:69], v[104:105], v[144:145], v[68:69] op_sel_hi:[1,0,1]
	v_pk_fma_f32 v[70:71], v[106:107], v[144:145], v[70:71] op_sel_hi:[1,0,1]
	v_pk_fma_f32 v[68:69], v[108:109], v[146:147], v[68:69] op_sel_hi:[1,0,1]
	v_pk_fma_f32 v[70:71], v[110:111], v[146:147], v[70:71] op_sel_hi:[1,0,1]
	v_cvt_pk_f32_fp8_e32 v[104:105], v42
	v_cvt_pk_f32_fp8_e32 v[108:109], v46
	v_cvt_pk_f32_fp8_sdwa v[106:107], v42 src0_sel:WORD_1
	v_cvt_pk_f32_fp8_sdwa v[110:111], v46 src0_sel:WORD_1
	v_pk_fma_f32 v[72:73], v[104:105], v[144:145], v[72:73] op_sel_hi:[1,0,1]
	v_pk_fma_f32 v[74:75], v[106:107], v[144:145], v[74:75] op_sel_hi:[1,0,1]
	v_pk_fma_f32 v[72:73], v[108:109], v[146:147], v[72:73] op_sel_hi:[1,0,1]
	v_pk_fma_f32 v[74:75], v[110:111], v[146:147], v[74:75] op_sel_hi:[1,0,1]
	v_cvt_pk_f32_fp8_e32 v[104:105], v43
	v_cvt_pk_f32_fp8_e32 v[108:109], v47
	v_cvt_pk_f32_fp8_sdwa v[106:107], v43 src0_sel:WORD_1
	v_cvt_pk_f32_fp8_sdwa v[110:111], v47 src0_sel:WORD_1
	v_pk_fma_f32 v[76:77], v[104:105], v[144:145], v[76:77] op_sel_hi:[1,0,1]
	v_pk_fma_f32 v[78:79], v[106:107], v[144:145], v[78:79] op_sel_hi:[1,0,1]
	s_waitcnt lgkmcnt(0)
; #define PG_ISSUE(BUF, TAB, e0_) do { const int isrc_ = ((e0_) < 64) ? myi0 : myi1; \
;       _Pragma("unroll") for (int e = 0; e < 8; ++e) { const int idx_ = __builtin_amdgcn_readlane(isrc_, ((e0_) + e) & 63); \
;         BUF[e] = *(const u32x4*)((TAB) + (size_t)idx_ * 1024 + lane * 16); } } while (0)
; DEV void peer_gather(const Params& P, int l, int m0, const int* idxs, const float* gs) {
;     ...
; #pragma nounroll
;     for (int e0 = 0; e0 < 128; e0 += 16) {
;       PG_ISSUE(b1, V, e0 + 8);
;       if (e0 == 64 && i + 1 < 16) sort_lists(lane, ni0, ni1, ng0, ng1);
;       PG_V16(b0, e0);
;       if (e0 + 16 < 128) PG_ISSUE(b0, V, e0 + 16);
;       PG_V16(b1, e0 + 8);
;     }
;     ...
;       hv[q][0] += acc[2 * q][0] * TAB_INV; hv[q][1] += acc[2 * q][1] * TAB_INV; hv[q][2] += acc[2 * q + 1][0] * TAB_INV; hv[q][3] += acc[2 * q + 1][1] * TAB_INV;
;       ss += hv[q][0] * hv[q][0] + hv[q][1] * hv[q][1] + hv[q][2] * hv[q][2] + hv[q][3] * hv[q][3];
;       *(f32x4*)(hrow + 4 * q) = hv[q];
	v_and_or_b32 v142, v142, s90, v240
	v_and_or_b32 v143, v143, s90, v240
	global_load_dwordx4 v[40:43], v142, s[84:85]
	global_load_dwordx4 v[44:47], v143, s[84:85]
	v_pk_fma_f32 v[76:77], v[108:109], v[146:147], v[76:77] op_sel_hi:[1,0,1]
	v_pk_fma_f32 v[78:79], v[110:111], v[146:147], v[78:79] op_sel_hi:[1,0,1]
	ds_bpermute_b32 v142, v253, v135
	ds_bpermute_b32 v143, v254, v135
	ds_bpermute_b32 v144, v255, v137
	ds_bpermute_b32 v146, v153, v137
	s_waitcnt vmcnt(18) lgkmcnt(4)
	v_cvt_pk_f32_fp8_e32 v[104:105], v48
	v_cvt_pk_f32_fp8_e32 v[108:109], v52
	v_cvt_pk_f32_fp8_sdwa v[106:107], v48 src0_sel:WORD_1
	v_cvt_pk_f32_fp8_sdwa v[110:111], v52 src0_sel:WORD_1
	v_pk_fma_f32 v[64:65], v[104:105], v[138:139], v[64:65] op_sel_hi:[1,0,1]
	v_pk_fma_f32 v[66:67], v[106:107], v[138:139], v[66:67] op_sel_hi:[1,0,1]
	v_pk_fma_f32 v[64:65], v[108:109], v[140:141], v[64:65] op_sel_hi:[1,0,1]
	v_pk_fma_f32 v[66:67], v[110:111], v[140:141], v[66:67] op_sel_hi:[1,0,1]
	v_cvt_pk_f32_fp8_e32 v[104:105], v49
	v_cvt_pk_f32_fp8_e32 v[108:109], v53
	v_cvt_pk_f32_fp8_sdwa v[106:107], v49 src0_sel:WORD_1
	v_cvt_pk_f32_fp8_sdwa v[110:111], v53 src0_sel:WORD_1
	v_pk_fma_f32 v[68:69], v[104:105], v[138:139], v[68:69] op_sel_hi:[1,0,1]
	v_pk_fma_f32 v[70:71], v[106:107], v[138:139], v[70:71] op_sel_hi:[1,0,1]
	v_pk_fma_f32 v[68:69], v[108:109], v[140:141], v[68:69] op_sel_hi:[1,0,1]
	v_pk_fma_f32 v[70:71], v[110:111], v[140:141], v[70:71] op_sel_hi:[1,0,1]
	v_cvt_pk_f32_fp8_e32 v[104:105], v50
	v_cvt_pk_f32_fp8_e32 v[108:109], v54
	v_cvt_pk_f32_fp8_sdwa v[106:107], v50 src0_sel:WORD_1
	v_cvt_pk_f32_fp8_sdwa v[110:111], v54 src0_sel:WORD_1
	v_pk_fma_f32 v[72:73], v[104:105], v[138:139], v[72:73] op_sel_hi:[1,0,1]
	v_pk_fma_f32 v[74:75], v[106:107], v[138:139], v[74:75] op_sel_hi:[1,0,1]
	v_pk_fma_f32 v[72:73], v[108:109], v[140:141], v[72:73] op_sel_hi:[1,0,1]
	v_pk_fma_f32 v[74:75], v[110:111], v[140:141], v[74:75] op_sel_hi:[1,0,1]
	v_cvt_pk_f32_fp8_e32 v[104:105], v51
	v_cvt_pk_f32_fp8_e32 v[108:109], v55
	v_cvt_pk_f32_fp8_sdwa v[106:107], v51 src0_sel:WORD_1
	v_cvt_pk_f32_fp8_sdwa v[110:111], v55 src0_sel:WORD_1
	v_pk_fma_f32 v[76:77], v[104:105], v[138:139], v[76:77] op_sel_hi:[1,0,1]
	v_pk_fma_f32 v[78:79], v[106:107], v[138:139], v[78:79] op_sel_hi:[1,0,1]
	s_waitcnt lgkmcnt(0)
	v_and_or_b32 v142, v142, s90, v240
	v_and_or_b32 v143, v143, s90, v240
	global_load_dwordx4 v[48:51], v142, s[84:85]
	global_load_dwordx4 v[52:55], v143, s[84:85]
	v_pk_fma_f32 v[76:77], v[108:109], v[140:141], v[76:77] op_sel_hi:[1,0,1]
	v_pk_fma_f32 v[78:79], v[110:111], v[140:141], v[78:79] op_sel_hi:[1,0,1]
	ds_bpermute_b32 v142, v255, v135
	ds_bpermute_b32 v143, v153, v135
	s_waitcnt vmcnt(18) lgkmcnt(2)
	v_cvt_pk_f32_fp8_e32 v[104:105], v56
	v_cvt_pk_f32_fp8_e32 v[108:109], v60
	v_cvt_pk_f32_fp8_sdwa v[106:107], v56 src0_sel:WORD_1
	v_cvt_pk_f32_fp8_sdwa v[110:111], v60 src0_sel:WORD_1
	v_pk_fma_f32 v[64:65], v[104:105], v[144:145], v[64:65] op_sel_hi:[1,0,1]
	v_pk_fma_f32 v[66:67], v[106:107], v[144:145], v[66:67] op_sel_hi:[1,0,1]
	v_pk_fma_f32 v[64:65], v[108:109], v[146:147], v[64:65] op_sel_hi:[1,0,1]
	v_pk_fma_f32 v[66:67], v[110:111], v[146:147], v[66:67] op_sel_hi:[1,0,1]
	v_cvt_pk_f32_fp8_e32 v[104:105], v57
	v_cvt_pk_f32_fp8_e32 v[108:109], v61
	v_cvt_pk_f32_fp8_sdwa v[106:107], v57 src0_sel:WORD_1
	v_cvt_pk_f32_fp8_sdwa v[110:111], v61 src0_sel:WORD_1
	v_pk_fma_f32 v[68:69], v[104:105], v[144:145], v[68:69] op_sel_hi:[1,0,1]
	v_pk_fma_f32 v[70:71], v[106:107], v[144:145], v[70:71] op_sel_hi:[1,0,1]
	v_pk_fma_f32 v[68:69], v[108:109], v[146:147], v[68:69] op_sel_hi:[1,0,1]
	v_pk_fma_f32 v[70:71], v[110:111], v[146:147], v[70:71] op_sel_hi:[1,0,1]
	v_cvt_pk_f32_fp8_e32 v[104:105], v58
	v_cvt_pk_f32_fp8_e32 v[108:109], v62
	v_cvt_pk_f32_fp8_sdwa v[106:107], v58 src0_sel:WORD_1
	v_cvt_pk_f32_fp8_sdwa v[110:111], v62 src0_sel:WORD_1
	v_pk_fma_f32 v[72:73], v[104:105], v[144:145], v[72:73] op_sel_hi:[1,0,1]
	v_pk_fma_f32 v[74:75], v[106:107], v[144:145], v[74:75] op_sel_hi:[1,0,1]
	v_pk_fma_f32 v[72:73], v[108:109], v[146:147], v[72:73] op_sel_hi:[1,0,1]
	v_pk_fma_f32 v[74:75], v[110:111], v[146:147], v[74:75] op_sel_hi:[1,0,1]
	v_cvt_pk_f32_fp8_e32 v[104:105], v59
	v_cvt_pk_f32_fp8_e32 v[108:109], v63
	v_cvt_pk_f32_fp8_sdwa v[106:107], v59 src0_sel:WORD_1
	v_cvt_pk_f32_fp8_sdwa v[110:111], v63 src0_sel:WORD_1
	v_pk_fma_f32 v[76:77], v[104:105], v[144:145], v[76:77] op_sel_hi:[1,0,1]
	v_pk_fma_f32 v[78:79], v[106:107], v[144:145], v[78:79] op_sel_hi:[1,0,1]
	s_waitcnt lgkmcnt(0)
	v_and_or_b32 v142, v142, s90, v240
	v_and_or_b32 v143, v143, s90, v240
	global_load_dwordx4 v[56:59], v142, s[84:85]
	global_load_dwordx4 v[60:63], v143, s[84:85]
	v_pk_fma_f32 v[76:77], v[108:109], v[146:147], v[76:77] op_sel_hi:[1,0,1]
	v_pk_fma_f32 v[78:79], v[110:111], v[146:147], v[78:79] op_sel_hi:[1,0,1]
	s_add_u32 s92, s100, 2
	s_min_u32 s92, s92, 127
	s_and_b32 s92, s92, 15
	s_lshl_b32 vcc_lo, s92, 9
	s_add_u32 vcc_lo, vcc_lo, s101
	v_add_u32_e32 v116, vcc_lo, v234
	ds_read_b32 v134, v116
	ds_read_b32 v135, v116 offset:256
	s_add_u32 s92, s100, 1
	s_min_u32 s92, s92, 127
	s_and_b32 s92, s92, 15
	s_lshl_b32 vcc_lo, s92, 9
	s_add_u32 vcc_lo, vcc_lo, s101
	s_add_u32 vcc_lo, vcc_lo, 0x10000
	v_add_u32_e32 v117, vcc_lo, v234
	ds_read_b32 v136, v117
	ds_read_b32 v137, v117 offset:256
	s_nop 1
	v_permlane32_swap_b32_e32 v64, v65
	v_permlane32_swap_b32_e32 v66, v67
	v_permlane32_swap_b32_e32 v68, v69
	v_permlane32_swap_b32_e32 v70, v71
	v_permlane32_swap_b32_e32 v72, v73
	v_permlane32_swap_b32_e32 v74, v75
	v_permlane32_swap_b32_e32 v76, v77
	v_permlane32_swap_b32_e32 v78, v79
	v_add_f32_e32 v64, v64, v65
	v_add_f32_e32 v66, v66, v67
	v_add_f32_e32 v68, v68, v69
	v_add_f32_e32 v70, v70, v71
	v_add_f32_e32 v72, v72, v73
	v_add_f32_e32 v74, v74, v75
	v_add_f32_e32 v76, v76, v77
	v_add_f32_e32 v78, v78, v79
	s_nop 1
	v_permlane16_swap_b32_e32 v64, v66
	v_permlane16_swap_b32_e32 v68, v70
	v_permlane16_swap_b32_e32 v72, v74
	v_permlane16_swap_b32_e32 v76, v78
	v_add_f32_e32 v64, v64, v66
	v_add_f32_e32 v68, v68, v70
	v_add_f32_e32 v72, v72, v74
	v_add_f32_e32 v76, v76, v78
	s_mov_b32 s88, 0xff00ff00
	s_mov_b32 s89, 0xff00ff00
	s_nop 0
	v_cndmask_b32_e64 v65, v64, v68, s[88:89]
	v_cndmask_b32_e64 v66, v68, v64, s[88:89]
	v_cndmask_b32_e64 v73, v72, v76, s[88:89]
	v_cndmask_b32_e64 v74, v76, v72, s[88:89]
	s_nop 1
	v_add_f32_dpp v64, v66, v65 row_ror:8 row_mask:0xf bank_mask:0xf
	v_add_f32_dpp v72, v74, v73 row_ror:8 row_mask:0xf bank_mask:0xf
	s_waitcnt vmcnt(16)
	v_fmac_f32_e32 v80, 0x3c800000, v64
	v_fmac_f32_e32 v81, 0x3c800000, v72
	global_store_dword v119, v80, s[82:83]
	global_store_dword v119, v81, s[82:83] offset:32
	s_add_u32 s100, s100, 1
	s_cmp_lt_u32 s100, 128
	s_cbranch_scc1 .Lpg0_vloop
; DEV void peer_gather(const Params& P, int l, int m0, const int* idxs, const float* gs) {
;     ...
;     for (int q = 0; q < 4; ++q) {
;       const f32x4 g = *(const f32x4*)(gp + lane * 16 + 4 * q);
	s_waitcnt vmcnt(0) lgkmcnt(0)
	v_readfirstlane_b32 s88, v130
	v_readfirstlane_b32 s89, v131
	s_nop 4
	v_lshlrev_b32_e32 v117, 6, v233
	global_load_dwordx4 v[16:19], v117, s[88:89] offset:0
	global_load_dwordx4 v[20:23], v117, s[88:89] offset:16
	global_load_dwordx4 v[24:27], v117, s[88:89] offset:32
	global_load_dwordx4 v[28:31], v117, s[88:89] offset:48
	s_mov_b32 s2, 0

; DEV void sort_lists(int lane, int& myi0, int& myi1, float& myg0, float& myg1) {
; #pragma unroll
;     for (int k = 2; k <= 128; k <<= 1) {
; #pragma unroll
;       for (int j = k >> 1; j >= 1; j >>= 1) {
;         if (j == 64) {
;           const bool sw_ = myi1 < myi0;
;           const int ti = sw_ ? myi1 : myi0, tj = sw_ ? myi0 : myi1; const float tg = sw_ ? myg1 : myg0, th = sw_ ? myg0 : myg1;
;           myi0 = ti; myi1 = tj; myg0 = tg; myg1 = th;
;         } else {
;           const bool lower = (lane & j) == 0;
;           {
;             const bool up = (k == 128) ? true : ((k == 64) ? true : ((lane & k) == 0));
;             const int oi = __shfl_xor(myi0, j); const float og = __shfl_xor(myg0, j);
;             const bool take = (lower == up) ? (oi < myi0) : (oi > myi0);
;             myi0 = take ? oi : myi0; myg0 = take ? og : myg0;
;           }
;           {
;             const bool up = (k == 128) ? true : ((k == 64) ? false : ((lane & k) == 0));
;             const int oi = __shfl_xor(myi1, j); const float og = __shfl_xor(myg1, j);
;             const bool take = (lower == up) ? (oi < myi1) : (oi > myi1);
;             myi1 = take ? oi : myi1; myg1 = take ? og : myg1;
;           }
;         }
;       }
;     }
; }
; DEV void peer_gather(const Params& P, int l, int m0, const int* idxs, const float* gs) {
;     ...
;   int ni0 = idxs[(wid * 16) * 128 + lane], ni1 = idxs[(wid * 16) * 128 + 64 + lane];
;   float ng0 = gs[(wid * 16) * 128 + lane], ng1 = gs[(wid * 16) * 128 + 64 + lane];
;   sort_lists(lane, ni0, ni1, ng0, ng1);
.Lpg1_p0:
	v_readlane_b32 s82, v231, 13
	v_readlane_b32 s83, v231, 14
	s_nop 4
	s_lshl_b32 s98, s2, 2
	s_add_u32 s98, s98, s33
	s_add_u32 s98, s98, 0
	s_lshl_b32 s98, s98, 9
	v_add_u32_e32 v116, s98, v234
	global_load_dword v241, v116, s[82:83]
	global_load_dword v242, v116, s[82:83] offset:256
	s_lshl_b32 s98, s2, 2
	s_add_u32 s98, s98, s33
	s_add_u32 s98, s98, 1
	s_lshl_b32 s98, s98, 9
	v_add_u32_e32 v117, s98, v234
	global_load_dword v243, v117, s[82:83]
	global_load_dword v244, v117, s[82:83] offset:256
	s_lshl_b32 s98, s2, 2
	s_add_u32 s98, s98, s33
	s_add_u32 s98, s98, 2
	s_lshl_b32 s98, s98, 9
	v_add_u32_e32 v118, s98, v234
	global_load_dword v245, v118, s[82:83]
	global_load_dword v246, v118, s[82:83] offset:256
	s_lshl_b32 s98, s2, 2
	s_add_u32 s98, s98, s33
	s_add_u32 s98, s98, 3
	s_lshl_b32 s98, s98, 9
	v_add_u32_e32 v119, s98, v234
	global_load_dword v247, v119, s[82:83]
	global_load_dword v248, v119, s[82:83] offset:256
	s_waitcnt vmcnt(0)
	v_or_b32_e32 v116, 64, v233
	v_lshl_or_b32 v241, v241, 7, v233
	v_lshl_or_b32 v242, v242, 7, v116
	v_lshl_or_b32 v243, v243, 7, v233
	v_lshl_or_b32 v244, v244, 7, v116
	v_lshl_or_b32 v245, v245, 7, v233
	v_lshl_or_b32 v246, v246, 7, v116
	v_lshl_or_b32 v247, v247, 7, v233
	v_lshl_or_b32 v248, v248, 7, v116
	v_xor_b32_e32 v116, 4, v234
	ds_bpermute_b32 v0, v116, v241
	ds_bpermute_b32 v1, v116, v243
	ds_bpermute_b32 v2, v116, v245
	ds_bpermute_b32 v3, v116, v247
	ds_bpermute_b32 v4, v116, v242
	ds_bpermute_b32 v5, v116, v244
	ds_bpermute_b32 v6, v116, v246
	ds_bpermute_b32 v7, v116, v248
	s_waitcnt lgkmcnt(0)
	s_mov_b32 s88, 0x99999999
	s_mov_b32 s89, 0x99999999
	v_min_u32_e32 v104, v241, v0
	v_max_u32_e32 v105, v241, v0
	v_cndmask_b32_e64 v241, v105, v104, s[88:89]
	v_min_u32_e32 v106, v243, v1
	v_max_u32_e32 v107, v243, v1
	v_cndmask_b32_e64 v243, v107, v106, s[88:89]
	v_min_u32_e32 v104, v245, v2
	v_max_u32_e32 v105, v245, v2
	v_cndmask_b32_e64 v245, v105, v104, s[88:89]
	v_min_u32_e32 v106, v247, v3
	v_max_u32_e32 v107, v247, v3
	v_cndmask_b32_e64 v247, v107, v106, s[88:89]
	v_min_u32_e32 v104, v242, v4
	v_max_u32_e32 v105, v242, v4
	v_cndmask_b32_e64 v242, v105, v104, s[88:89]
	v_min_u32_e32 v106, v244, v5
	v_max_u32_e32 v107, v244, v5
	v_cndmask_b32_e64 v244, v107, v106, s[88:89]
	v_min_u32_e32 v104, v246, v6
	v_max_u32_e32 v105, v246, v6
	v_cndmask_b32_e64 v246, v105, v104, s[88:89]
	v_min_u32_e32 v106, v248, v7
	v_max_u32_e32 v107, v248, v7
	v_cndmask_b32_e64 v248, v107, v106, s[88:89]
	v_xor_b32_e32 v116, 8, v234
	ds_bpermute_b32 v0, v116, v241
	ds_bpermute_b32 v1, v116, v243
	ds_bpermute_b32 v2, v116, v245
	ds_bpermute_b32 v3, v116, v247
	ds_bpermute_b32 v4, v116, v242
	ds_bpermute_b32 v5, v116, v244
	ds_bpermute_b32 v6, v116, v246
	ds_bpermute_b32 v7, v116, v248
	s_waitcnt lgkmcnt(0)
	s_mov_b32 s88, 0xc3c3c3c3
	s_mov_b32 s89, 0xc3c3c3c3
	v_min_u32_e32 v104, v241, v0
	v_max_u32_e32 v105, v241, v0
	v_cndmask_b32_e64 v241, v105, v104, s[88:89]
	v_min_u32_e32 v106, v243, v1
	v_max_u32_e32 v107, v243, v1
	v_cndmask_b32_e64 v243, v107, v106, s[88:89]
	v_min_u32_e32 v104, v245, v2
	v_max_u32_e32 v105, v245, v2
	v_cndmask_b32_e64 v245, v105, v104, s[88:89]
	v_min_u32_e32 v106, v247, v3
	v_max_u32_e32 v107, v247, v3
	v_cndmask_b32_e64 v247, v107, v106, s[88:89]
	v_min_u32_e32 v104, v242, v4
	v_max_u32_e32 v105, v242, v4
	v_cndmask_b32_e64 v242, v105, v104, s[88:89]
	v_min_u32_e32 v106, v244, v5
	v_max_u32_e32 v107, v244, v5
	v_cndmask_b32_e64 v244, v107, v106, s[88:89]
	v_min_u32_e32 v104, v246, v6
	v_max_u32_e32 v105, v246, v6
	v_cndmask_b32_e64 v246, v105, v104, s[88:89]
	v_min_u32_e32 v106, v248, v7
	v_max_u32_e32 v107, v248, v7
	v_cndmask_b32_e64 v248, v107, v106, s[88:89]
	v_xor_b32_e32 v116, 4, v234
	ds_bpermute_b32 v0, v116, v241
	ds_bpermute_b32 v1, v116, v243
	ds_bpermute_b32 v2, v116, v245
	ds_bpermute_b32 v3, v116, v247
	ds_bpermute_b32 v4, v116, v242
	ds_bpermute_b32 v5, v116, v244
	ds_bpermute_b32 v6, v116, v246
	ds_bpermute_b32 v7, v116, v248
	s_waitcnt lgkmcnt(0)
	s_mov_b32 s88, 0xa5a5a5a5
	s_mov_b32 s89, 0xa5a5a5a5
	v_min_u32_e32 v104, v241, v0
	v_max_u32_e32 v105, v241, v0
	v_cndmask_b32_e64 v241, v105, v104, s[88:89]
	v_min_u32_e32 v106, v243, v1
	v_max_u32_e32 v107, v243, v1
	v_cndmask_b32_e64 v243, v107, v106, s[88:89]
	v_min_u32_e32 v104, v245, v2
	v_max_u32_e32 v105, v245, v2
	v_cndmask_b32_e64 v245, v105, v104, s[88:89]
	v_min_u32_e32 v106, v247, v3
	v_max_u32_e32 v107, v247, v3
	v_cndmask_b32_e64 v247, v107, v106, s[88:89]
	v_min_u32_e32 v104, v242, v4
	v_max_u32_e32 v105, v242, v4
	v_cndmask_b32_e64 v242, v105, v104, s[88:89]
	v_min_u32_e32 v106, v244, v5
	v_max_u32_e32 v107, v244, v5
	v_cndmask_b32_e64 v244, v107, v106, s[88:89]
	v_min_u32_e32 v104, v246, v6
	v_max_u32_e32 v105, v246, v6
	v_cndmask_b32_e64 v246, v105, v104, s[88:89]
	v_min_u32_e32 v106, v248, v7
	v_max_u32_e32 v107, v248, v7
	v_cndmask_b32_e64 v248, v107, v106, s[88:89]
	v_xor_b32_e32 v116, 16, v234
	ds_bpermute_b32 v0, v116, v241
	ds_bpermute_b32 v1, v116, v243
	ds_bpermute_b32 v2, v116, v245
	ds_bpermute_b32 v3, v116, v247
	ds_bpermute_b32 v4, v116, v242
	ds_bpermute_b32 v5, v116, v244
	ds_bpermute_b32 v6, v116, v246
	ds_bpermute_b32 v7, v116, v248
	s_waitcnt lgkmcnt(0)
; DEV void sort_lists(int lane, int& myi0, int& myi1, float& myg0, float& myg1) {
; #pragma unroll
;     for (int k = 2; k <= 128; k <<= 1) {
; #pragma unroll
;       for (int j = k >> 1; j >= 1; j >>= 1) {
;         if (j == 64) {
;           const bool sw_ = myi1 < myi0;
;           const int ti = sw_ ? myi1 : myi0, tj = sw_ ? myi0 : myi1; const float tg = sw_ ? myg1 : myg0, th = sw_ ? myg0 : myg1;
;           myi0 = ti; myi1 = tj; myg0 = tg; myg1 = th;
;         } else {
;           const bool lower = (lane & j) == 0;
;           {
;             const bool up = (k == 128) ? true : ((k == 64) ? true : ((lane & k) == 0));
;             const int oi = __shfl_xor(myi0, j); const float og = __shfl_xor(myg0, j);
;             const bool take = (lower == up) ? (oi < myi0) : (oi > myi0);
;             myi0 = take ? oi : myi0; myg0 = take ? og : myg0;
;           }
;           {
;             const bool up = (k == 128) ? true : ((k == 64) ? false : ((lane & k) == 0));
;             const int oi = __shfl_xor(myi1, j); const float og = __shfl_xor(myg1, j);
;             const bool take = (lower == up) ? (oi < myi1) : (oi > myi1);
;             myi1 = take ? oi : myi1; myg1 = take ? og : myg1;
;           }
;         }
;       }
;     }
; }
	s_mov_b32 s88, 0xf00ff00f
	s_mov_b32 s89, 0xf00ff00f
	v_min_u32_e32 v104, v241, v0
	v_max_u32_e32 v105, v241, v0
	v_cndmask_b32_e64 v241, v105, v104, s[88:89]
	v_min_u32_e32 v106, v243, v1
	v_max_u32_e32 v107, v243, v1
	v_cndmask_b32_e64 v243, v107, v106, s[88:89]
	v_min_u32_e32 v104, v245, v2
	v_max_u32_e32 v105, v245, v2
	v_cndmask_b32_e64 v245, v105, v104, s[88:89]
	v_min_u32_e32 v106, v247, v3
	v_max_u32_e32 v107, v247, v3
	v_cndmask_b32_e64 v247, v107, v106, s[88:89]
	v_min_u32_e32 v104, v242, v4
	v_max_u32_e32 v105, v242, v4
	v_cndmask_b32_e64 v242, v105, v104, s[88:89]
	v_min_u32_e32 v106, v244, v5
	v_max_u32_e32 v107, v244, v5
	v_cndmask_b32_e64 v244, v107, v106, s[88:89]
	v_min_u32_e32 v104, v246, v6
	v_max_u32_e32 v105, v246, v6
	v_cndmask_b32_e64 v246, v105, v104, s[88:89]
	v_min_u32_e32 v106, v248, v7
	v_max_u32_e32 v107, v248, v7
	v_cndmask_b32_e64 v248, v107, v106, s[88:89]
	v_xor_b32_e32 v116, 8, v234
	ds_bpermute_b32 v0, v116, v241
	ds_bpermute_b32 v1, v116, v243
	ds_bpermute_b32 v2, v116, v245
	ds_bpermute_b32 v3, v116, v247
	ds_bpermute_b32 v4, v116, v242
	ds_bpermute_b32 v5, v116, v244
	ds_bpermute_b32 v6, v116, v246
	ds_bpermute_b32 v7, v116, v248
	s_waitcnt lgkmcnt(0)
	s_mov_b32 s88, 0xcc33cc33
	s_mov_b32 s89, 0xcc33cc33
	v_min_u32_e32 v104, v241, v0
	v_max_u32_e32 v105, v241, v0
	v_cndmask_b32_e64 v241, v105, v104, s[88:89]
	v_min_u32_e32 v106, v243, v1
	v_max_u32_e32 v107, v243, v1
	v_cndmask_b32_e64 v243, v107, v106, s[88:89]
	v_min_u32_e32 v104, v245, v2
	v_max_u32_e32 v105, v245, v2
	v_cndmask_b32_e64 v245, v105, v104, s[88:89]
	v_min_u32_e32 v106, v247, v3
	v_max_u32_e32 v107, v247, v3
	v_cndmask_b32_e64 v247, v107, v106, s[88:89]
	v_min_u32_e32 v104, v242, v4
	v_max_u32_e32 v105, v242, v4
	v_cndmask_b32_e64 v242, v105, v104, s[88:89]
	v_min_u32_e32 v106, v244, v5
	v_max_u32_e32 v107, v244, v5
	v_cndmask_b32_e64 v244, v107, v106, s[88:89]
	v_min_u32_e32 v104, v246, v6
	v_max_u32_e32 v105, v246, v6
	v_cndmask_b32_e64 v246, v105, v104, s[88:89]
	v_min_u32_e32 v106, v248, v7
	v_max_u32_e32 v107, v248, v7
	v_cndmask_b32_e64 v248, v107, v106, s[88:89]
	v_xor_b32_e32 v116, 4, v234
	ds_bpermute_b32 v0, v116, v241
	ds_bpermute_b32 v1, v116, v243
	ds_bpermute_b32 v2, v116, v245
	ds_bpermute_b32 v3, v116, v247
	ds_bpermute_b32 v4, v116, v242
	ds_bpermute_b32 v5, v116, v244
	ds_bpermute_b32 v6, v116, v246
	ds_bpermute_b32 v7, v116, v248
	s_waitcnt lgkmcnt(0)
	s_mov_b32 s88, 0xaa55aa55
	s_mov_b32 s89, 0xaa55aa55
	v_min_u32_e32 v104, v241, v0
	v_max_u32_e32 v105, v241, v0
	v_cndmask_b32_e64 v241, v105, v104, s[88:89]
	v_min_u32_e32 v106, v243, v1
	v_max_u32_e32 v107, v243, v1
	v_cndmask_b32_e64 v243, v107, v106, s[88:89]
	v_min_u32_e32 v104, v245, v2
	v_max_u32_e32 v105, v245, v2
	v_cndmask_b32_e64 v245, v105, v104, s[88:89]
	v_min_u32_e32 v106, v247, v3
	v_max_u32_e32 v107, v247, v3
	v_cndmask_b32_e64 v247, v107, v106, s[88:89]
	v_min_u32_e32 v104, v242, v4
	v_max_u32_e32 v105, v242, v4
	v_cndmask_b32_e64 v242, v105, v104, s[88:89]
	v_min_u32_e32 v106, v244, v5
	v_max_u32_e32 v107, v244, v5
	v_cndmask_b32_e64 v244, v107, v106, s[88:89]
	v_min_u32_e32 v104, v246, v6
	v_max_u32_e32 v105, v246, v6
	v_cndmask_b32_e64 v246, v105, v104, s[88:89]
	v_min_u32_e32 v106, v248, v7
	v_max_u32_e32 v107, v248, v7
	v_cndmask_b32_e64 v248, v107, v106, s[88:89]
	v_xor_b32_e32 v116, 32, v234
	ds_bpermute_b32 v0, v116, v241
	ds_bpermute_b32 v1, v116, v243
	ds_bpermute_b32 v2, v116, v245
	ds_bpermute_b32 v3, v116, v247
	ds_bpermute_b32 v4, v116, v242
	ds_bpermute_b32 v5, v116, v244
	ds_bpermute_b32 v6, v116, v246
	ds_bpermute_b32 v7, v116, v248
	s_waitcnt lgkmcnt(0)
	s_mov_b32 s88, 0xff0000ff
	s_mov_b32 s89, 0xff0000ff
	v_min_u32_e32 v104, v241, v0
	v_max_u32_e32 v105, v241, v0
	v_cndmask_b32_e64 v241, v105, v104, s[88:89]
	v_min_u32_e32 v106, v243, v1
	v_max_u32_e32 v107, v243, v1
	v_cndmask_b32_e64 v243, v107, v106, s[88:89]
	v_min_u32_e32 v104, v245, v2
	v_max_u32_e32 v105, v245, v2
	v_cndmask_b32_e64 v245, v105, v104, s[88:89]
	v_min_u32_e32 v106, v247, v3
	v_max_u32_e32 v107, v247, v3
	v_cndmask_b32_e64 v247, v107, v106, s[88:89]
	v_min_u32_e32 v104, v242, v4
	v_max_u32_e32 v105, v242, v4
	v_cndmask_b32_e64 v242, v105, v104, s[88:89]
	v_min_u32_e32 v106, v244, v5
	v_max_u32_e32 v107, v244, v5
	v_cndmask_b32_e64 v244, v107, v106, s[88:89]
	v_min_u32_e32 v104, v246, v6
	v_max_u32_e32 v105, v246, v6
	v_cndmask_b32_e64 v246, v105, v104, s[88:89]
	v_min_u32_e32 v106, v248, v7
	v_max_u32_e32 v107, v248, v7
	v_cndmask_b32_e64 v248, v107, v106, s[88:89]
	v_xor_b32_e32 v116, 16, v234
	ds_bpermute_b32 v0, v116, v241
	ds_bpermute_b32 v1, v116, v243
	ds_bpermute_b32 v2, v116, v245
	ds_bpermute_b32 v3, v116, v247
	ds_bpermute_b32 v4, v116, v242
	ds_bpermute_b32 v5, v116, v244
	ds_bpermute_b32 v6, v116, v246
	ds_bpermute_b32 v7, v116, v248
	s_waitcnt lgkmcnt(0)
	s_mov_b32 s88, 0xf0f00f0f
	s_mov_b32 s89, 0xf0f00f0f
	v_min_u32_e32 v104, v241, v0
	v_max_u32_e32 v105, v241, v0
	v_cndmask_b32_e64 v241, v105, v104, s[88:89]
	v_min_u32_e32 v106, v243, v1
	v_max_u32_e32 v107, v243, v1
	v_cndmask_b32_e64 v243, v107, v106, s[88:89]
	v_min_u32_e32 v104, v245, v2
	v_max_u32_e32 v105, v245, v2
	v_cndmask_b32_e64 v245, v105, v104, s[88:89]
	v_min_u32_e32 v106, v247, v3
	v_max_u32_e32 v107, v247, v3
	v_cndmask_b32_e64 v247, v107, v106, s[88:89]
	v_min_u32_e32 v104, v242, v4
	v_max_u32_e32 v105, v242, v4
	v_cndmask_b32_e64 v242, v105, v104, s[88:89]
	v_min_u32_e32 v106, v244, v5
	v_max_u32_e32 v107, v244, v5
	v_cndmask_b32_e64 v244, v107, v106, s[88:89]
	v_min_u32_e32 v104, v246, v6
	v_max_u32_e32 v105, v246, v6
	v_cndmask_b32_e64 v246, v105, v104, s[88:89]
	v_min_u32_e32 v106, v248, v7
	v_max_u32_e32 v107, v248, v7
	v_cndmask_b32_e64 v248, v107, v106, s[88:89]
	v_xor_b32_e32 v116, 8, v234
	ds_bpermute_b32 v0, v116, v241
	ds_bpermute_b32 v1, v116, v243
	ds_bpermute_b32 v2, v116, v245
	ds_bpermute_b32 v3, v116, v247
	ds_bpermute_b32 v4, v116, v242
	ds_bpermute_b32 v5, v116, v244
	ds_bpermute_b32 v6, v116, v246
	ds_bpermute_b32 v7, v116, v248
	s_waitcnt lgkmcnt(0)
; DEV void sort_lists(int lane, int& myi0, int& myi1, float& myg0, float& myg1) {
; #pragma unroll
;     for (int k = 2; k <= 128; k <<= 1) {
; #pragma unroll
;       for (int j = k >> 1; j >= 1; j >>= 1) {
;         if (j == 64) {
;           const bool sw_ = myi1 < myi0;
;           const int ti = sw_ ? myi1 : myi0, tj = sw_ ? myi0 : myi1; const float tg = sw_ ? myg1 : myg0, th = sw_ ? myg0 : myg1;
;           myi0 = ti; myi1 = tj; myg0 = tg; myg1 = th;
;         } else {
;           const bool lower = (lane & j) == 0;
;           {
;             const bool up = (k == 128) ? true : ((k == 64) ? true : ((lane & k) == 0));
;             const int oi = __shfl_xor(myi0, j); const float og = __shfl_xor(myg0, j);
;             const bool take = (lower == up) ? (oi < myi0) : (oi > myi0);
;             myi0 = take ? oi : myi0; myg0 = take ? og : myg0;
;           }
;           {
;             const bool up = (k == 128) ? true : ((k == 64) ? false : ((lane & k) == 0));
;             const int oi = __shfl_xor(myi1, j); const float og = __shfl_xor(myg1, j);
;             const bool take = (lower == up) ? (oi < myi1) : (oi > myi1);
;             myi1 = take ? oi : myi1; myg1 = take ? og : myg1;
;           }
;         }
;       }
;     }
; }
	s_mov_b32 s88, 0xcccc3333
	s_mov_b32 s89, 0xcccc3333
	v_min_u32_e32 v104, v241, v0
	v_max_u32_e32 v105, v241, v0
	v_cndmask_b32_e64 v241, v105, v104, s[88:89]
	v_min_u32_e32 v106, v243, v1
	v_max_u32_e32 v107, v243, v1
	v_cndmask_b32_e64 v243, v107, v106, s[88:89]
	v_min_u32_e32 v104, v245, v2
	v_max_u32_e32 v105, v245, v2
	v_cndmask_b32_e64 v245, v105, v104, s[88:89]
	v_min_u32_e32 v106, v247, v3
	v_max_u32_e32 v107, v247, v3
	v_cndmask_b32_e64 v247, v107, v106, s[88:89]
	v_min_u32_e32 v104, v242, v4
	v_max_u32_e32 v105, v242, v4
	v_cndmask_b32_e64 v242, v105, v104, s[88:89]
	v_min_u32_e32 v106, v244, v5
	v_max_u32_e32 v107, v244, v5
	v_cndmask_b32_e64 v244, v107, v106, s[88:89]
	v_min_u32_e32 v104, v246, v6
	v_max_u32_e32 v105, v246, v6
	v_cndmask_b32_e64 v246, v105, v104, s[88:89]
	v_min_u32_e32 v106, v248, v7
	v_max_u32_e32 v107, v248, v7
	v_cndmask_b32_e64 v248, v107, v106, s[88:89]
	v_xor_b32_e32 v116, 4, v234
	ds_bpermute_b32 v0, v116, v241
	ds_bpermute_b32 v1, v116, v243
	ds_bpermute_b32 v2, v116, v245
	ds_bpermute_b32 v3, v116, v247
	ds_bpermute_b32 v4, v116, v242
	ds_bpermute_b32 v5, v116, v244
	ds_bpermute_b32 v6, v116, v246
	ds_bpermute_b32 v7, v116, v248
	s_waitcnt lgkmcnt(0)
	s_mov_b32 s88, 0xaaaa5555
	s_mov_b32 s89, 0xaaaa5555
	v_min_u32_e32 v104, v241, v0
	v_max_u32_e32 v105, v241, v0
	v_cndmask_b32_e64 v241, v105, v104, s[88:89]
	v_min_u32_e32 v106, v243, v1
	v_max_u32_e32 v107, v243, v1
	v_cndmask_b32_e64 v243, v107, v106, s[88:89]
	v_min_u32_e32 v104, v245, v2
	v_max_u32_e32 v105, v245, v2
	v_cndmask_b32_e64 v245, v105, v104, s[88:89]
	v_min_u32_e32 v106, v247, v3
	v_max_u32_e32 v107, v247, v3
	v_cndmask_b32_e64 v247, v107, v106, s[88:89]
	v_min_u32_e32 v104, v242, v4
	v_max_u32_e32 v105, v242, v4
	v_cndmask_b32_e64 v242, v105, v104, s[88:89]
	v_min_u32_e32 v106, v244, v5
	v_max_u32_e32 v107, v244, v5
	v_cndmask_b32_e64 v244, v107, v106, s[88:89]
	v_min_u32_e32 v104, v246, v6
	v_max_u32_e32 v105, v246, v6
	v_cndmask_b32_e64 v246, v105, v104, s[88:89]
	v_min_u32_e32 v106, v248, v7
	v_max_u32_e32 v107, v248, v7
	v_cndmask_b32_e64 v248, v107, v106, s[88:89]
	v_xor_b32_e32 v116, 64, v234
	ds_bpermute_b32 v0, v116, v241
	ds_bpermute_b32 v1, v116, v243
	ds_bpermute_b32 v2, v116, v245
	ds_bpermute_b32 v3, v116, v247
	ds_bpermute_b32 v4, v116, v242
	ds_bpermute_b32 v5, v116, v244
	ds_bpermute_b32 v6, v116, v246
	ds_bpermute_b32 v7, v116, v248
	s_waitcnt lgkmcnt(0)
	s_mov_b32 s88, 0xffff
	s_mov_b32 s89, 0xffff0000
	v_min_u32_e32 v104, v241, v0
	v_max_u32_e32 v105, v241, v0
	v_cndmask_b32_e64 v241, v105, v104, s[88:89]
	v_min_u32_e32 v106, v243, v1
	v_max_u32_e32 v107, v243, v1
	v_cndmask_b32_e64 v243, v107, v106, s[88:89]
	v_min_u32_e32 v104, v245, v2
	v_max_u32_e32 v105, v245, v2
	v_cndmask_b32_e64 v245, v105, v104, s[88:89]
	v_min_u32_e32 v106, v247, v3
	v_max_u32_e32 v107, v247, v3
	v_cndmask_b32_e64 v247, v107, v106, s[88:89]
	v_min_u32_e32 v104, v242, v4
	v_max_u32_e32 v105, v242, v4
	v_cndmask_b32_e64 v242, v105, v104, s[88:89]
	v_min_u32_e32 v106, v244, v5
	v_max_u32_e32 v107, v244, v5
	v_cndmask_b32_e64 v244, v107, v106, s[88:89]
	v_min_u32_e32 v104, v246, v6
	v_max_u32_e32 v105, v246, v6
	v_cndmask_b32_e64 v246, v105, v104, s[88:89]
	v_min_u32_e32 v106, v248, v7
	v_max_u32_e32 v107, v248, v7
	v_cndmask_b32_e64 v248, v107, v106, s[88:89]
	v_xor_b32_e32 v116, 32, v234
	ds_bpermute_b32 v0, v116, v241
	ds_bpermute_b32 v1, v116, v243
	ds_bpermute_b32 v2, v116, v245
	ds_bpermute_b32 v3, v116, v247
	ds_bpermute_b32 v4, v116, v242
	ds_bpermute_b32 v5, v116, v244
	ds_bpermute_b32 v6, v116, v246
	ds_bpermute_b32 v7, v116, v248
	s_waitcnt lgkmcnt(0)
	s_mov_b32 s88, 0xff00ff
	s_mov_b32 s89, 0xff00ff00
	v_min_u32_e32 v104, v241, v0
	v_max_u32_e32 v105, v241, v0
	v_cndmask_b32_e64 v241, v105, v104, s[88:89]
	v_min_u32_e32 v106, v243, v1
	v_max_u32_e32 v107, v243, v1
	v_cndmask_b32_e64 v243, v107, v106, s[88:89]
	v_min_u32_e32 v104, v245, v2
	v_max_u32_e32 v105, v245, v2
	v_cndmask_b32_e64 v245, v105, v104, s[88:89]
	v_min_u32_e32 v106, v247, v3
	v_max_u32_e32 v107, v247, v3
	v_cndmask_b32_e64 v247, v107, v106, s[88:89]
	v_min_u32_e32 v104, v242, v4
	v_max_u32_e32 v105, v242, v4
	v_cndmask_b32_e64 v242, v105, v104, s[88:89]
	v_min_u32_e32 v106, v244, v5
	v_max_u32_e32 v107, v244, v5
	v_cndmask_b32_e64 v244, v107, v106, s[88:89]
	v_min_u32_e32 v104, v246, v6
	v_max_u32_e32 v105, v246, v6
	v_cndmask_b32_e64 v246, v105, v104, s[88:89]
	v_min_u32_e32 v106, v248, v7
	v_max_u32_e32 v107, v248, v7
	v_cndmask_b32_e64 v248, v107, v106, s[88:89]
	v_xor_b32_e32 v116, 16, v234
	ds_bpermute_b32 v0, v116, v241
	ds_bpermute_b32 v1, v116, v243
	ds_bpermute_b32 v2, v116, v245
	ds_bpermute_b32 v3, v116, v247
	ds_bpermute_b32 v4, v116, v242
	ds_bpermute_b32 v5, v116, v244
	ds_bpermute_b32 v6, v116, v246
	ds_bpermute_b32 v7, v116, v248
	s_waitcnt lgkmcnt(0)
	s_mov_b32 s88, 0xf0f0f0f
	s_mov_b32 s89, 0xf0f0f0f0
	v_min_u32_e32 v104, v241, v0
	v_max_u32_e32 v105, v241, v0
	v_cndmask_b32_e64 v241, v105, v104, s[88:89]
	v_min_u32_e32 v106, v243, v1
	v_max_u32_e32 v107, v243, v1
	v_cndmask_b32_e64 v243, v107, v106, s[88:89]
	v_min_u32_e32 v104, v245, v2
	v_max_u32_e32 v105, v245, v2
	v_cndmask_b32_e64 v245, v105, v104, s[88:89]
	v_min_u32_e32 v106, v247, v3
	v_max_u32_e32 v107, v247, v3
	v_cndmask_b32_e64 v247, v107, v106, s[88:89]
	v_min_u32_e32 v104, v242, v4
	v_max_u32_e32 v105, v242, v4
	v_cndmask_b32_e64 v242, v105, v104, s[88:89]
	v_min_u32_e32 v106, v244, v5
	v_max_u32_e32 v107, v244, v5
	v_cndmask_b32_e64 v244, v107, v106, s[88:89]
	v_min_u32_e32 v104, v246, v6
	v_max_u32_e32 v105, v246, v6
	v_cndmask_b32_e64 v246, v105, v104, s[88:89]
	v_min_u32_e32 v106, v248, v7
	v_max_u32_e32 v107, v248, v7
	v_cndmask_b32_e64 v248, v107, v106, s[88:89]
	v_xor_b32_e32 v116, 8, v234
	ds_bpermute_b32 v0, v116, v241
	ds_bpermute_b32 v1, v116, v243
	ds_bpermute_b32 v2, v116, v245
	ds_bpermute_b32 v3, v116, v247
	ds_bpermute_b32 v4, v116, v242
	ds_bpermute_b32 v5, v116, v244
	ds_bpermute_b32 v6, v116, v246
	ds_bpermute_b32 v7, v116, v248
	s_waitcnt lgkmcnt(0)
; DEV void sort_lists(int lane, int& myi0, int& myi1, float& myg0, float& myg1) {
; #pragma unroll
;     for (int k = 2; k <= 128; k <<= 1) {
; #pragma unroll
;       for (int j = k >> 1; j >= 1; j >>= 1) {
;         if (j == 64) {
;           const bool sw_ = myi1 < myi0;
;           const int ti = sw_ ? myi1 : myi0, tj = sw_ ? myi0 : myi1; const float tg = sw_ ? myg1 : myg0, th = sw_ ? myg0 : myg1;
;           myi0 = ti; myi1 = tj; myg0 = tg; myg1 = th;
;         } else {
;           const bool lower = (lane & j) == 0;
;           {
;             const bool up = (k == 128) ? true : ((k == 64) ? true : ((lane & k) == 0));
;             const int oi = __shfl_xor(myi0, j); const float og = __shfl_xor(myg0, j);
;             const bool take = (lower == up) ? (oi < myi0) : (oi > myi0);
;             myi0 = take ? oi : myi0; myg0 = take ? og : myg0;
;           }
;           {
;             const bool up = (k == 128) ? true : ((k == 64) ? false : ((lane & k) == 0));
;             const int oi = __shfl_xor(myi1, j); const float og = __shfl_xor(myg1, j);
;             const bool take = (lower == up) ? (oi < myi1) : (oi > myi1);
;             myi1 = take ? oi : myi1; myg1 = take ? og : myg1;
;           }
;         }
;       }
;     }
; }
	s_mov_b32 s88, 0x33333333
	s_mov_b32 s89, 0xcccccccc
	v_min_u32_e32 v104, v241, v0
	v_max_u32_e32 v105, v241, v0
	v_cndmask_b32_e64 v241, v105, v104, s[88:89]
	v_min_u32_e32 v106, v243, v1
	v_max_u32_e32 v107, v243, v1
	v_cndmask_b32_e64 v243, v107, v106, s[88:89]
	v_min_u32_e32 v104, v245, v2
	v_max_u32_e32 v105, v245, v2
	v_cndmask_b32_e64 v245, v105, v104, s[88:89]
	v_min_u32_e32 v106, v247, v3
	v_max_u32_e32 v107, v247, v3
	v_cndmask_b32_e64 v247, v107, v106, s[88:89]
	v_min_u32_e32 v104, v242, v4
	v_max_u32_e32 v105, v242, v4
	v_cndmask_b32_e64 v242, v105, v104, s[88:89]
	v_min_u32_e32 v106, v244, v5
	v_max_u32_e32 v107, v244, v5
	v_cndmask_b32_e64 v244, v107, v106, s[88:89]
	v_min_u32_e32 v104, v246, v6
	v_max_u32_e32 v105, v246, v6
	v_cndmask_b32_e64 v246, v105, v104, s[88:89]
	v_min_u32_e32 v106, v248, v7
	v_max_u32_e32 v107, v248, v7
	v_cndmask_b32_e64 v248, v107, v106, s[88:89]
	v_xor_b32_e32 v116, 4, v234
	ds_bpermute_b32 v0, v116, v241
	ds_bpermute_b32 v1, v116, v243
	ds_bpermute_b32 v2, v116, v245
	ds_bpermute_b32 v3, v116, v247
	ds_bpermute_b32 v4, v116, v242
	ds_bpermute_b32 v5, v116, v244
	ds_bpermute_b32 v6, v116, v246
	ds_bpermute_b32 v7, v116, v248
	s_waitcnt lgkmcnt(0)
	s_mov_b32 s88, 0x55555555
	s_mov_b32 s89, 0xaaaaaaaa
	v_min_u32_e32 v104, v241, v0
	v_max_u32_e32 v105, v241, v0
	v_cndmask_b32_e64 v241, v105, v104, s[88:89]
	v_min_u32_e32 v106, v243, v1
	v_max_u32_e32 v107, v243, v1
	v_cndmask_b32_e64 v243, v107, v106, s[88:89]
	v_min_u32_e32 v104, v245, v2
	v_max_u32_e32 v105, v245, v2
	v_cndmask_b32_e64 v245, v105, v104, s[88:89]
	v_min_u32_e32 v106, v247, v3
	v_max_u32_e32 v107, v247, v3
	v_cndmask_b32_e64 v247, v107, v106, s[88:89]
	v_min_u32_e32 v104, v242, v4
	v_max_u32_e32 v105, v242, v4
	v_cndmask_b32_e64 v242, v105, v104, s[88:89]
	v_min_u32_e32 v106, v244, v5
	v_max_u32_e32 v107, v244, v5
	v_cndmask_b32_e64 v244, v107, v106, s[88:89]
	v_min_u32_e32 v104, v246, v6
	v_max_u32_e32 v105, v246, v6
	v_cndmask_b32_e64 v246, v105, v104, s[88:89]
	v_min_u32_e32 v106, v248, v7
	v_max_u32_e32 v107, v248, v7
	v_cndmask_b32_e64 v248, v107, v106, s[88:89]
	v_xor_b32_e32 v116, 128, v234
	ds_bpermute_b32 v0, v116, v241
	ds_bpermute_b32 v1, v116, v243
	ds_bpermute_b32 v2, v116, v245
	ds_bpermute_b32 v3, v116, v247
	ds_bpermute_b32 v4, v116, v242
	ds_bpermute_b32 v5, v116, v244
	ds_bpermute_b32 v6, v116, v246
	ds_bpermute_b32 v7, v116, v248
	s_waitcnt lgkmcnt(0)
	s_mov_b32 s88, 0xffffffff
	s_mov_b32 s89, 0x0
	v_min_u32_e32 v104, v241, v0
	v_max_u32_e32 v105, v241, v0
	v_cndmask_b32_e64 v241, v105, v104, s[88:89]
	v_min_u32_e32 v106, v243, v1
	v_max_u32_e32 v107, v243, v1
	v_cndmask_b32_e64 v243, v107, v106, s[88:89]
	v_min_u32_e32 v104, v245, v2
	v_max_u32_e32 v105, v245, v2
	v_cndmask_b32_e64 v245, v105, v104, s[88:89]
	v_min_u32_e32 v106, v247, v3
	v_max_u32_e32 v107, v247, v3
	v_cndmask_b32_e64 v247, v107, v106, s[88:89]
	s_mov_b32 s88, 0x0
	s_mov_b32 s89, 0xffffffff
	v_min_u32_e32 v104, v242, v4
	v_max_u32_e32 v105, v242, v4
	v_cndmask_b32_e64 v242, v105, v104, s[88:89]
	v_min_u32_e32 v106, v244, v5
	v_max_u32_e32 v107, v244, v5
	v_cndmask_b32_e64 v244, v107, v106, s[88:89]
	v_min_u32_e32 v104, v246, v6
	v_max_u32_e32 v105, v246, v6
	v_cndmask_b32_e64 v246, v105, v104, s[88:89]
	v_min_u32_e32 v106, v248, v7
	v_max_u32_e32 v107, v248, v7
	v_cndmask_b32_e64 v248, v107, v106, s[88:89]
	v_xor_b32_e32 v116, 64, v234
	ds_bpermute_b32 v0, v116, v241
	ds_bpermute_b32 v1, v116, v243
	ds_bpermute_b32 v2, v116, v245
	ds_bpermute_b32 v3, v116, v247
	ds_bpermute_b32 v4, v116, v242
	ds_bpermute_b32 v5, v116, v244
	ds_bpermute_b32 v6, v116, v246
	ds_bpermute_b32 v7, v116, v248
	s_waitcnt lgkmcnt(0)
	s_mov_b32 s88, 0xffff
	s_mov_b32 s89, 0xffff
	v_min_u32_e32 v104, v241, v0
	v_max_u32_e32 v105, v241, v0
	v_cndmask_b32_e64 v241, v105, v104, s[88:89]
	v_min_u32_e32 v106, v243, v1
	v_max_u32_e32 v107, v243, v1
	v_cndmask_b32_e64 v243, v107, v106, s[88:89]
	v_min_u32_e32 v104, v245, v2
	v_max_u32_e32 v105, v245, v2
	v_cndmask_b32_e64 v245, v105, v104, s[88:89]
	v_min_u32_e32 v106, v247, v3
	v_max_u32_e32 v107, v247, v3
	v_cndmask_b32_e64 v247, v107, v106, s[88:89]
	s_mov_b32 s88, 0xffff0000
	s_mov_b32 s89, 0xffff0000
	v_min_u32_e32 v104, v242, v4
	v_max_u32_e32 v105, v242, v4
	v_cndmask_b32_e64 v242, v105, v104, s[88:89]
	v_min_u32_e32 v106, v244, v5
	v_max_u32_e32 v107, v244, v5
	v_cndmask_b32_e64 v244, v107, v106, s[88:89]
	v_min_u32_e32 v104, v246, v6
	v_max_u32_e32 v105, v246, v6
	v_cndmask_b32_e64 v246, v105, v104, s[88:89]
	v_min_u32_e32 v106, v248, v7
	v_max_u32_e32 v107, v248, v7
	v_cndmask_b32_e64 v248, v107, v106, s[88:89]
	v_xor_b32_e32 v116, 32, v234
	ds_bpermute_b32 v0, v116, v241
	ds_bpermute_b32 v1, v116, v243
	ds_bpermute_b32 v2, v116, v245
	ds_bpermute_b32 v3, v116, v247
	ds_bpermute_b32 v4, v116, v242
	ds_bpermute_b32 v5, v116, v244
	ds_bpermute_b32 v6, v116, v246
	ds_bpermute_b32 v7, v116, v248
	s_waitcnt lgkmcnt(0)
	s_mov_b32 s88, 0xff00ff
	s_mov_b32 s89, 0xff00ff
	v_min_u32_e32 v104, v241, v0
	v_max_u32_e32 v105, v241, v0
	v_cndmask_b32_e64 v241, v105, v104, s[88:89]
	v_min_u32_e32 v106, v243, v1
	v_max_u32_e32 v107, v243, v1
	v_cndmask_b32_e64 v243, v107, v106, s[88:89]
	v_min_u32_e32 v104, v245, v2
	v_max_u32_e32 v105, v245, v2
	v_cndmask_b32_e64 v245, v105, v104, s[88:89]
	v_min_u32_e32 v106, v247, v3
	v_max_u32_e32 v107, v247, v3
	v_cndmask_b32_e64 v247, v107, v106, s[88:89]
	s_mov_b32 s88, 0xff00ff00
	s_mov_b32 s89, 0xff00ff00
	v_min_u32_e32 v104, v242, v4
	v_max_u32_e32 v105, v242, v4
	v_cndmask_b32_e64 v242, v105, v104, s[88:89]
	v_min_u32_e32 v106, v244, v5
	v_max_u32_e32 v107, v244, v5
	v_cndmask_b32_e64 v244, v107, v106, s[88:89]
	v_min_u32_e32 v104, v246, v6
	v_max_u32_e32 v105, v246, v6
	v_cndmask_b32_e64 v246, v105, v104, s[88:89]
	v_min_u32_e32 v106, v248, v7
	v_max_u32_e32 v107, v248, v7
	v_cndmask_b32_e64 v248, v107, v106, s[88:89]
	v_xor_b32_e32 v116, 16, v234
	ds_bpermute_b32 v0, v116, v241
	ds_bpermute_b32 v1, v116, v243
	ds_bpermute_b32 v2, v116, v245
	ds_bpermute_b32 v3, v116, v247
	ds_bpermute_b32 v4, v116, v242
	ds_bpermute_b32 v5, v116, v244
	ds_bpermute_b32 v6, v116, v246
	ds_bpermute_b32 v7, v116, v248
	s_waitcnt lgkmcnt(0)
; DEV void sort_lists(int lane, int& myi0, int& myi1, float& myg0, float& myg1) {
; #pragma unroll
;     for (int k = 2; k <= 128; k <<= 1) {
; #pragma unroll
;       for (int j = k >> 1; j >= 1; j >>= 1) {
;         if (j == 64) {
;           const bool sw_ = myi1 < myi0;
;           const int ti = sw_ ? myi1 : myi0, tj = sw_ ? myi0 : myi1; const float tg = sw_ ? myg1 : myg0, th = sw_ ? myg0 : myg1;
;           myi0 = ti; myi1 = tj; myg0 = tg; myg1 = th;
;         } else {
;           const bool lower = (lane & j) == 0;
;           {
;             const bool up = (k == 128) ? true : ((k == 64) ? true : ((lane & k) == 0));
;             const int oi = __shfl_xor(myi0, j); const float og = __shfl_xor(myg0, j);
;             const bool take = (lower == up) ? (oi < myi0) : (oi > myi0);
;             myi0 = take ? oi : myi0; myg0 = take ? og : myg0;
;           }
;           {
;             const bool up = (k == 128) ? true : ((k == 64) ? false : ((lane & k) == 0));
;             const int oi = __shfl_xor(myi1, j); const float og = __shfl_xor(myg1, j);
;             const bool take = (lower == up) ? (oi < myi1) : (oi > myi1);
;             myi1 = take ? oi : myi1; myg1 = take ? og : myg1;
;           }
;         }
;       }
;     }
; }
	s_mov_b32 s88, 0xf0f0f0f
	s_mov_b32 s89, 0xf0f0f0f
	v_min_u32_e32 v104, v241, v0
	v_max_u32_e32 v105, v241, v0
	v_cndmask_b32_e64 v241, v105, v104, s[88:89]
	v_min_u32_e32 v106, v243, v1
	v_max_u32_e32 v107, v243, v1
	v_cndmask_b32_e64 v243, v107, v106, s[88:89]
	v_min_u32_e32 v104, v245, v2
	v_max_u32_e32 v105, v245, v2
	v_cndmask_b32_e64 v245, v105, v104, s[88:89]
	v_min_u32_e32 v106, v247, v3
	v_max_u32_e32 v107, v247, v3
	v_cndmask_b32_e64 v247, v107, v106, s[88:89]
	s_mov_b32 s88, 0xf0f0f0f0
	s_mov_b32 s89, 0xf0f0f0f0
	v_min_u32_e32 v104, v242, v4
	v_max_u32_e32 v105, v242, v4
	v_cndmask_b32_e64 v242, v105, v104, s[88:89]
	v_min_u32_e32 v106, v244, v5
	v_max_u32_e32 v107, v244, v5
	v_cndmask_b32_e64 v244, v107, v106, s[88:89]
	v_min_u32_e32 v104, v246, v6
	v_max_u32_e32 v105, v246, v6
	v_cndmask_b32_e64 v246, v105, v104, s[88:89]
	v_min_u32_e32 v106, v248, v7
	v_max_u32_e32 v107, v248, v7
	v_cndmask_b32_e64 v248, v107, v106, s[88:89]
	v_xor_b32_e32 v116, 8, v234
	ds_bpermute_b32 v0, v116, v241
	ds_bpermute_b32 v1, v116, v243
	ds_bpermute_b32 v2, v116, v245
	ds_bpermute_b32 v3, v116, v247
	ds_bpermute_b32 v4, v116, v242
	ds_bpermute_b32 v5, v116, v244
	ds_bpermute_b32 v6, v116, v246
	ds_bpermute_b32 v7, v116, v248
	s_waitcnt lgkmcnt(0)
	s_mov_b32 s88, 0x33333333
	s_mov_b32 s89, 0x33333333
	v_min_u32_e32 v104, v241, v0
	v_max_u32_e32 v105, v241, v0
	v_cndmask_b32_e64 v241, v105, v104, s[88:89]
	v_min_u32_e32 v106, v243, v1
	v_max_u32_e32 v107, v243, v1
	v_cndmask_b32_e64 v243, v107, v106, s[88:89]
	v_min_u32_e32 v104, v245, v2
	v_max_u32_e32 v105, v245, v2
	v_cndmask_b32_e64 v245, v105, v104, s[88:89]
	v_min_u32_e32 v106, v247, v3
	v_max_u32_e32 v107, v247, v3
	v_cndmask_b32_e64 v247, v107, v106, s[88:89]
	s_mov_b32 s88, 0xcccccccc
	s_mov_b32 s89, 0xcccccccc
	v_min_u32_e32 v104, v242, v4
	v_max_u32_e32 v105, v242, v4
	v_cndmask_b32_e64 v242, v105, v104, s[88:89]
	v_min_u32_e32 v106, v244, v5
	v_max_u32_e32 v107, v244, v5
	v_cndmask_b32_e64 v244, v107, v106, s[88:89]
	v_min_u32_e32 v104, v246, v6
	v_max_u32_e32 v105, v246, v6
	v_cndmask_b32_e64 v246, v105, v104, s[88:89]
	v_min_u32_e32 v106, v248, v7
	v_max_u32_e32 v107, v248, v7
	v_cndmask_b32_e64 v248, v107, v106, s[88:89]
	v_xor_b32_e32 v116, 4, v234
	ds_bpermute_b32 v0, v116, v241
	ds_bpermute_b32 v1, v116, v243
	ds_bpermute_b32 v2, v116, v245
	ds_bpermute_b32 v3, v116, v247
	ds_bpermute_b32 v4, v116, v242
	ds_bpermute_b32 v5, v116, v244
	ds_bpermute_b32 v6, v116, v246
	ds_bpermute_b32 v7, v116, v248
	s_waitcnt lgkmcnt(0)
	s_mov_b32 s88, 0x55555555
	s_mov_b32 s89, 0x55555555
	v_min_u32_e32 v104, v241, v0
	v_max_u32_e32 v105, v241, v0
	v_cndmask_b32_e64 v241, v105, v104, s[88:89]
	v_min_u32_e32 v106, v243, v1
	v_max_u32_e32 v107, v243, v1
	v_cndmask_b32_e64 v243, v107, v106, s[88:89]
	v_min_u32_e32 v104, v245, v2
	v_max_u32_e32 v105, v245, v2
	v_cndmask_b32_e64 v245, v105, v104, s[88:89]
	v_min_u32_e32 v106, v247, v3
	v_max_u32_e32 v107, v247, v3
	v_cndmask_b32_e64 v247, v107, v106, s[88:89]
	s_mov_b32 s88, 0xaaaaaaaa
	s_mov_b32 s89, 0xaaaaaaaa
	v_min_u32_e32 v104, v242, v4
	v_max_u32_e32 v105, v242, v4
	v_cndmask_b32_e64 v242, v105, v104, s[88:89]
	v_min_u32_e32 v106, v244, v5
	v_max_u32_e32 v107, v244, v5
	v_cndmask_b32_e64 v244, v107, v106, s[88:89]
	v_min_u32_e32 v104, v246, v6
	v_max_u32_e32 v105, v246, v6
	v_cndmask_b32_e64 v246, v105, v104, s[88:89]
	v_min_u32_e32 v106, v248, v7
	v_max_u32_e32 v107, v248, v7
	v_cndmask_b32_e64 v248, v107, v106, s[88:89]
	v_min_u32_e32 v104, v241, v242
	v_max_u32_e32 v242, v241, v242
	v_mov_b32_e32 v241, v104
	v_min_u32_e32 v106, v243, v244
	v_max_u32_e32 v244, v243, v244
	v_mov_b32_e32 v243, v106
	v_min_u32_e32 v104, v245, v246
	v_max_u32_e32 v246, v245, v246
	v_mov_b32_e32 v245, v104
	v_min_u32_e32 v106, v247, v248
	v_max_u32_e32 v248, v247, v248
	v_mov_b32_e32 v247, v106
	v_xor_b32_e32 v116, 128, v234
	ds_bpermute_b32 v0, v116, v241
	ds_bpermute_b32 v1, v116, v243
	ds_bpermute_b32 v2, v116, v245
	ds_bpermute_b32 v3, v116, v247
	ds_bpermute_b32 v4, v116, v242
	ds_bpermute_b32 v5, v116, v244
	ds_bpermute_b32 v6, v116, v246
	ds_bpermute_b32 v7, v116, v248
	s_waitcnt lgkmcnt(0)
	s_mov_b32 s88, 0xffffffff
	s_mov_b32 s89, 0x0
	v_min_u32_e32 v104, v241, v0
	v_max_u32_e32 v105, v241, v0
	v_cndmask_b32_e64 v241, v105, v104, s[88:89]
	v_min_u32_e32 v106, v243, v1
	v_max_u32_e32 v107, v243, v1
	v_cndmask_b32_e64 v243, v107, v106, s[88:89]
	v_min_u32_e32 v104, v245, v2
	v_max_u32_e32 v105, v245, v2
	v_cndmask_b32_e64 v245, v105, v104, s[88:89]
	v_min_u32_e32 v106, v247, v3
	v_max_u32_e32 v107, v247, v3
	v_cndmask_b32_e64 v247, v107, v106, s[88:89]
	v_min_u32_e32 v104, v242, v4
	v_max_u32_e32 v105, v242, v4
	v_cndmask_b32_e64 v242, v105, v104, s[88:89]
	v_min_u32_e32 v106, v244, v5
	v_max_u32_e32 v107, v244, v5
	v_cndmask_b32_e64 v244, v107, v106, s[88:89]
	v_min_u32_e32 v104, v246, v6
	v_max_u32_e32 v105, v246, v6
	v_cndmask_b32_e64 v246, v105, v104, s[88:89]
	v_min_u32_e32 v106, v248, v7
	v_max_u32_e32 v107, v248, v7
	v_cndmask_b32_e64 v248, v107, v106, s[88:89]
	v_xor_b32_e32 v116, 64, v234
	ds_bpermute_b32 v0, v116, v241
	ds_bpermute_b32 v1, v116, v243
	ds_bpermute_b32 v2, v116, v245
	ds_bpermute_b32 v3, v116, v247
	ds_bpermute_b32 v4, v116, v242
	ds_bpermute_b32 v5, v116, v244
	ds_bpermute_b32 v6, v116, v246
	ds_bpermute_b32 v7, v116, v248
	s_waitcnt lgkmcnt(0)
; DEV void sort_lists(int lane, int& myi0, int& myi1, float& myg0, float& myg1) {
; #pragma unroll
;     for (int k = 2; k <= 128; k <<= 1) {
; #pragma unroll
;       for (int j = k >> 1; j >= 1; j >>= 1) {
;         if (j == 64) {
;           const bool sw_ = myi1 < myi0;
;           const int ti = sw_ ? myi1 : myi0, tj = sw_ ? myi0 : myi1; const float tg = sw_ ? myg1 : myg0, th = sw_ ? myg0 : myg1;
;           myi0 = ti; myi1 = tj; myg0 = tg; myg1 = th;
;         } else {
;           const bool lower = (lane & j) == 0;
;           {
;             const bool up = (k == 128) ? true : ((k == 64) ? true : ((lane & k) == 0));
;             const int oi = __shfl_xor(myi0, j); const float og = __shfl_xor(myg0, j);
;             const bool take = (lower == up) ? (oi < myi0) : (oi > myi0);
;             myi0 = take ? oi : myi0; myg0 = take ? og : myg0;
;           }
;           {
;             const bool up = (k == 128) ? true : ((k == 64) ? false : ((lane & k) == 0));
;             const int oi = __shfl_xor(myi1, j); const float og = __shfl_xor(myg1, j);
;             const bool take = (lower == up) ? (oi < myi1) : (oi > myi1);
;             myi1 = take ? oi : myi1; myg1 = take ? og : myg1;
;           }
;         }
;       }
;     }
; }
	s_mov_b32 s88, 0xffff
	s_mov_b32 s89, 0xffff
	v_min_u32_e32 v104, v241, v0
	v_max_u32_e32 v105, v241, v0
	v_cndmask_b32_e64 v241, v105, v104, s[88:89]
	v_min_u32_e32 v106, v243, v1
	v_max_u32_e32 v107, v243, v1
	v_cndmask_b32_e64 v243, v107, v106, s[88:89]
	v_min_u32_e32 v104, v245, v2
	v_max_u32_e32 v105, v245, v2
	v_cndmask_b32_e64 v245, v105, v104, s[88:89]
	v_min_u32_e32 v106, v247, v3
	v_max_u32_e32 v107, v247, v3
	v_cndmask_b32_e64 v247, v107, v106, s[88:89]
	v_min_u32_e32 v104, v242, v4
	v_max_u32_e32 v105, v242, v4
	v_cndmask_b32_e64 v242, v105, v104, s[88:89]
	v_min_u32_e32 v106, v244, v5
	v_max_u32_e32 v107, v244, v5
	v_cndmask_b32_e64 v244, v107, v106, s[88:89]
	v_min_u32_e32 v104, v246, v6
	v_max_u32_e32 v105, v246, v6
	v_cndmask_b32_e64 v246, v105, v104, s[88:89]
	v_min_u32_e32 v106, v248, v7
	v_max_u32_e32 v107, v248, v7
	v_cndmask_b32_e64 v248, v107, v106, s[88:89]
	v_xor_b32_e32 v116, 32, v234
	ds_bpermute_b32 v0, v116, v241
	ds_bpermute_b32 v1, v116, v243
	ds_bpermute_b32 v2, v116, v245
	ds_bpermute_b32 v3, v116, v247
	ds_bpermute_b32 v4, v116, v242
	ds_bpermute_b32 v5, v116, v244
	ds_bpermute_b32 v6, v116, v246
	ds_bpermute_b32 v7, v116, v248
	s_waitcnt lgkmcnt(0)
	s_mov_b32 s88, 0xff00ff
	s_mov_b32 s89, 0xff00ff
	v_min_u32_e32 v104, v241, v0
	v_max_u32_e32 v105, v241, v0
	v_cndmask_b32_e64 v241, v105, v104, s[88:89]
	v_min_u32_e32 v106, v243, v1
	v_max_u32_e32 v107, v243, v1
	v_cndmask_b32_e64 v243, v107, v106, s[88:89]
	v_min_u32_e32 v104, v245, v2
	v_max_u32_e32 v105, v245, v2
	v_cndmask_b32_e64 v245, v105, v104, s[88:89]
	v_min_u32_e32 v106, v247, v3
	v_max_u32_e32 v107, v247, v3
	v_cndmask_b32_e64 v247, v107, v106, s[88:89]
	v_min_u32_e32 v104, v242, v4
	v_max_u32_e32 v105, v242, v4
	v_cndmask_b32_e64 v242, v105, v104, s[88:89]
	v_min_u32_e32 v106, v244, v5
	v_max_u32_e32 v107, v244, v5
	v_cndmask_b32_e64 v244, v107, v106, s[88:89]
	v_min_u32_e32 v104, v246, v6
	v_max_u32_e32 v105, v246, v6
	v_cndmask_b32_e64 v246, v105, v104, s[88:89]
	v_min_u32_e32 v106, v248, v7
	v_max_u32_e32 v107, v248, v7
	v_cndmask_b32_e64 v248, v107, v106, s[88:89]
	v_xor_b32_e32 v116, 16, v234
	ds_bpermute_b32 v0, v116, v241
	ds_bpermute_b32 v1, v116, v243
	ds_bpermute_b32 v2, v116, v245
	ds_bpermute_b32 v3, v116, v247
	ds_bpermute_b32 v4, v116, v242
	ds_bpermute_b32 v5, v116, v244
	ds_bpermute_b32 v6, v116, v246
	ds_bpermute_b32 v7, v116, v248
	s_waitcnt lgkmcnt(0)
	s_mov_b32 s88, 0xf0f0f0f
	s_mov_b32 s89, 0xf0f0f0f
	v_min_u32_e32 v104, v241, v0
	v_max_u32_e32 v105, v241, v0
	v_cndmask_b32_e64 v241, v105, v104, s[88:89]
	v_min_u32_e32 v106, v243, v1
	v_max_u32_e32 v107, v243, v1
	v_cndmask_b32_e64 v243, v107, v106, s[88:89]
	v_min_u32_e32 v104, v245, v2
	v_max_u32_e32 v105, v245, v2
	v_cndmask_b32_e64 v245, v105, v104, s[88:89]
	v_min_u32_e32 v106, v247, v3
	v_max_u32_e32 v107, v247, v3
	v_cndmask_b32_e64 v247, v107, v106, s[88:89]
	v_min_u32_e32 v104, v242, v4
	v_max_u32_e32 v105, v242, v4
	v_cndmask_b32_e64 v242, v105, v104, s[88:89]
	v_min_u32_e32 v106, v244, v5
	v_max_u32_e32 v107, v244, v5
	v_cndmask_b32_e64 v244, v107, v106, s[88:89]
	v_min_u32_e32 v104, v246, v6
	v_max_u32_e32 v105, v246, v6
	v_cndmask_b32_e64 v246, v105, v104, s[88:89]
	v_min_u32_e32 v106, v248, v7
	v_max_u32_e32 v107, v248, v7
	v_cndmask_b32_e64 v248, v107, v106, s[88:89]
	v_xor_b32_e32 v116, 8, v234
	ds_bpermute_b32 v0, v116, v241
	ds_bpermute_b32 v1, v116, v243
	ds_bpermute_b32 v2, v116, v245
	ds_bpermute_b32 v3, v116, v247
	ds_bpermute_b32 v4, v116, v242
	ds_bpermute_b32 v5, v116, v244
	ds_bpermute_b32 v6, v116, v246
	ds_bpermute_b32 v7, v116, v248
	s_waitcnt lgkmcnt(0)
	s_mov_b32 s88, 0x33333333
	s_mov_b32 s89, 0x33333333
	v_min_u32_e32 v104, v241, v0
	v_max_u32_e32 v105, v241, v0
	v_cndmask_b32_e64 v241, v105, v104, s[88:89]
	v_min_u32_e32 v106, v243, v1
	v_max_u32_e32 v107, v243, v1
	v_cndmask_b32_e64 v243, v107, v106, s[88:89]
	v_min_u32_e32 v104, v245, v2
	v_max_u32_e32 v105, v245, v2
	v_cndmask_b32_e64 v245, v105, v104, s[88:89]
	v_min_u32_e32 v106, v247, v3
	v_max_u32_e32 v107, v247, v3
	v_cndmask_b32_e64 v247, v107, v106, s[88:89]
	v_min_u32_e32 v104, v242, v4
	v_max_u32_e32 v105, v242, v4
	v_cndmask_b32_e64 v242, v105, v104, s[88:89]
	v_min_u32_e32 v106, v244, v5
	v_max_u32_e32 v107, v244, v5
	v_cndmask_b32_e64 v244, v107, v106, s[88:89]
	v_min_u32_e32 v104, v246, v6
	v_max_u32_e32 v105, v246, v6
	v_cndmask_b32_e64 v246, v105, v104, s[88:89]
	v_min_u32_e32 v106, v248, v7
	v_max_u32_e32 v107, v248, v7
	v_cndmask_b32_e64 v248, v107, v106, s[88:89]
	v_xor_b32_e32 v116, 4, v234
	ds_bpermute_b32 v0, v116, v241
	ds_bpermute_b32 v1, v116, v243
	ds_bpermute_b32 v2, v116, v245
	ds_bpermute_b32 v3, v116, v247
	ds_bpermute_b32 v4, v116, v242
	ds_bpermute_b32 v5, v116, v244
	ds_bpermute_b32 v6, v116, v246
	ds_bpermute_b32 v7, v116, v248
	s_waitcnt lgkmcnt(0)
	s_mov_b32 s88, 0x55555555
	s_mov_b32 s89, 0x55555555
	v_min_u32_e32 v104, v241, v0
	v_max_u32_e32 v105, v241, v0
	v_cndmask_b32_e64 v241, v105, v104, s[88:89]
	v_min_u32_e32 v106, v243, v1
	v_max_u32_e32 v107, v243, v1
	v_cndmask_b32_e64 v243, v107, v106, s[88:89]
	v_min_u32_e32 v104, v245, v2
	v_max_u32_e32 v105, v245, v2
	v_cndmask_b32_e64 v245, v105, v104, s[88:89]
	v_min_u32_e32 v106, v247, v3
	v_max_u32_e32 v107, v247, v3
	v_cndmask_b32_e64 v247, v107, v106, s[88:89]
	v_min_u32_e32 v104, v242, v4
	v_max_u32_e32 v105, v242, v4
	v_cndmask_b32_e64 v242, v105, v104, s[88:89]
	v_min_u32_e32 v106, v244, v5
	v_max_u32_e32 v107, v244, v5
	v_cndmask_b32_e64 v244, v107, v106, s[88:89]
	v_min_u32_e32 v104, v246, v6
	v_max_u32_e32 v105, v246, v6
	v_cndmask_b32_e64 v246, v105, v104, s[88:89]
	v_min_u32_e32 v106, v248, v7
	v_max_u32_e32 v107, v248, v7
	v_cndmask_b32_e64 v248, v107, v106, s[88:89]
	v_mov_b32_e32 v117, 0
	s_lshl_b32 s98, s2, 11
	s_add_u32 s98, s98, s101
	v_add_u32_e32 v116, s98, v234
	ds_write_b32 v116, v241 offset:0
	ds_write_b32 v116, v242 offset:256
	ds_write_b32 v116, v243 offset:512
	ds_write_b32 v116, v244 offset:768
	ds_write_b32 v116, v245 offset:1024
	ds_write_b32 v116, v246 offset:1280
	ds_write_b32 v116, v247 offset:1536
	ds_write_b32 v116, v248 offset:1792
	v_add_u32_e32 v118, 0x10000, v116
	ds_write_b32 v118, v117 offset:0
	ds_write_b32 v118, v117 offset:256
	ds_write_b32 v118, v117 offset:512
	ds_write_b32 v118, v117 offset:768
	ds_write_b32 v118, v117 offset:1024
	ds_write_b32 v118, v117 offset:1280
	ds_write_b32 v118, v117 offset:1536
	ds_write_b32 v118, v117 offset:1792
	s_add_u32 s2, s2, 1
	s_cmp_lt_u32 s2, 4
	s_cbranch_scc1 .Lpg1_p0
; #define PG_ISSUE(BUF, TAB, e0_) do { const int isrc_ = ((e0_) < 64) ? myi0 : myi1; \
;       _Pragma("unroll") for (int e = 0; e < 8; ++e) { const int idx_ = __builtin_amdgcn_readlane(isrc_, ((e0_) + e) & 63); \
;         BUF[e] = *(const u32x4*)((TAB) + (size_t)idx_ * 1024 + lane * 16); } } while (0)
; DEV void peer_gather(const Params& P, int l, int m0, const int* idxs, const float* gs) {
;     ...
;     PG_ISSUE(b0, U, 0);
; #pragma nounroll
;     for (int e0 = 0; e0 < 128; e0 += 16) {
;       PG_ISSUE(b1, U, e0 + 8);
;       PG_U8(b0, 0, e0);
;       if (e0 + 16 < 128) PG_ISSUE(b0, U, e0 + 16); else PG_ISSUE(b0, V, 0);
;       PG_U8(b1, 0, e0 + 8);
;     }
	s_waitcnt lgkmcnt(0)
	v_lshrrev_b32_e32 v248, 3, v233
	v_readfirstlane_b32 s82, v122
	v_readfirstlane_b32 s83, v123
	s_nop 4
	v_readfirstlane_b32 s80, v126
	v_readfirstlane_b32 s81, v127
	s_nop 4
	s_mov_b32 s90, 0xffffff80
	s_mov_b32 s86, 0xcccccccc
	s_mov_b32 s87, 0xcccccccc
	s_mov_b32 s88, 0xaaaaaaaa
	s_mov_b32 s89, 0xaaaaaaaa
	s_mov_b32 s100, 0
	s_mov_b32 s98, 0
	s_mov_b32 s99, 0
	s_add_u32 vcc_lo, s3, s98
	s_lshl_b32 vcc_lo, vcc_lo, 11
	s_lshl_b32 vcc_hi, s99, 8
	s_add_u32 vcc_lo, vcc_lo, vcc_hi
	v_add_u32_e32 v119, vcc_lo, v236
	global_load_dwordx4 v[80:83], v119, s[82:83]
	global_load_dwordx4 v[84:87], v119, s[82:83] offset:16
	s_lshl_b32 vcc_lo, s98, 9
	s_add_u32 vcc_lo, vcc_lo, s101
	v_add_u32_e32 v116, vcc_lo, v234
	ds_read_b32 v134, v116
	ds_read_b32 v135, v116 offset:256
	s_lshl_b32 vcc_lo, s99, 21
	s_add_u32 s84, s80, vcc_lo
	s_addc_u32 s85, s81, 0
	v_mov_b32_e32 v240, v235
	s_waitcnt lgkmcnt(0)
	ds_bpermute_b32 v142, v249, v134
	ds_bpermute_b32 v143, v250, v134
	s_waitcnt lgkmcnt(0)
	v_and_or_b32 v142, v142, s90, v240
	v_and_or_b32 v143, v143, s90, v240
	global_load_dwordx4 v[0:3], v142, s[84:85]
	global_load_dwordx4 v[4:7], v143, s[84:85]
	ds_bpermute_b32 v142, v251, v134
	ds_bpermute_b32 v143, v252, v134
	s_waitcnt lgkmcnt(0)
	v_and_or_b32 v142, v142, s90, v240
	v_and_or_b32 v143, v143, s90, v240
	global_load_dwordx4 v[8:11], v142, s[84:85]
	global_load_dwordx4 v[12:15], v143, s[84:85]
	ds_bpermute_b32 v142, v253, v134
	ds_bpermute_b32 v143, v254, v134
	s_waitcnt lgkmcnt(0)
	v_and_or_b32 v142, v142, s90, v240
	v_and_or_b32 v143, v143, s90, v240
	global_load_dwordx4 v[16:19], v142, s[84:85]
	global_load_dwordx4 v[20:23], v143, s[84:85]
	ds_bpermute_b32 v142, v255, v134
	ds_bpermute_b32 v143, v153, v134
	s_waitcnt lgkmcnt(0)
	v_and_or_b32 v142, v142, s90, v240
	v_and_or_b32 v143, v143, s90, v240
	global_load_dwordx4 v[24:27], v142, s[84:85]
	global_load_dwordx4 v[28:31], v143, s[84:85]
	ds_bpermute_b32 v142, v249, v135
	ds_bpermute_b32 v143, v250, v135
	s_waitcnt lgkmcnt(0)
	v_and_or_b32 v142, v142, s90, v240
	v_and_or_b32 v143, v143, s90, v240
	global_load_dwordx4 v[32:35], v142, s[84:85]
	global_load_dwordx4 v[36:39], v143, s[84:85]
	ds_bpermute_b32 v142, v251, v135
	ds_bpermute_b32 v143, v252, v135
	s_waitcnt lgkmcnt(0)
	v_and_or_b32 v142, v142, s90, v240
	v_and_or_b32 v143, v143, s90, v240
	global_load_dwordx4 v[40:43], v142, s[84:85]
	global_load_dwordx4 v[44:47], v143, s[84:85]
	ds_bpermute_b32 v142, v253, v135
	ds_bpermute_b32 v143, v254, v135
	s_waitcnt lgkmcnt(0)
	v_and_or_b32 v142, v142, s90, v240
	v_and_or_b32 v143, v143, s90, v240
	global_load_dwordx4 v[48:51], v142, s[84:85]
	global_load_dwordx4 v[52:55], v143, s[84:85]
	ds_bpermute_b32 v142, v255, v135
	ds_bpermute_b32 v143, v153, v135
	s_waitcnt lgkmcnt(0)
	v_and_or_b32 v142, v142, s90, v240
	v_and_or_b32 v143, v143, s90, v240
	global_load_dwordx4 v[56:59], v142, s[84:85]
	global_load_dwordx4 v[60:63], v143, s[84:85]
	s_mov_b32 s92, 1
	s_lshl_b32 vcc_lo, s92, 9
	s_add_u32 vcc_lo, vcc_lo, s101
	v_add_u32_e32 v116, vcc_lo, v234
	ds_read_b32 v134, v116
	ds_read_b32 v135, v116 offset:256

.Lpg1_act:
	v_readlane_b32 s82, v232, 1
	v_readlane_b32 s83, v232, 2
	s_nop 4
	s_lshl_b32 s98, s2, 11
	s_add_u32 s98, s98, s101
	v_add_u32_e32 v116, s98, v234
	v_add_u32_e32 v117, 0x10000, v116
	ds_read_b32 v0, v116 offset:0
	ds_read_b32 v8, v117 offset:0
	ds_read_b32 v1, v116 offset:256
	ds_read_b32 v9, v117 offset:256
	ds_read_b32 v2, v116 offset:512
	ds_read_b32 v10, v117 offset:512
	ds_read_b32 v3, v116 offset:768
	ds_read_b32 v11, v117 offset:768
	ds_read_b32 v4, v116 offset:1024
	ds_read_b32 v12, v117 offset:1024
	ds_read_b32 v5, v116 offset:1280
	ds_read_b32 v13, v117 offset:1280
	ds_read_b32 v6, v116 offset:1536
	ds_read_b32 v14, v117 offset:1536
	ds_read_b32 v7, v116 offset:1792
	ds_read_b32 v15, v117 offset:1792
	s_waitcnt lgkmcnt(0)
	s_lshl_b32 s99, s2, 2
	s_add_u32 s99, s99, s33
	s_add_u32 s99, s99, 0
	s_lshl_b32 s99, s99, 9
	v_and_b32_e32 v0, 0x7f, v0
	v_lshl_add_u32 v0, v0, 2, s99
	global_load_dword v16, v0, s[82:83]
	v_and_b32_e32 v1, 0x7f, v1
	v_lshl_add_u32 v1, v1, 2, s99
	global_load_dword v17, v1, s[82:83]
	s_lshl_b32 s99, s2, 2
	s_add_u32 s99, s99, s33
	s_add_u32 s99, s99, 1
	s_lshl_b32 s99, s99, 9
	v_and_b32_e32 v2, 0x7f, v2
	v_lshl_add_u32 v2, v2, 2, s99
	global_load_dword v18, v2, s[82:83]
	v_and_b32_e32 v3, 0x7f, v3
	v_lshl_add_u32 v3, v3, 2, s99
	global_load_dword v19, v3, s[82:83]
	s_lshl_b32 s99, s2, 2
	s_add_u32 s99, s99, s33
	s_add_u32 s99, s99, 2
	s_lshl_b32 s99, s99, 9
	v_and_b32_e32 v4, 0x7f, v4
	v_lshl_add_u32 v4, v4, 2, s99
	global_load_dword v20, v4, s[82:83]
	v_and_b32_e32 v5, 0x7f, v5
	v_lshl_add_u32 v5, v5, 2, s99
	global_load_dword v21, v5, s[82:83]
	s_lshl_b32 s99, s2, 2
	s_add_u32 s99, s99, s33
	s_add_u32 s99, s99, 3
	s_lshl_b32 s99, s99, 9
	v_and_b32_e32 v6, 0x7f, v6
	v_lshl_add_u32 v6, v6, 2, s99
	global_load_dword v22, v6, s[82:83]
	v_and_b32_e32 v7, 0x7f, v7
	v_lshl_add_u32 v7, v7, 2, s99
	global_load_dword v23, v7, s[82:83]
	v_mul_f32_e32 v8, 0x3c800000, v8
	v_mul_f32_e32 v9, 0x3c800000, v9
	v_mul_f32_e32 v10, 0x3c800000, v10
	v_mul_f32_e32 v11, 0x3c800000, v11
	v_mul_f32_e32 v12, 0x3c800000, v12
	v_mul_f32_e32 v13, 0x3c800000, v13
	v_mul_f32_e32 v14, 0x3c800000, v14
	v_mul_f32_e32 v15, 0x3c800000, v15
	v_mul_f32_e32 v24, 0x3d372713, v8
	v_mul_f32_e32 v25, 0x3d372713, v9
	v_mul_f32_e32 v26, 0x3d372713, v10
	v_mul_f32_e32 v27, 0x3d372713, v11
	v_mul_f32_e32 v28, 0x3d372713, v12
	v_mul_f32_e32 v29, 0x3d372713, v13
	v_mul_f32_e32 v30, 0x3d372713, v14
	v_mul_f32_e32 v31, 0x3d372713, v15
	v_mul_f32_e32 v24, v8, v24
	v_mul_f32_e32 v25, v9, v25
	v_mul_f32_e32 v26, v10, v26
	v_mul_f32_e32 v27, v11, v27
	v_mul_f32_e32 v28, v12, v28
	v_mul_f32_e32 v29, v13, v29
	v_mul_f32_e32 v30, v14, v30
	v_mul_f32_e32 v31, v15, v31
	v_fma_f32 v24, v8, v24, v8
	v_fma_f32 v25, v9, v25, v9
	v_fma_f32 v26, v10, v26, v10
	v_fma_f32 v27, v11, v27, v11
	v_fma_f32 v28, v12, v28, v12
	v_fma_f32 v29, v13, v29, v13
	v_fma_f32 v30, v14, v30, v14
	v_fma_f32 v31, v15, v31, v15
	v_mul_f32_e32 v24, 0xbfcc422a, v24
	v_mul_f32_e32 v25, 0xbfcc422a, v25
	v_mul_f32_e32 v26, 0xbfcc422a, v26
	v_mul_f32_e32 v27, 0xbfcc422a, v27
	v_mul_f32_e32 v28, 0xbfcc422a, v28
	v_mul_f32_e32 v29, 0xbfcc422a, v29
	v_mul_f32_e32 v30, 0xbfcc422a, v30
	v_mul_f32_e32 v31, 0xbfcc422a, v31
	v_mul_f32_e32 v24, 0x3fb8aa3b, v24
	v_mul_f32_e32 v25, 0x3fb8aa3b, v25
	v_mul_f32_e32 v26, 0x3fb8aa3b, v26
	v_mul_f32_e32 v27, 0x3fb8aa3b, v27
	v_mul_f32_e32 v28, 0x3fb8aa3b, v28
	v_mul_f32_e32 v29, 0x3fb8aa3b, v29
	v_mul_f32_e32 v30, 0x3fb8aa3b, v30
	v_mul_f32_e32 v31, 0x3fb8aa3b, v31
	v_exp_f32_e32 v24, v24
	v_exp_f32_e32 v25, v25
	v_exp_f32_e32 v26, v26
	v_exp_f32_e32 v27, v27
	v_exp_f32_e32 v28, v28
	v_exp_f32_e32 v29, v29
	v_exp_f32_e32 v30, v30
	v_exp_f32_e32 v31, v31
	s_nop 0
	v_add_f32_e32 v24, 1.0, v24
	v_add_f32_e32 v25, 1.0, v25
	v_add_f32_e32 v26, 1.0, v26
	v_add_f32_e32 v27, 1.0, v27
	v_add_f32_e32 v28, 1.0, v28
	v_add_f32_e32 v29, 1.0, v29
	v_add_f32_e32 v30, 1.0, v30
	v_add_f32_e32 v31, 1.0, v31
	v_rcp_f32_e32 v24, v24
	v_rcp_f32_e32 v25, v25
	v_rcp_f32_e32 v26, v26
	v_rcp_f32_e32 v27, v27
	v_rcp_f32_e32 v28, v28
	v_rcp_f32_e32 v29, v29
	v_rcp_f32_e32 v30, v30
	v_rcp_f32_e32 v31, v31
	s_nop 0
	v_mul_f32_e32 v24, v8, v24
	v_mul_f32_e32 v25, v9, v25
	v_mul_f32_e32 v26, v10, v26
	v_mul_f32_e32 v27, v11, v27
	v_mul_f32_e32 v28, v12, v28
	v_mul_f32_e32 v29, v13, v29
	v_mul_f32_e32 v30, v14, v30
	v_mul_f32_e32 v31, v15, v31
	s_waitcnt vmcnt(0)
	v_mul_f32_e32 v24, v24, v16
	ds_write_b32 v117, v24 offset:0
	v_mul_f32_e32 v25, v25, v17
	ds_write_b32 v117, v25 offset:256
	v_mul_f32_e32 v26, v26, v18
	ds_write_b32 v117, v26 offset:512
	v_mul_f32_e32 v27, v27, v19
	ds_write_b32 v117, v27 offset:768
	v_mul_f32_e32 v28, v28, v20
	ds_write_b32 v117, v28 offset:1024
	v_mul_f32_e32 v29, v29, v21
	ds_write_b32 v117, v29 offset:1280
	v_mul_f32_e32 v30, v30, v22
	ds_write_b32 v117, v30 offset:1536
	v_mul_f32_e32 v31, v31, v23
	ds_write_b32 v117, v31 offset:1792
	s_add_u32 s2, s2, 1
	s_cmp_lt_u32 s2, 4
	s_cbranch_scc1 .Lpg1_act
; #define PG_ISSUE(BUF, TAB, e0_) do { const int isrc_ = ((e0_) < 64) ? myi0 : myi1; \
;       _Pragma("unroll") for (int e = 0; e < 8; ++e) { const int idx_ = __builtin_amdgcn_readlane(isrc_, ((e0_) + e) & 63); \
;         BUF[e] = *(const u32x4*)((TAB) + (size_t)idx_ * 1024 + lane * 16); } } while (0)
; DEV void peer_gather(const Params& P, int l, int m0, const int* idxs, const float* gs) {
;     ...
;     PG_ISSUE(b0, U, 0);
; #pragma nounroll
;     for (int e0 = 0; e0 < 128; e0 += 16) {
;       PG_ISSUE(b1, U, e0 + 8);
;       PG_U8(b0, 0, e0);
;       if (e0 + 16 < 128) PG_ISSUE(b0, U, e0 + 16); else PG_ISSUE(b0, V, 0);
;       PG_U8(b1, 0, e0 + 8);
;     }
;     float* hrow = P.out + tok * DM + lane * 16;
;     f32x4 hv[4];
; #pragma unroll
;     for (int q = 0; q < 4; ++q) hv[q] = *(const f32x4*)(hrow + 4 * q);
;     if (i + 1 < 16) {
;       const int tn = tt + 1;
;       nxa = *(const u32x4*)(hn + (size_t)(m0 + tn) * DM + lane * 16); nxb = *(const u32x4*)(hn + (size_t)(m0 + tn) * DM + lane * 16 + 8);
;       ni0 = idxs[tn * 128 + lane]; ni1 = idxs[tn * 128 + 64 + lane]; ng0 = gs[tn * 128 + lane]; ng1 = gs[tn * 128 + 64 + lane];
;     }
; #pragma nounroll
;     for (int e0 = 0; e0 < 128; e0 += 16) {
;       PG_ISSUE(b1, V, e0 + 8);
;       if (e0 == 64 && i + 1 < 16) sort_lists(lane, ni0, ni1, ng0, ng1);
;       PG_V16(b0, e0);
;       if (e0 + 16 < 128) PG_ISSUE(b0, V, e0 + 16);
;       PG_V16(b1, e0 + 8);
	s_waitcnt lgkmcnt(0)
	v_add_u32_e32 v249, 0, v237
	v_add_u32_e32 v250, 32, v237
	v_add_u32_e32 v251, 64, v237
	v_add_u32_e32 v252, 96, v237
	v_add_u32_e32 v253, 128, v237
	v_add_u32_e32 v254, 160, v237
	v_add_u32_e32 v255, 192, v237
	v_add_u32_e32 v153, 224, v237
	v_readfirstlane_b32 s80, v128
	v_readfirstlane_b32 s81, v129
	s_nop 4
	v_readfirstlane_b32 s82, v132
	v_readfirstlane_b32 s83, v133
	s_nop 4
	s_mov_b32 s90, 0xffffff80
	s_mov_b32 s100, 0
	s_mov_b32 s98, 0
	s_mov_b32 s99, 0
	s_lshl_b32 vcc_lo, s98, 9
	s_add_u32 vcc_lo, vcc_lo, s101
	v_add_u32_e32 v116, vcc_lo, v234
	ds_read_b32 v134, v116
	ds_read_b32 v135, v116 offset:256
	s_lshl_b32 vcc_lo, s99, 21
	s_add_u32 s84, s80, vcc_lo
	s_addc_u32 s85, s81, 0
	v_mov_b32_e32 v240, v235
	s_waitcnt lgkmcnt(0)
	ds_bpermute_b32 v142, v249, v134
	ds_bpermute_b32 v143, v250, v134
	s_waitcnt lgkmcnt(0)
	v_and_or_b32 v142, v142, s90, v240
	v_and_or_b32 v143, v143, s90, v240
	global_load_dwordx4 v[0:3], v142, s[84:85]
	global_load_dwordx4 v[4:7], v143, s[84:85]
	ds_bpermute_b32 v142, v251, v134
	ds_bpermute_b32 v143, v252, v134
	s_waitcnt lgkmcnt(0)
	v_and_or_b32 v142, v142, s90, v240
	v_and_or_b32 v143, v143, s90, v240
	global_load_dwordx4 v[8:11], v142, s[84:85]
	global_load_dwordx4 v[12:15], v143, s[84:85]
	ds_bpermute_b32 v142, v253, v134
	ds_bpermute_b32 v143, v254, v134
	s_waitcnt lgkmcnt(0)
	v_and_or_b32 v142, v142, s90, v240
	v_and_or_b32 v143, v143, s90, v240
	global_load_dwordx4 v[16:19], v142, s[84:85]
	global_load_dwordx4 v[20:23], v143, s[84:85]
	ds_bpermute_b32 v142, v255, v134
	ds_bpermute_b32 v143, v153, v134
	s_waitcnt lgkmcnt(0)
	v_and_or_b32 v142, v142, s90, v240
	v_and_or_b32 v143, v143, s90, v240
	global_load_dwordx4 v[24:27], v142, s[84:85]
	global_load_dwordx4 v[28:31], v143, s[84:85]
	ds_bpermute_b32 v142, v249, v135
	ds_bpermute_b32 v143, v250, v135
	s_waitcnt lgkmcnt(0)
	v_and_or_b32 v142, v142, s90, v240
	v_and_or_b32 v143, v143, s90, v240
	global_load_dwordx4 v[32:35], v142, s[84:85]
	global_load_dwordx4 v[36:39], v143, s[84:85]
	ds_bpermute_b32 v142, v251, v135
	ds_bpermute_b32 v143, v252, v135
	s_waitcnt lgkmcnt(0)
	v_and_or_b32 v142, v142, s90, v240
	v_and_or_b32 v143, v143, s90, v240
	global_load_dwordx4 v[40:43], v142, s[84:85]
	global_load_dwordx4 v[44:47], v143, s[84:85]
	ds_bpermute_b32 v142, v253, v135
	ds_bpermute_b32 v143, v254, v135
	s_waitcnt lgkmcnt(0)
	v_and_or_b32 v142, v142, s90, v240
	v_and_or_b32 v143, v143, s90, v240
	global_load_dwordx4 v[48:51], v142, s[84:85]
	global_load_dwordx4 v[52:55], v143, s[84:85]
	ds_bpermute_b32 v142, v255, v135
	ds_bpermute_b32 v143, v153, v135
	s_waitcnt lgkmcnt(0)
	v_and_or_b32 v142, v142, s90, v240
	v_and_or_b32 v143, v143, s90, v240
	global_load_dwordx4 v[56:59], v142, s[84:85]
	global_load_dwordx4 v[60:63], v143, s[84:85]
	s_mov_b32 s92, 1
	s_lshl_b32 vcc_lo, s92, 9
	s_add_u32 vcc_lo, vcc_lo, s101
	v_add_u32_e32 v116, vcc_lo, v234
	ds_read_b32 v134, v116
	ds_read_b32 v135, v116 offset:256
	s_lshl_b32 vcc_lo, s98, 9
	s_add_u32 vcc_lo, vcc_lo, s101
	s_add_u32 vcc_lo, vcc_lo, 0x10000
	v_add_u32_e32 v117, vcc_lo, v234
	ds_read_b32 v136, v117
	ds_read_b32 v137, v117 offset:256
	s_waitcnt vmcnt(0)
